# stack: mixing wait fixes + DPP gate scans + cross-attention 12 stage bodies (hoisted LDS reads, QK interleaved across accumulators, hazard padding kept)
# baseline (speedup 1.0000x reference)
.LBB0_318:
	s_or_b64 exec, exec, s[6:7]
	s_lshl_b32 s6, s52, 7
	s_add_u32 s6, s71, s6
	s_waitcnt lgkmcnt(0)
	s_barrier
	s_addc_u32 s7, s72, 0
	v_lshlrev_b32_e32 v1, 5, v144
	global_load_dwordx4 v[136:139], v1, s[6:7] offset:16
	global_load_dwordx4 v[144:147], v1, s[6:7]
	s_waitcnt lgkmcnt(0)
	global_load_dwordx4 v[132:135], v1, s[6:7] offset:528
	global_load_dwordx4 v[140:143], v1, s[6:7] offset:512
	s_lshl_b32 s6, s55, 10
	s_add_i32 s6, s6, 0
	v_lshl_add_u32 v3, v3, 4, s6
	v_add_u32_e32 v1, 0x20000, v3
	ds_read_b128 v[154:157], v1
	s_lshl_b32 s8, s52, 6
	s_add_i32 s15, s8, 0
	s_movk_i32 s16, 0x210
	s_ashr_i32 s6, s54, 3
	s_waitcnt lgkmcnt(0)
	v_mov_b32_e32 v158, v155
	v_mov_b32_e32 v159, v156
	v_mov_b32_e32 v155, v157
	v_pk_add_f32 v[154:155], v[158:159], v[154:155]
	v_readlane_b32 s10, v254, 18
	v_add_f32_e32 v1, v154, v155
	v_fmamk_f32 v1, v1, 0x3b800000, v213
	v_rsq_f32_e32 v1, v1
	v_readlane_b32 s11, v254, 19
	v_readlane_b32 s48, v254, 41
	v_readlane_b32 s49, v254, 42
	v_mul_f32_e32 v160, v0, v1
	v_add_u32_e32 v0, 0x20100, v3
	ds_read_b128 v[154:157], v0
	v_pk_mul_f32 v[128:129], v[128:129], v[160:161] op_sel_hi:[1,0]
	v_pk_mul_f32 v[120:121], v[120:121], v[160:161] op_sel_hi:[1,0]
	v_pk_mul_f32 v[124:125], v[124:125], v[160:161] op_sel_hi:[1,0]
	v_pk_mul_f32 v[126:127], v[126:127], v[160:161] op_sel_hi:[1,0]
	s_waitcnt lgkmcnt(0)
	v_mov_b32_e32 v0, v155
	v_mov_b32_e32 v1, v156
	v_mov_b32_e32 v155, v157
	v_pk_add_f32 v[0:1], v[0:1], v[154:155]
	v_pk_mul_f32 v[116:117], v[116:117], v[160:161] op_sel_hi:[1,0]
	v_add_f32_e32 v0, v0, v1
	v_fmamk_f32 v0, v0, 0x3b800000, v213
	v_rsq_f32_e32 v0, v0
	v_pk_mul_f32 v[118:119], v[118:119], v[160:161] op_sel_hi:[1,0]
	v_pk_mul_f32 v[130:131], v[130:131], v[160:161] op_sel_hi:[1,0]
	v_pk_mul_f32 v[122:123], v[122:123], v[160:161] op_sel_hi:[1,0]
	v_mul_f32_e32 v158, v148, v0
	v_add_u32_e32 v0, 0x20200, v3
	ds_read_b128 v[154:157], v0
	v_pk_mul_f32 v[112:113], v[112:113], v[158:159] op_sel_hi:[1,0]
	v_pk_mul_f32 v[100:101], v[100:101], v[158:159] op_sel_hi:[1,0]
	v_pk_mul_f32 v[108:109], v[108:109], v[158:159] op_sel_hi:[1,0]
	v_pk_mul_f32 v[110:111], v[110:111], v[158:159] op_sel_hi:[1,0]
	s_waitcnt lgkmcnt(0)
	v_mov_b32_e32 v0, v155
	v_mov_b32_e32 v1, v156
	v_mov_b32_e32 v155, v157
	v_pk_add_f32 v[0:1], v[0:1], v[154:155]
	v_pk_mul_f32 v[92:93], v[92:93], v[158:159] op_sel_hi:[1,0]
	v_add_f32_e32 v0, v0, v1
	v_fmamk_f32 v0, v0, 0x3b800000, v213
	v_rsq_f32_e32 v0, v0
	v_pk_mul_f32 v[94:95], v[94:95], v[158:159] op_sel_hi:[1,0]
	v_pk_mul_f32 v[102:103], v[102:103], v[158:159] op_sel_hi:[1,0]
	v_pk_mul_f32 v[114:115], v[114:115], v[158:159] op_sel_hi:[1,0]
	v_mul_f32_e32 v156, v150, v0
	v_add_u32_e32 v0, 0x20300, v3
	ds_read_b128 v[174:177], v0
	v_pk_mul_f32 v[84:85], v[84:85], v[156:157] op_sel_hi:[1,0]
	v_pk_mul_f32 v[96:97], v[96:97], v[156:157] op_sel_hi:[1,0]
	v_pk_mul_f32 v[98:99], v[98:99], v[156:157] op_sel_hi:[1,0]
	v_pk_mul_f32 v[76:77], v[76:77], v[156:157] op_sel_hi:[1,0]
	s_waitcnt lgkmcnt(0)
	v_mov_b32_e32 v0, v175
	v_mov_b32_e32 v1, v176
	v_mov_b32_e32 v175, v177
	v_pk_add_f32 v[0:1], v[0:1], v[174:175]
	v_pk_mul_f32 v[78:79], v[78:79], v[156:157] op_sel_hi:[1,0]
	v_add_f32_e32 v0, v0, v1
	v_fmamk_f32 v0, v0, 0x3b800000, v213
	v_rsq_f32_e32 v0, v0
	v_pk_mul_f32 v[86:87], v[86:87], v[156:157] op_sel_hi:[1,0]
	v_mul_f32_e32 v154, v152, v0
	v_add_u32_e32 v0, 0x20800, v3
	ds_read_b128 v[174:177], v0
	s_waitcnt vmcnt(0)
	v_pk_mul_f32 v[128:129], v[144:145], v[128:129]
	v_pk_mul_f32 v[112:113], v[144:145], v[112:113]
	v_pk_mul_f32 v[120:121], v[140:141], v[120:121]
	v_pk_mul_f32 v[100:101], v[140:141], v[100:101]
	s_waitcnt lgkmcnt(0)
	v_mov_b32_e32 v0, v175
	v_mov_b32_e32 v1, v176
	v_mov_b32_e32 v175, v177
	v_pk_add_f32 v[0:1], v[0:1], v[174:175]
	v_pk_mul_f32 v[84:85], v[140:141], v[84:85]
	v_add_f32_e32 v0, v0, v1
	v_fmamk_f32 v0, v0, 0x3b800000, v213
	v_rsq_f32_e32 v0, v0
	v_pk_mul_f32 v[72:73], v[72:73], v[154:155] op_sel_hi:[1,0]
	v_pk_mul_f32 v[80:81], v[80:81], v[154:155] op_sel_hi:[1,0]
	v_pk_mul_f32 v[82:83], v[82:83], v[154:155] op_sel_hi:[1,0]
	v_mul_f32_e32 v152, v162, v0
	v_add_u32_e32 v0, 0x20900, v3
	ds_read_b128 v[174:177], v0
	v_pk_mul_f32 v[72:73], v[140:141], v[72:73]
	v_pk_mul_f32 v[68:69], v[68:69], v[154:155] op_sel_hi:[1,0]
	v_pk_mul_f32 v[70:71], v[70:71], v[154:155] op_sel_hi:[1,0]
	v_pk_mul_f32 v[102:103], v[142:143], v[102:103]
	s_waitcnt lgkmcnt(0)
	v_mov_b32_e32 v0, v175
	v_mov_b32_e32 v1, v176
	v_mov_b32_e32 v175, v177
	v_pk_add_f32 v[0:1], v[0:1], v[174:175]
	v_pk_mul_f32 v[86:87], v[142:143], v[86:87]
	v_add_f32_e32 v0, v0, v1
	v_fmamk_f32 v0, v0, 0x3b800000, v213
	v_rsq_f32_e32 v0, v0
	v_pk_mul_f32 v[130:131], v[146:147], v[130:131]
	v_pk_mul_f32 v[74:75], v[74:75], v[154:155] op_sel_hi:[1,0]
	v_pk_mul_f32 v[122:123], v[142:143], v[122:123]
	v_mul_f32_e32 v150, v164, v0
	v_add_u32_e32 v0, 0x20a00, v3
	ds_read_b128 v[162:165], v0
	v_pk_mul_f32 v[56:57], v[56:57], v[150:151] op_sel_hi:[1,0]
	v_pk_mul_f32 v[20:21], v[20:21], v[150:151] op_sel_hi:[1,0]
	v_pk_mul_f32 v[22:23], v[22:23], v[150:151] op_sel_hi:[1,0]
	v_pk_mul_f32 v[56:57], v[136:137], v[56:57]
	s_waitcnt lgkmcnt(0)
	v_mov_b32_e32 v0, v163
	v_mov_b32_e32 v1, v164
	v_mov_b32_e32 v163, v165
	v_pk_add_f32 v[0:1], v[0:1], v[162:163]
	v_pk_mul_f32 v[22:23], v[142:143], v[22:23]
	v_add_f32_e32 v0, v0, v1
	v_fmamk_f32 v0, v0, 0x3b800000, v213
	v_rsq_f32_e32 v0, v0
	v_pk_mul_f32 v[20:21], v[140:141], v[20:21]
	v_pk_mul_f32 v[16:17], v[16:17], v[150:151] op_sel_hi:[1,0]
	v_pk_mul_f32 v[18:19], v[18:19], v[150:151] op_sel_hi:[1,0]
	v_mul_f32_e32 v148, v166, v0
	v_add_u32_e32 v0, 0x20b00, v3
	ds_read_b128 v[162:165], v0
	v_mov_b32_e32 v3, v217
	v_pk_mul_f32 v[48:49], v[48:49], v[148:149] op_sel_hi:[1,0]
	v_and_b32_e32 v153, 48, v3
	s_waitcnt lgkmcnt(0)
	v_mov_b32_e32 v0, v163
	v_mov_b32_e32 v1, v164
	v_mov_b32_e32 v163, v165
	v_pk_add_f32 v[0:1], v[0:1], v[162:163]
	v_pk_mul_f32 v[162:163], v[138:139], v[126:127]
	v_pk_mul_f32 v[126:127], v[136:137], v[124:125]
	v_cvt_pk_bf16_f32 v124, v128, v129
	v_pk_mul_f32 v[128:129], v[134:135], v[118:119]
	v_pk_mul_f32 v[118:119], v[132:133], v[116:117]
	v_cvt_pk_bf16_f32 v116, v120, v121
	v_pk_mul_f32 v[120:121], v[138:139], v[110:111]
	v_pk_mul_f32 v[110:111], v[136:137], v[108:109]
	v_cvt_pk_bf16_f32 v108, v112, v113
	v_pk_mul_f32 v[112:113], v[134:135], v[94:95]
	v_pk_mul_f32 v[94:95], v[132:133], v[92:93]
	v_cvt_pk_bf16_f32 v92, v100, v101
	v_pk_mul_f32 v[100:101], v[104:105], v[156:157] op_sel_hi:[1,0]
	v_add_f32_e32 v0, v0, v1
	v_pk_mul_f32 v[100:101], v[144:145], v[100:101]
	v_fmamk_f32 v0, v0, 0x3b800000, v213
	v_pk_mul_f32 v[104:105], v[138:139], v[98:99]
	v_pk_mul_f32 v[98:99], v[136:137], v[96:97]
	v_cvt_pk_bf16_f32 v96, v100, v101
	v_pk_mul_f32 v[100:101], v[134:135], v[78:79]
	v_pk_mul_f32 v[78:79], v[132:133], v[76:77]
	v_cvt_pk_bf16_f32 v76, v84, v85
	v_pk_mul_f32 v[84:85], v[88:89], v[154:155] op_sel_hi:[1,0]
	v_pk_mul_f32 v[64:65], v[64:65], v[152:153] op_sel_hi:[1,0]
	v_pk_mul_f32 v[12:13], v[12:13], v[152:153] op_sel_hi:[1,0]
	v_pk_mul_f32 v[14:15], v[14:15], v[152:153] op_sel_hi:[1,0]
	v_rsq_f32_e32 v0, v0
	v_pk_mul_f32 v[84:85], v[144:145], v[84:85]
	v_pk_mul_f32 v[64:65], v[144:145], v[64:65]
	v_pk_mul_f32 v[4:5], v[4:5], v[152:153] op_sel_hi:[1,0]
	v_pk_mul_f32 v[6:7], v[6:7], v[152:153] op_sel_hi:[1,0]
	v_pk_mul_f32 v[14:15], v[142:143], v[14:15]
	v_pk_mul_f32 v[12:13], v[140:141], v[12:13]
	v_pk_mul_f32 v[8:9], v[8:9], v[152:153] op_sel_hi:[1,0]
	v_pk_mul_f32 v[10:11], v[10:11], v[152:153] op_sel_hi:[1,0]
	v_pk_mul_f32 v[88:89], v[138:139], v[82:83]
	v_pk_mul_f32 v[82:83], v[136:137], v[80:81]
	v_cvt_pk_bf16_f32 v80, v84, v85
	v_pk_mul_f32 v[84:85], v[134:135], v[70:71]
	v_pk_mul_f32 v[70:71], v[132:133], v[68:69]
	v_cvt_pk_bf16_f32 v68, v72, v73
	v_pk_mul_f32 v[72:73], v[138:139], v[6:7]
	v_pk_mul_f32 v[6:7], v[136:137], v[4:5]
	v_cvt_pk_bf16_f32 v4, v64, v65
	v_pk_mul_f32 v[64:65], v[134:135], v[10:11]
	v_pk_mul_f32 v[10:11], v[132:133], v[8:9]
	v_cvt_pk_bf16_f32 v8, v12, v13
	v_cvt_pk_bf16_f32 v9, v14, v15
	v_pk_mul_f32 v[12:13], v[60:61], v[150:151] op_sel_hi:[1,0]
	v_pk_mul_f32 v[14:15], v[62:63], v[150:151] op_sel_hi:[1,0]
	v_pk_mul_f32 v[12:13], v[144:145], v[12:13]
	v_pk_mul_f32 v[14:15], v[146:147], v[14:15]
	v_cvt_pk_bf16_f32 v12, v12, v13
	v_cvt_pk_bf16_f32 v13, v14, v15
	v_cvt_pk_bf16_f32 v14, v56, v57
	v_pk_mul_f32 v[56:57], v[134:135], v[18:19]
	v_pk_mul_f32 v[18:19], v[132:133], v[16:17]
	v_cvt_pk_bf16_f32 v16, v20, v21
	v_cvt_pk_bf16_f32 v17, v22, v23
	v_pk_mul_f32 v[20:21], v[52:53], v[148:149] op_sel_hi:[1,0]
	v_pk_mul_f32 v[22:23], v[54:55], v[148:149] op_sel_hi:[1,0]
	v_pk_mul_f32 v[28:29], v[28:29], v[148:149] op_sel_hi:[1,0]
	v_pk_mul_f32 v[30:31], v[30:31], v[148:149] op_sel_hi:[1,0]
	v_mul_f32_e32 v0, v168, v0
	v_pk_mul_f32 v[22:23], v[146:147], v[22:23]
	v_pk_mul_f32 v[20:21], v[144:145], v[20:21]
	v_pk_mul_f32 v[48:49], v[136:137], v[48:49]
	v_pk_mul_f32 v[30:31], v[142:143], v[30:31]
	v_pk_mul_f32 v[28:29], v[140:141], v[28:29]
	v_pk_mul_f32 v[24:25], v[24:25], v[148:149] op_sel_hi:[1,0]
	v_pk_mul_f32 v[26:27], v[26:27], v[148:149] op_sel_hi:[1,0]
	v_cvt_pk_bf16_f32 v20, v20, v21
	v_cvt_pk_bf16_f32 v21, v22, v23
	v_cvt_pk_bf16_f32 v22, v48, v49
	v_pk_mul_f32 v[48:49], v[134:135], v[26:27]
	v_pk_mul_f32 v[26:27], v[132:133], v[24:25]
	v_cvt_pk_bf16_f32 v24, v28, v29
	v_cvt_pk_bf16_f32 v25, v30, v31
	v_pk_mul_f32 v[28:29], v[44:45], v[0:1] op_sel_hi:[1,0]
	v_pk_mul_f32 v[30:31], v[46:47], v[0:1] op_sel_hi:[1,0]
	v_pk_mul_f32 v[40:41], v[40:41], v[0:1] op_sel_hi:[1,0]
	v_pk_mul_f32 v[42:43], v[42:43], v[0:1] op_sel_hi:[1,0]
	v_pk_mul_f32 v[36:37], v[36:37], v[0:1] op_sel_hi:[1,0]
	v_pk_mul_f32 v[38:39], v[38:39], v[0:1] op_sel_hi:[1,0]
	v_pk_mul_f32 v[32:33], v[32:33], v[0:1] op_sel_hi:[1,0]
	v_pk_mul_f32 v[0:1], v[34:35], v[0:1] op_sel_hi:[1,0]
	v_readfirstlane_b32 s7, v3
	v_pk_mul_f32 v[0:1], v[134:135], v[0:1]
	v_pk_mul_f32 v[34:35], v[132:133], v[32:33]
	s_ashr_i32 s8, s7, 2
	v_pk_mul_f32 v[36:37], v[140:141], v[36:37]
	v_cvt_pk_bf16_f32 v34, v34, v35
	v_cvt_pk_bf16_f32 v35, v0, v1
	v_bfi_b32 v1, -16, s8, v3
	v_cvt_pk_bf16_f32 v32, v36, v37
	v_mul_lo_u32 v36, v1, s16
	v_add3_u32 v175, 0, v36, v153
	v_ashrrev_i32_e32 v36, 3, v3
	v_pk_mul_f32 v[30:31], v[146:147], v[30:31]
	v_pk_mul_f32 v[28:29], v[144:145], v[28:29]
	v_pk_mul_f32 v[40:41], v[136:137], v[40:41]
	v_pk_mul_f32 v[38:39], v[142:143], v[38:39]
	v_ashrrev_i32_e32 v37, 31, v36
	v_cvt_pk_bf16_f32 v28, v28, v29
	v_cvt_pk_bf16_f32 v29, v30, v31
	v_cvt_pk_bf16_f32 v30, v40, v41
	v_cvt_pk_bf16_f32 v33, v38, v39
	v_and_b32_e32 v38, 15, v3
	v_bfe_u32 v39, v3, 4, 2
	v_lshlrev_b64 v[44:45], 13, v[36:37]
	v_lshlrev_b32_e32 v37, 3, v3
	v_lshlrev_b32_e32 v40, 4, v3
	v_bfe_u32 v3, v3, 2, 2
	v_mul_lo_u32 v36, v36, s16
	v_and_b32_e32 v180, 0x70, v40
	v_lshl_or_b32 v3, v39, 2, v3
	s_ashr_i32 s7, s6, 31
	s_lshl_b32 s8, s53, 8
	v_add3_u32 v170, s10, v36, v180
	v_mul_u32_u24_e32 v38, 0x210, v38
	v_add3_u32 v168, s11, v36, v180
	v_mul_u32_u24_e32 v3, 0x210, v3
	v_and_b32_e32 v36, 24, v37
	s_lshl_b64 s[12:13], s[6:7], 21
	s_ashr_i32 s9, s8, 31
	v_add3_u32 v174, s10, v153, v38
	v_add3_u32 v173, s11, v153, v38
	v_add3_u32 v169, s10, v3, v36
	v_add3_u32 v3, s11, v3, v36
	s_lshl_b64 s[10:11], s[6:7], 22
	s_add_u32 s12, s60, s12
	s_addc_u32 s13, s61, s13
	v_lshl_add_u64 v[44:45], s[12:13], 0, v[44:45]
	s_lshl_b32 s12, s0, 11
	s_ashr_i32 s13, s12, 31
	v_cvt_pk_bf16_f32 v93, v102, v103
	v_pk_mul_f32 v[102:103], v[106:107], v[156:157] op_sel_hi:[1,0]
	v_cvt_pk_bf16_f32 v77, v86, v87
	v_pk_mul_f32 v[86:87], v[90:91], v[154:155] op_sel_hi:[1,0]
	v_mul_lo_u32 v36, v149, s16
	v_lshl_add_u64 v[44:45], s[12:13], 1, v[44:45]
	s_lshl_b64 s[8:9], s[8:9], 1
	v_cvt_pk_bf16_f32 v125, v130, v131
	v_cvt_pk_bf16_f32 v126, v126, v127
	v_cvt_pk_bf16_f32 v127, v162, v163
	v_pk_mul_f32 v[114:115], v[146:147], v[114:115]
	v_pk_mul_f32 v[102:103], v[146:147], v[102:103]
	v_pk_mul_f32 v[86:87], v[146:147], v[86:87]
	v_pk_mul_f32 v[74:75], v[142:143], v[74:75]
	v_add3_u32 v176, s15, v151, v36
	v_lshl_add_u64 v[44:45], v[44:45], 0, s[8:9]
	v_cvt_pk_bf16_f32 v117, v122, v123
	v_cvt_pk_bf16_f32 v118, v118, v119
	v_cvt_pk_bf16_f32 v119, v128, v129
	v_cvt_pk_bf16_f32 v109, v114, v115
	v_cvt_pk_bf16_f32 v110, v110, v111
	v_cvt_pk_bf16_f32 v111, v120, v121
	v_cvt_pk_bf16_f32 v94, v94, v95
	v_cvt_pk_bf16_f32 v95, v112, v113
	v_cvt_pk_bf16_f32 v97, v102, v103
	v_cvt_pk_bf16_f32 v98, v98, v99
	v_cvt_pk_bf16_f32 v99, v104, v105
	v_cvt_pk_bf16_f32 v78, v78, v79
	v_cvt_pk_bf16_f32 v79, v100, v101
	v_cvt_pk_bf16_f32 v81, v86, v87
	v_cvt_pk_bf16_f32 v82, v82, v83
	v_cvt_pk_bf16_f32 v83, v88, v89
	v_cvt_pk_bf16_f32 v69, v74, v75
	v_cvt_pk_bf16_f32 v70, v70, v71
	v_cvt_pk_bf16_f32 v71, v84, v85
	s_waitcnt lgkmcnt(0)
	s_barrier
	ds_write_b128 v176, v[124:127]
	ds_write_b128 v176, v[116:119] offset:256
	ds_write_b128 v176, v[108:111] offset:8448
	ds_write_b128 v176, v[92:95] offset:8704
	ds_write_b128 v176, v[96:99] offset:16896
	ds_write_b128 v176, v[76:79] offset:17152
	ds_write_b128 v176, v[80:83] offset:25344
	ds_write_b128 v176, v[68:71] offset:25600
	v_lshl_add_u64 v[166:167], v[44:45], 0, v[180:181]
	s_mov_b32 s7, 0x80000
	v_pk_mul_f32 v[66:67], v[66:67], v[152:153] op_sel_hi:[1,0]
	v_pk_mul_f32 v[58:59], v[58:59], v[150:151] op_sel_hi:[1,0]
	v_pk_mul_f32 v[50:51], v[50:51], v[148:149] op_sel_hi:[1,0]
	v_pk_mul_f32 v[42:43], v[138:139], v[42:43]
	s_waitcnt lgkmcnt(0)
	s_barrier
	v_add_co_u32_e32 v164, vcc, s7, v166
	v_pk_mul_f32 v[66:67], v[146:147], v[66:67]
	v_pk_mul_f32 v[58:59], v[138:139], v[58:59]
	v_pk_mul_f32 v[50:51], v[138:139], v[50:51]
	v_cvt_pk_bf16_f32 v31, v42, v43
	v_lshlrev_b32_e32 v0, 3, v39
	ds_read_b128 v[124:127], v175
	ds_read_b128 v[120:123], v175 offset:64
	ds_read_b128 v[116:119], v175 offset:128
	ds_read_b128 v[108:111], v175 offset:192
	ds_read_b128 v[80:83], v175 offset:256
	ds_read_b128 v[76:79], v175 offset:320
	ds_read_b128 v[40:43], v175 offset:384
	ds_read_b128 v[36:39], v175 offset:448
	global_load_dwordx4 v[60:63], v[166:167], off
	v_addc_co_u32_e32 v165, vcc, 0, v167, vcc
	v_cvt_pk_bf16_f32 v5, v66, v67
	v_cvt_pk_bf16_f32 v6, v6, v7
	v_cvt_pk_bf16_f32 v7, v72, v73
	v_cvt_pk_bf16_f32 v10, v10, v11
	v_cvt_pk_bf16_f32 v11, v64, v65
	v_cvt_pk_bf16_f32 v15, v58, v59
	v_cvt_pk_bf16_f32 v18, v18, v19
	v_cvt_pk_bf16_f32 v19, v56, v57
	v_cvt_pk_bf16_f32 v23, v50, v51
	v_cvt_pk_bf16_f32 v26, v26, v27
	v_cvt_pk_bf16_f32 v27, v48, v49
	global_load_dwordx4 v[44:47], v[164:165], off
	global_load_dwordx4 v[64:67], v[166:167], off offset:128
	global_load_dwordx4 v[48:51], v[164:165], off offset:128
	global_load_dwordx4 v[68:71], v[166:167], off offset:256
	global_load_dwordx4 v[52:55], v[164:165], off offset:256
	global_load_dwordx4 v[72:75], v[166:167], off offset:384
	global_load_dwordx4 v[56:59], v[164:165], off offset:384
	s_mov_b32 s7, 0x100000
	v_add_co_u32_e32 v162, vcc, s7, v166
	s_waitcnt vmcnt(7)
	ds_write_b128 v170, v[60:63]
	s_waitcnt vmcnt(5)
	ds_write_b128 v170, v[64:67] offset:128
	s_waitcnt vmcnt(3)
	ds_write_b128 v170, v[68:71] offset:256
	s_waitcnt vmcnt(1)
	ds_write_b128 v170, v[72:75] offset:384
	v_addc_co_u32_e32 v163, vcc, 0, v167, vcc
	global_load_dwordx4 v[60:63], v[162:163], off
	global_load_dwordx4 v[64:67], v[162:163], off offset:128
	global_load_dwordx4 v[68:71], v[162:163], off offset:256
	global_load_dwordx4 v[72:75], v[162:163], off offset:384
	s_waitcnt lgkmcnt(0)
	s_barrier
	ds_read_b128 v[204:207], v174
	ds_read_b128 v[208:211], v174 offset:8448
	ds_read_b128 v[218:221], v174 offset:16896
	ds_read_b128 v[224:227], v174 offset:25344
	ds_read_b128 v[228:231], v174 offset:64
	ds_read_b128 v[232:235], v174 offset:8512
	ds_read_b128 v[236:239], v174 offset:16960
	ds_read_b128 v[240:243], v174 offset:25408
	s_waitcnt lgkmcnt(7)
	v_mfma_f32_16x16x32_bf16 v[84:87], v[204:207], v[124:127], 0
	ds_read_b128 v[204:207], v174 offset:128
	s_waitcnt lgkmcnt(7)
	v_mfma_f32_16x16x32_bf16 v[88:91], v[208:211], v[124:127], 0
	ds_read_b128 v[208:211], v174 offset:8576
	s_mov_b32 s7, 0x180000
	v_add_co_u32_e32 v160, vcc, s7, v166
	s_nop 1
	s_waitcnt lgkmcnt(7)
	v_mfma_f32_16x16x32_bf16 v[92:95], v[218:221], v[124:127], 0
	ds_read_b128 v[218:221], v174 offset:17024
	v_addc_co_u32_e32 v161, vcc, 0, v167, vcc
	s_nop 1
	s_waitcnt lgkmcnt(7)
	v_mfma_f32_16x16x32_bf16 v[96:99], v[224:227], v[124:127], 0
	ds_read_b128 v[224:227], v174 offset:25472
	s_mov_b32 s7, 0xf149f2ca
	s_waitcnt lgkmcnt(7)
	v_mfma_f32_16x16x32_bf16 v[84:87], v[228:231], v[120:123], v[84:87]
	ds_read_b128 v[228:231], v174 offset:192
	s_waitcnt lgkmcnt(7)
	v_mfma_f32_16x16x32_bf16 v[88:91], v[232:235], v[120:123], v[88:91]
	ds_read_b128 v[232:235], v174 offset:8640
	s_waitcnt lgkmcnt(7)
	v_mfma_f32_16x16x32_bf16 v[92:95], v[236:239], v[120:123], v[92:95]
	ds_read_b128 v[236:239], v174 offset:17088
	s_waitcnt lgkmcnt(7)
	v_mfma_f32_16x16x32_bf16 v[96:99], v[240:243], v[120:123], v[96:99]
	ds_read_b128 v[240:243], v174 offset:25536
	s_waitcnt lgkmcnt(7)
	v_mfma_f32_16x16x32_bf16 v[84:87], v[204:207], v[116:119], v[84:87]
	ds_read_b128 v[204:207], v174 offset:256
	s_waitcnt lgkmcnt(7)
	v_mfma_f32_16x16x32_bf16 v[88:91], v[208:211], v[116:119], v[88:91]
	ds_read_b128 v[208:211], v174 offset:8704
	s_waitcnt lgkmcnt(7)
	v_mfma_f32_16x16x32_bf16 v[92:95], v[218:221], v[116:119], v[92:95]
	ds_read_b128 v[218:221], v174 offset:17152
	s_waitcnt lgkmcnt(7)
	v_mfma_f32_16x16x32_bf16 v[96:99], v[224:227], v[116:119], v[96:99]
	ds_read_b128 v[224:227], v174 offset:25600
	s_waitcnt lgkmcnt(7)
	v_mfma_f32_16x16x32_bf16 v[84:87], v[228:231], v[108:111], v[84:87]
	ds_read_b128 v[228:231], v174 offset:320
	s_waitcnt lgkmcnt(7)
	v_mfma_f32_16x16x32_bf16 v[88:91], v[232:235], v[108:111], v[88:91]
	ds_read_b128 v[232:235], v174 offset:8768
	s_waitcnt lgkmcnt(7)
	v_mfma_f32_16x16x32_bf16 v[92:95], v[236:239], v[108:111], v[92:95]
	ds_read_b128 v[236:239], v174 offset:17216
	s_waitcnt lgkmcnt(7)
	v_mfma_f32_16x16x32_bf16 v[96:99], v[240:243], v[108:111], v[96:99]
	ds_read_b128 v[240:243], v174 offset:25664
	s_waitcnt lgkmcnt(7)
	v_mfma_f32_16x16x32_bf16 v[84:87], v[204:207], v[80:83], v[84:87]
	ds_read_b128 v[204:207], v174 offset:384
	s_waitcnt lgkmcnt(7)
	v_mfma_f32_16x16x32_bf16 v[88:91], v[208:211], v[80:83], v[88:91]
	ds_read_b128 v[208:211], v174 offset:8832
	s_waitcnt lgkmcnt(7)
	v_mfma_f32_16x16x32_bf16 v[92:95], v[218:221], v[80:83], v[92:95]
	ds_read_b128 v[218:221], v174 offset:17280
	s_waitcnt lgkmcnt(7)
	v_mfma_f32_16x16x32_bf16 v[96:99], v[224:227], v[80:83], v[96:99]
	ds_read_b128 v[224:227], v174 offset:25728
	s_waitcnt lgkmcnt(7)
	v_mfma_f32_16x16x32_bf16 v[84:87], v[228:231], v[76:79], v[84:87]
	ds_read_b128 v[228:231], v174 offset:448
	s_waitcnt lgkmcnt(7)
	v_mfma_f32_16x16x32_bf16 v[88:91], v[232:235], v[76:79], v[88:91]
	ds_read_b128 v[232:235], v174 offset:8896
	s_waitcnt lgkmcnt(7)
	v_mfma_f32_16x16x32_bf16 v[92:95], v[236:239], v[76:79], v[92:95]
	ds_read_b128 v[236:239], v174 offset:17344
	s_waitcnt lgkmcnt(7)
	v_mfma_f32_16x16x32_bf16 v[96:99], v[240:243], v[76:79], v[96:99]
	s_waitcnt lgkmcnt(6)
	v_mfma_f32_16x16x32_bf16 v[84:87], v[204:207], v[40:43], v[84:87]
	s_waitcnt lgkmcnt(5)
	v_mfma_f32_16x16x32_bf16 v[88:91], v[208:211], v[40:43], v[88:91]
	s_waitcnt lgkmcnt(4)
	v_mfma_f32_16x16x32_bf16 v[92:95], v[218:221], v[40:43], v[92:95]
	s_waitcnt lgkmcnt(3)
	v_mfma_f32_16x16x32_bf16 v[96:99], v[224:227], v[40:43], v[96:99]
	s_waitcnt lgkmcnt(2)
	v_mfma_f32_16x16x32_bf16 v[84:87], v[228:231], v[36:39], v[84:87]
	s_waitcnt lgkmcnt(1)
	v_mfma_f32_16x16x32_bf16 v[88:91], v[232:235], v[36:39], v[88:91]
	s_waitcnt lgkmcnt(0)
	v_mfma_f32_16x16x32_bf16 v[92:95], v[236:239], v[36:39], v[92:95]
	s_nop 7
	ds_read_b128 v[100:103], v174 offset:25792
	ds_write_b128 v168, v[44:47]
	ds_write_b128 v168, v[48:51] offset:128
	ds_write_b128 v168, v[52:55] offset:256
	s_waitcnt vmcnt(4)
	ds_write_b128 v168, v[56:59] offset:384
	global_load_dwordx4 v[44:47], v[160:161], off
	global_load_dwordx4 v[48:51], v[160:161], off offset:128
	global_load_dwordx4 v[52:55], v[160:161], off offset:256
	global_load_dwordx4 v[56:59], v[160:161], off offset:384
	s_waitcnt lgkmcnt(0)
	s_barrier
	s_waitcnt lgkmcnt(4)
	v_mfma_f32_16x16x32_bf16 v[96:99], v[100:103], v[36:39], v[96:99]
	ds_read_b128 v[204:207], v173
	ds_read_b128 v[208:211], v173 offset:8448
	ds_read_b128 v[218:221], v173 offset:16896
	ds_read_b128 v[224:227], v173 offset:25344
	ds_read_b128 v[228:231], v173 offset:64
	ds_read_b128 v[232:235], v173 offset:8512
	ds_read_b128 v[236:239], v173 offset:16960
	ds_read_b128 v[240:243], v173 offset:25408
	s_waitcnt lgkmcnt(7)
	v_mfma_f32_16x16x32_bf16 v[100:103], v[204:207], v[124:127], 0
	ds_read_b128 v[204:207], v173 offset:128
	s_waitcnt lgkmcnt(7)
	v_mfma_f32_16x16x32_bf16 v[104:107], v[208:211], v[124:127], 0
	ds_read_b128 v[208:211], v173 offset:8576
	s_waitcnt lgkmcnt(7)
	v_mfma_f32_16x16x32_bf16 v[112:115], v[218:221], v[124:127], 0
	ds_read_b128 v[218:221], v173 offset:17024
	s_waitcnt lgkmcnt(7)
	v_mfma_f32_16x16x32_bf16 v[128:131], v[224:227], v[124:127], 0
	ds_read_b128 v[224:227], v173 offset:25472
	s_waitcnt lgkmcnt(7)
	v_mfma_f32_16x16x32_bf16 v[100:103], v[228:231], v[120:123], v[100:103]
	ds_read_b128 v[228:231], v173 offset:192
	s_waitcnt lgkmcnt(7)
	v_mfma_f32_16x16x32_bf16 v[104:107], v[232:235], v[120:123], v[104:107]
	ds_read_b128 v[232:235], v173 offset:8640
	s_waitcnt lgkmcnt(7)
	v_mfma_f32_16x16x32_bf16 v[112:115], v[236:239], v[120:123], v[112:115]
	ds_read_b128 v[236:239], v173 offset:17088
	s_waitcnt lgkmcnt(7)
	v_mfma_f32_16x16x32_bf16 v[128:131], v[240:243], v[120:123], v[128:131]
	ds_read_b128 v[240:243], v173 offset:25536
	s_waitcnt lgkmcnt(7)
	v_mfma_f32_16x16x32_bf16 v[100:103], v[204:207], v[116:119], v[100:103]
	ds_read_b128 v[204:207], v173 offset:256
	s_waitcnt lgkmcnt(7)
	v_mfma_f32_16x16x32_bf16 v[104:107], v[208:211], v[116:119], v[104:107]
	ds_read_b128 v[208:211], v173 offset:8704
	s_waitcnt lgkmcnt(7)
	v_mfma_f32_16x16x32_bf16 v[112:115], v[218:221], v[116:119], v[112:115]
	ds_read_b128 v[218:221], v173 offset:17152
	s_waitcnt lgkmcnt(7)
	v_mfma_f32_16x16x32_bf16 v[128:131], v[224:227], v[116:119], v[128:131]
	ds_read_b128 v[224:227], v173 offset:25600
	s_waitcnt lgkmcnt(7)
	v_mfma_f32_16x16x32_bf16 v[100:103], v[228:231], v[108:111], v[100:103]
	ds_read_b128 v[228:231], v173 offset:320
	s_waitcnt lgkmcnt(7)
	v_mfma_f32_16x16x32_bf16 v[104:107], v[232:235], v[108:111], v[104:107]
	ds_read_b128 v[232:235], v173 offset:8768
	s_waitcnt lgkmcnt(7)
	v_mfma_f32_16x16x32_bf16 v[112:115], v[236:239], v[108:111], v[112:115]
	ds_read_b128 v[236:239], v173 offset:17216
	s_waitcnt lgkmcnt(7)
	v_mfma_f32_16x16x32_bf16 v[128:131], v[240:243], v[108:111], v[128:131]
	ds_read_b128 v[240:243], v173 offset:25664
	s_waitcnt lgkmcnt(7)
	v_mfma_f32_16x16x32_bf16 v[100:103], v[204:207], v[80:83], v[100:103]
	ds_read_b128 v[204:207], v173 offset:384
	s_waitcnt lgkmcnt(7)
	v_mfma_f32_16x16x32_bf16 v[104:107], v[208:211], v[80:83], v[104:107]
	ds_read_b128 v[208:211], v173 offset:8832
	s_waitcnt lgkmcnt(7)
	v_mfma_f32_16x16x32_bf16 v[112:115], v[218:221], v[80:83], v[112:115]
	ds_read_b128 v[218:221], v173 offset:17280
	s_waitcnt lgkmcnt(7)
	v_mfma_f32_16x16x32_bf16 v[128:131], v[224:227], v[80:83], v[128:131]
	ds_read_b128 v[224:227], v173 offset:25728
	s_waitcnt lgkmcnt(7)
	v_mfma_f32_16x16x32_bf16 v[100:103], v[228:231], v[76:79], v[100:103]
	ds_read_b128 v[228:231], v173 offset:448
	s_waitcnt lgkmcnt(7)
	v_mfma_f32_16x16x32_bf16 v[104:107], v[232:235], v[76:79], v[104:107]
	ds_read_b128 v[232:235], v173 offset:8896
	s_waitcnt lgkmcnt(7)
	v_mfma_f32_16x16x32_bf16 v[112:115], v[236:239], v[76:79], v[112:115]
	ds_read_b128 v[236:239], v173 offset:17344
	s_waitcnt lgkmcnt(7)
	v_mfma_f32_16x16x32_bf16 v[128:131], v[240:243], v[76:79], v[128:131]
	s_waitcnt lgkmcnt(6)
	v_mfma_f32_16x16x32_bf16 v[100:103], v[204:207], v[40:43], v[100:103]
	s_waitcnt lgkmcnt(5)
	v_mfma_f32_16x16x32_bf16 v[104:107], v[208:211], v[40:43], v[104:107]
	s_waitcnt lgkmcnt(4)
	v_mfma_f32_16x16x32_bf16 v[112:115], v[218:221], v[40:43], v[112:115]
	s_waitcnt lgkmcnt(3)
	v_mfma_f32_16x16x32_bf16 v[128:131], v[224:227], v[40:43], v[128:131]
	s_waitcnt lgkmcnt(2)
	v_mfma_f32_16x16x32_bf16 v[100:103], v[228:231], v[36:39], v[100:103]
	s_waitcnt lgkmcnt(1)
	v_mfma_f32_16x16x32_bf16 v[104:107], v[232:235], v[36:39], v[104:107]
	s_waitcnt lgkmcnt(0)
	v_mfma_f32_16x16x32_bf16 v[112:115], v[236:239], v[36:39], v[112:115]
	s_nop 7
	ds_read_b128 v[132:135], v173 offset:25792
	s_waitcnt vmcnt(7)
	ds_write_b128 v170, v[60:63]
	s_waitcnt vmcnt(6)
	ds_write_b128 v170, v[64:67] offset:128
	s_waitcnt vmcnt(5)
	ds_write_b128 v170, v[68:71] offset:256
	s_waitcnt vmcnt(4)
	ds_write_b128 v170, v[72:75] offset:384
	global_load_dwordx4 v[60:63], v[166:167], off offset:2048
	global_load_dwordx4 v[64:67], v[166:167], off offset:2176
	global_load_dwordx4 v[68:71], v[166:167], off offset:2304
	global_load_dwordx4 v[72:75], v[166:167], off offset:2432
	s_waitcnt lgkmcnt(0)
	s_barrier
	s_waitcnt lgkmcnt(4)
	v_mfma_f32_16x16x32_bf16 v[128:131], v[132:135], v[36:39], v[128:131]
	ds_read_b128 v[204:207], v174
	ds_read_b128 v[208:211], v174 offset:8448
	ds_read_b128 v[218:221], v174 offset:16896
	ds_read_b128 v[224:227], v174 offset:25344
	ds_read_b128 v[228:231], v174 offset:64
	ds_read_b128 v[232:235], v174 offset:8512
	ds_read_b128 v[236:239], v174 offset:16960
	ds_read_b128 v[240:243], v174 offset:25408
	s_waitcnt lgkmcnt(7)
	v_mfma_f32_16x16x32_bf16 v[132:135], v[204:207], v[124:127], 0
	ds_read_b128 v[204:207], v174 offset:128
	s_waitcnt lgkmcnt(7)
	v_mfma_f32_16x16x32_bf16 v[136:139], v[208:211], v[124:127], 0
	ds_read_b128 v[208:211], v174 offset:8576
	s_waitcnt lgkmcnt(7)
	v_mfma_f32_16x16x32_bf16 v[140:143], v[218:221], v[124:127], 0
	ds_read_b128 v[218:221], v174 offset:17024
	s_waitcnt lgkmcnt(7)
	v_mfma_f32_16x16x32_bf16 v[144:147], v[224:227], v[124:127], 0
	ds_read_b128 v[224:227], v174 offset:25472
	s_waitcnt lgkmcnt(7)
	v_mfma_f32_16x16x32_bf16 v[132:135], v[228:231], v[120:123], v[132:135]
	ds_read_b128 v[228:231], v174 offset:192
	s_waitcnt lgkmcnt(7)
	v_mfma_f32_16x16x32_bf16 v[136:139], v[232:235], v[120:123], v[136:139]
	ds_read_b128 v[232:235], v174 offset:8640
	s_waitcnt lgkmcnt(7)
	v_mfma_f32_16x16x32_bf16 v[140:143], v[236:239], v[120:123], v[140:143]
	ds_read_b128 v[236:239], v174 offset:17088
	s_waitcnt lgkmcnt(7)
	v_mfma_f32_16x16x32_bf16 v[144:147], v[240:243], v[120:123], v[144:147]
	ds_read_b128 v[240:243], v174 offset:25536
	s_waitcnt lgkmcnt(7)
	v_mfma_f32_16x16x32_bf16 v[132:135], v[204:207], v[116:119], v[132:135]
	ds_read_b128 v[204:207], v174 offset:256
	s_waitcnt lgkmcnt(7)
	v_mfma_f32_16x16x32_bf16 v[136:139], v[208:211], v[116:119], v[136:139]
	ds_read_b128 v[208:211], v174 offset:8704
	s_waitcnt lgkmcnt(7)
	v_mfma_f32_16x16x32_bf16 v[140:143], v[218:221], v[116:119], v[140:143]
	ds_read_b128 v[218:221], v174 offset:17152
	s_waitcnt lgkmcnt(7)
	v_mfma_f32_16x16x32_bf16 v[144:147], v[224:227], v[116:119], v[144:147]
	ds_read_b128 v[224:227], v174 offset:25600
	s_waitcnt lgkmcnt(7)
	v_mfma_f32_16x16x32_bf16 v[132:135], v[228:231], v[108:111], v[132:135]
	ds_read_b128 v[228:231], v174 offset:320
	s_waitcnt lgkmcnt(7)
	v_mfma_f32_16x16x32_bf16 v[136:139], v[232:235], v[108:111], v[136:139]
	ds_read_b128 v[232:235], v174 offset:8768
	s_waitcnt lgkmcnt(7)
	v_mfma_f32_16x16x32_bf16 v[140:143], v[236:239], v[108:111], v[140:143]
	ds_read_b128 v[236:239], v174 offset:17216
	s_waitcnt lgkmcnt(7)
	v_mfma_f32_16x16x32_bf16 v[144:147], v[240:243], v[108:111], v[144:147]
	ds_read_b128 v[240:243], v174 offset:25664
	s_waitcnt lgkmcnt(7)
	v_mfma_f32_16x16x32_bf16 v[132:135], v[204:207], v[80:83], v[132:135]
	ds_read_b128 v[204:207], v174 offset:384
	s_waitcnt lgkmcnt(7)
	v_mfma_f32_16x16x32_bf16 v[136:139], v[208:211], v[80:83], v[136:139]
	ds_read_b128 v[208:211], v174 offset:8832
	s_waitcnt lgkmcnt(7)
	v_mfma_f32_16x16x32_bf16 v[140:143], v[218:221], v[80:83], v[140:143]
	ds_read_b128 v[218:221], v174 offset:17280
	s_waitcnt lgkmcnt(7)
	v_mfma_f32_16x16x32_bf16 v[144:147], v[224:227], v[80:83], v[144:147]
	ds_read_b128 v[224:227], v174 offset:25728
	s_waitcnt lgkmcnt(7)
	v_mfma_f32_16x16x32_bf16 v[132:135], v[228:231], v[76:79], v[132:135]
	ds_read_b128 v[228:231], v174 offset:448
	s_waitcnt lgkmcnt(7)
	v_mfma_f32_16x16x32_bf16 v[136:139], v[232:235], v[76:79], v[136:139]
	ds_read_b128 v[232:235], v174 offset:8896
	s_waitcnt lgkmcnt(7)
	v_mfma_f32_16x16x32_bf16 v[140:143], v[236:239], v[76:79], v[140:143]
	ds_read_b128 v[236:239], v174 offset:17344
	s_waitcnt lgkmcnt(7)
	v_mfma_f32_16x16x32_bf16 v[144:147], v[240:243], v[76:79], v[144:147]
	s_waitcnt lgkmcnt(6)
	v_mfma_f32_16x16x32_bf16 v[132:135], v[204:207], v[40:43], v[132:135]
	s_waitcnt lgkmcnt(5)
	v_mfma_f32_16x16x32_bf16 v[136:139], v[208:211], v[40:43], v[136:139]
	s_waitcnt lgkmcnt(4)
	v_mfma_f32_16x16x32_bf16 v[140:143], v[218:221], v[40:43], v[140:143]
	s_waitcnt lgkmcnt(3)
	v_mfma_f32_16x16x32_bf16 v[144:147], v[224:227], v[40:43], v[144:147]
	s_waitcnt lgkmcnt(2)
	v_mfma_f32_16x16x32_bf16 v[132:135], v[228:231], v[36:39], v[132:135]
	s_waitcnt lgkmcnt(1)
	v_mfma_f32_16x16x32_bf16 v[136:139], v[232:235], v[36:39], v[136:139]
	s_waitcnt lgkmcnt(0)
	v_mfma_f32_16x16x32_bf16 v[140:143], v[236:239], v[36:39], v[140:143]
	s_nop 7
	ds_read_b128 v[148:151], v174 offset:25792
	s_waitcnt vmcnt(7)
	ds_write_b128 v168, v[44:47]
	s_waitcnt vmcnt(6)
	ds_write_b128 v168, v[48:51] offset:128
	s_waitcnt vmcnt(5)
	ds_write_b128 v168, v[52:55] offset:256
	s_waitcnt vmcnt(4)
	ds_write_b128 v168, v[56:59] offset:384
	global_load_dwordx4 v[44:47], v[164:165], off offset:2048
	global_load_dwordx4 v[48:51], v[164:165], off offset:2176
	global_load_dwordx4 v[52:55], v[164:165], off offset:2304
	global_load_dwordx4 v[56:59], v[164:165], off offset:2432
	s_waitcnt lgkmcnt(0)
	s_barrier
	s_waitcnt lgkmcnt(4)
	v_mfma_f32_16x16x32_bf16 v[144:147], v[148:151], v[36:39], v[144:147]
	ds_read_b128 v[148:151], v173
	ds_read_b128 v[152:155], v173 offset:64
	ds_read_b128 v[156:159], v173 offset:8512
	s_waitcnt lgkmcnt(2)
	v_mfma_f32_16x16x32_bf16 v[148:151], v[148:151], v[124:127], 0
	ds_read_b128 v[190:193], v173 offset:16960
	s_waitcnt lgkmcnt(2)
	v_mfma_f32_16x16x32_bf16 v[148:151], v[152:155], v[120:123], v[148:151]
	ds_read_b128 v[152:155], v173 offset:128
	s_waitcnt lgkmcnt(0)
	v_mfma_f32_16x16x32_bf16 v[148:151], v[152:155], v[116:119], v[148:151]
	ds_read_b128 v[152:155], v173 offset:192
	s_waitcnt lgkmcnt(0)
	v_mfma_f32_16x16x32_bf16 v[148:151], v[152:155], v[108:111], v[148:151]
	ds_read_b128 v[152:155], v173 offset:256
	s_waitcnt lgkmcnt(0)
	v_mfma_f32_16x16x32_bf16 v[148:151], v[152:155], v[80:83], v[148:151]
	ds_read_b128 v[152:155], v173 offset:320
	s_waitcnt lgkmcnt(0)
	v_mfma_f32_16x16x32_bf16 v[148:151], v[152:155], v[76:79], v[148:151]
	ds_read_b128 v[152:155], v173 offset:384
	s_waitcnt lgkmcnt(0)
	v_mfma_f32_16x16x32_bf16 v[148:151], v[152:155], v[40:43], v[148:151]
	ds_read_b128 v[152:155], v173 offset:448
	s_waitcnt lgkmcnt(0)
	v_mfma_f32_16x16x32_bf16 v[148:151], v[152:155], v[36:39], v[148:151]
	ds_read_b128 v[152:155], v173 offset:8448
	s_waitcnt lgkmcnt(0)
	v_mfma_f32_16x16x32_bf16 v[152:155], v[152:155], v[124:127], 0
	v_mfma_f32_16x16x32_bf16 v[152:155], v[156:159], v[120:123], v[152:155]
	ds_read_b128 v[156:159], v173 offset:8576
	s_waitcnt lgkmcnt(0)
	v_mfma_f32_16x16x32_bf16 v[152:155], v[156:159], v[116:119], v[152:155]
	ds_read_b128 v[156:159], v173 offset:8640
	s_waitcnt lgkmcnt(0)
	v_mfma_f32_16x16x32_bf16 v[152:155], v[156:159], v[108:111], v[152:155]
	ds_read_b128 v[156:159], v173 offset:8704
	s_waitcnt lgkmcnt(0)
	v_mfma_f32_16x16x32_bf16 v[152:155], v[156:159], v[80:83], v[152:155]
	ds_read_b128 v[156:159], v173 offset:8768
	s_waitcnt lgkmcnt(0)
	v_mfma_f32_16x16x32_bf16 v[152:155], v[156:159], v[76:79], v[152:155]
	ds_read_b128 v[156:159], v173 offset:8832
	s_waitcnt lgkmcnt(0)
	v_mfma_f32_16x16x32_bf16 v[152:155], v[156:159], v[40:43], v[152:155]
	ds_read_b128 v[156:159], v173 offset:8896
	s_waitcnt lgkmcnt(0)
	v_mfma_f32_16x16x32_bf16 v[152:155], v[156:159], v[36:39], v[152:155]
	ds_read_b128 v[156:159], v173 offset:16896
	s_waitcnt lgkmcnt(0)
	v_mfma_f32_16x16x32_bf16 v[156:159], v[156:159], v[124:127], 0
	v_mfma_f32_16x16x32_bf16 v[156:159], v[190:193], v[120:123], v[156:159]
	ds_read_b128 v[190:193], v173 offset:17024
	s_waitcnt lgkmcnt(0)
	v_mfma_f32_16x16x32_bf16 v[156:159], v[190:193], v[116:119], v[156:159]
	ds_read_b128 v[190:193], v173 offset:17088
	s_waitcnt lgkmcnt(0)
	v_mfma_f32_16x16x32_bf16 v[156:159], v[190:193], v[108:111], v[156:159]
	ds_read_b128 v[190:193], v173 offset:17152
	s_waitcnt lgkmcnt(0)
	v_mfma_f32_16x16x32_bf16 v[156:159], v[190:193], v[80:83], v[156:159]
	ds_read_b128 v[190:193], v173 offset:17216
	s_waitcnt lgkmcnt(0)
	v_mfma_f32_16x16x32_bf16 v[156:159], v[190:193], v[76:79], v[156:159]
	ds_read_b128 v[190:193], v173 offset:17280
	s_waitcnt lgkmcnt(0)
	v_mfma_f32_16x16x32_bf16 v[156:159], v[190:193], v[40:43], v[156:159]
	ds_read_b128 v[190:193], v173 offset:17344
	s_waitcnt lgkmcnt(0)
	v_mfma_f32_16x16x32_bf16 v[156:159], v[190:193], v[36:39], v[156:159]
	ds_read_b128 v[190:193], v173 offset:25344
	s_waitcnt lgkmcnt(0)
	v_mfma_f32_16x16x32_bf16 v[124:127], v[190:193], v[124:127], 0
	ds_read_b128 v[190:193], v173 offset:25408
	s_waitcnt lgkmcnt(0)
	v_mfma_f32_16x16x32_bf16 v[120:123], v[190:193], v[120:123], v[124:127]
	s_nop 4
	ds_read_b128 v[124:127], v173 offset:25472
	s_waitcnt lgkmcnt(0)
	v_mfma_f32_16x16x32_bf16 v[116:119], v[124:127], v[116:119], v[120:123]
	s_nop 2
	ds_read_b128 v[120:123], v173 offset:25536
	s_waitcnt lgkmcnt(0)
	v_mfma_f32_16x16x32_bf16 v[108:111], v[120:123], v[108:111], v[116:119]
	s_nop 2
	ds_read_b128 v[116:119], v173 offset:25600
	s_waitcnt lgkmcnt(0)
	v_mfma_f32_16x16x32_bf16 v[80:83], v[116:119], v[80:83], v[108:111]
	s_nop 2
	ds_read_b128 v[108:111], v173 offset:25664
	s_waitcnt lgkmcnt(0)
	v_mfma_f32_16x16x32_bf16 v[76:79], v[108:111], v[76:79], v[80:83]
	s_nop 2
	ds_read_b128 v[80:83], v173 offset:25728
	s_waitcnt lgkmcnt(0)
	v_mfma_f32_16x16x32_bf16 v[40:43], v[80:83], v[40:43], v[76:79]
	s_nop 2
	ds_read_b128 v[76:79], v173 offset:25792
	s_waitcnt vmcnt(7)
	ds_write_b128 v170, v[60:63]
	s_waitcnt vmcnt(6)
	ds_write_b128 v170, v[64:67] offset:128
	s_waitcnt vmcnt(5)
	ds_write_b128 v170, v[68:71] offset:256
	s_waitcnt vmcnt(4)
	ds_write_b128 v170, v[72:75] offset:384
	global_load_dwordx4 v[60:63], v[162:163], off offset:2048
	global_load_dwordx4 v[64:67], v[162:163], off offset:2176
	global_load_dwordx4 v[68:71], v[162:163], off offset:2304
	global_load_dwordx4 v[72:75], v[162:163], off offset:2432
	s_waitcnt lgkmcnt(4)
	v_mfma_f32_16x16x32_bf16 v[36:39], v[76:79], v[36:39], v[40:43]
	s_nop 2
	v_max_f32_e32 v40, v87, v87
	v_max_f32_e32 v41, v86, v86
	v_max_f32_e32 v40, v41, v40
	v_max_f32_e32 v41, v91, v91
	v_max_f32_e32 v42, v90, v90
	v_max_f32_e32 v41, v42, v41
	v_max3_f32 v40, v84, v85, v40
	v_max3_f32 v41, v88, v89, v41
	v_max3_f32 v40, v40, s7, v41
	v_max_f32_e32 v41, v95, v95
	v_max_f32_e32 v42, v94, v94
	v_max_f32_e32 v41, v42, v41
	v_max_f32_e32 v42, v99, v99
	v_max_f32_e32 v43, v98, v98
	v_max_f32_e32 v42, v43, v42
	v_max3_f32 v41, v92, v93, v41
	v_max3_f32 v42, v96, v97, v42
	v_max3_f32 v40, v40, v41, v42
	v_max_f32_e32 v41, v103, v103
	v_max_f32_e32 v42, v102, v102
	v_max_f32_e32 v41, v42, v41
	v_max_f32_e32 v42, v107, v107
	v_max_f32_e32 v43, v106, v106
	v_max_f32_e32 v42, v43, v42
	v_max3_f32 v41, v100, v101, v41
	v_max3_f32 v42, v104, v105, v42
	v_max3_f32 v40, v40, v41, v42
	v_max_f32_e32 v41, v115, v115
	v_max_f32_e32 v42, v114, v114
	v_max_f32_e32 v41, v42, v41
	v_max_f32_e32 v42, v131, v131
	v_max_f32_e32 v43, v130, v130
	v_max_f32_e32 v42, v43, v42
	v_max3_f32 v41, v112, v113, v41
	v_max3_f32 v42, v128, v129, v42
	v_max3_f32 v40, v40, v41, v42
	v_max_f32_e32 v41, v135, v135
	v_max_f32_e32 v42, v134, v134
	v_max_f32_e32 v41, v42, v41
	v_max_f32_e32 v42, v139, v139
	v_max_f32_e32 v43, v138, v138
	v_max_f32_e32 v42, v43, v42
	v_max3_f32 v41, v132, v133, v41
	v_max3_f32 v42, v136, v137, v42
	v_max3_f32 v40, v40, v41, v42
	v_max_f32_e32 v41, v143, v143
	v_max_f32_e32 v42, v142, v142
	v_max_f32_e32 v41, v42, v41
	v_max_f32_e32 v42, v147, v147
	v_max_f32_e32 v43, v146, v146
	v_max_f32_e32 v42, v43, v42
	v_max3_f32 v41, v140, v141, v41
	v_max3_f32 v42, v144, v145, v42
	v_max3_f32 v40, v40, v41, v42
	v_max_f32_e32 v41, v151, v151
	v_max_f32_e32 v42, v150, v150
	v_max_f32_e32 v41, v42, v41
	v_max_f32_e32 v42, v155, v155
	v_max_f32_e32 v43, v154, v154
	v_max_f32_e32 v42, v43, v42
	v_max3_f32 v41, v148, v149, v41
	v_max3_f32 v42, v152, v153, v42
	v_max3_f32 v40, v40, v41, v42
	v_max_f32_e32 v41, v159, v159
	v_max_f32_e32 v42, v158, v158
	v_max_f32_e32 v41, v42, v41
	v_max_f32_e32 v42, v39, v39
	v_max_f32_e32 v43, v38, v38
	v_max_f32_e32 v42, v43, v42
	v_max3_f32 v41, v156, v157, v41
	v_max3_f32 v42, v36, v37, v42
	v_max3_f32 v40, v40, v41, v42
	ds_bpermute_b32 v41, v171, v40
	s_waitcnt lgkmcnt(0)
	s_barrier
	s_waitcnt lgkmcnt(0)
	v_max_f32_e32 v41, v41, v41
	v_max_f32_e32 v40, v40, v41
	ds_bpermute_b32 v41, v172, v40
	s_waitcnt lgkmcnt(0)
	v_max_f32_e32 v41, v41, v41
	v_max_f32_e32 v182, v40, v41
	v_sub_f32_e32 v40, v84, v182
	v_mul_f32_e32 v40, 0x3d800000, v40
	v_sub_f32_e32 v41, v85, v182
	v_mul_f32_e32 v40, 0x3fb8aa3b, v40
	v_mul_f32_e32 v41, 0x3d800000, v41
	v_exp_f32_e32 v40, v40
	v_mul_f32_e32 v41, 0x3fb8aa3b, v41
	v_exp_f32_e32 v41, v41
	v_sub_f32_e32 v85, v96, v182
	v_add_f32_e32 v42, 0, v40
	v_mul_f32_e32 v85, 0x3d800000, v85
	v_add_f32_e32 v43, v41, v42
	v_sub_f32_e32 v42, v86, v182
	v_mul_f32_e32 v42, 0x3d800000, v42
	v_mul_f32_e32 v42, 0x3fb8aa3b, v42
	v_exp_f32_e32 v42, v42
	v_mul_f32_e32 v85, 0x3fb8aa3b, v85
	v_sub_f32_e32 v36, v36, v182
	v_mul_f32_e32 v36, 0x3d800000, v36
	v_add_f32_e32 v76, v42, v43
	v_sub_f32_e32 v43, v87, v182
	v_mul_f32_e32 v43, 0x3d800000, v43
	v_mul_f32_e32 v43, 0x3fb8aa3b, v43
	v_exp_f32_e32 v43, v43
	v_mul_f32_e32 v36, 0x3fb8aa3b, v36
	v_exp_f32_e32 v195, v36
	v_sub_f32_e32 v37, v37, v182
	v_add_f32_e32 v77, v43, v76
	v_sub_f32_e32 v76, v88, v182
	v_mul_f32_e32 v76, 0x3d800000, v76
	v_mul_f32_e32 v76, 0x3fb8aa3b, v76
	v_exp_f32_e32 v76, v76
	v_exp_f32_e32 v88, v85
	v_sub_f32_e32 v85, v97, v182
	v_mul_f32_e32 v85, 0x3d800000, v85
	v_add_f32_e32 v78, v76, v77
	v_sub_f32_e32 v77, v89, v182
	v_mul_f32_e32 v77, 0x3d800000, v77
	v_mul_f32_e32 v77, 0x3fb8aa3b, v77
	v_exp_f32_e32 v77, v77
	v_mul_f32_e32 v85, 0x3fb8aa3b, v85
	v_exp_f32_e32 v89, v85
	v_sub_f32_e32 v85, v98, v182
	v_add_f32_e32 v79, v77, v78
	v_sub_f32_e32 v78, v90, v182
	v_mul_f32_e32 v78, 0x3d800000, v78
	v_mul_f32_e32 v78, 0x3fb8aa3b, v78
	v_mul_f32_e32 v85, 0x3d800000, v85
	v_exp_f32_e32 v78, v78
	v_mul_f32_e32 v85, 0x3fb8aa3b, v85
	v_exp_f32_e32 v90, v85
	v_sub_f32_e32 v85, v99, v182
	v_mul_f32_e32 v85, 0x3d800000, v85
	v_mul_f32_e32 v85, 0x3fb8aa3b, v85
	v_add_f32_e32 v80, v78, v79
	v_sub_f32_e32 v79, v91, v182
	v_exp_f32_e32 v91, v85
	v_sub_f32_e32 v85, v100, v182
	v_mul_f32_e32 v85, 0x3d800000, v85
	v_mul_f32_e32 v85, 0x3fb8aa3b, v85
	v_exp_f32_e32 v96, v85
	v_sub_f32_e32 v85, v101, v182
	v_mul_f32_e32 v85, 0x3d800000, v85
	v_mul_f32_e32 v85, 0x3fb8aa3b, v85
	v_exp_f32_e32 v97, v85
	v_sub_f32_e32 v85, v102, v182
	v_mul_f32_e32 v85, 0x3d800000, v85
	v_mul_f32_e32 v85, 0x3fb8aa3b, v85
	v_exp_f32_e32 v98, v85
	v_sub_f32_e32 v85, v103, v182
	v_mul_f32_e32 v85, 0x3d800000, v85
	v_mul_f32_e32 v85, 0x3fb8aa3b, v85
	v_exp_f32_e32 v99, v85
	v_sub_f32_e32 v85, v104, v182
	v_mul_f32_e32 v85, 0x3d800000, v85
	v_mul_f32_e32 v85, 0x3fb8aa3b, v85
	v_exp_f32_e32 v100, v85
	v_sub_f32_e32 v85, v105, v182
	v_mul_f32_e32 v85, 0x3d800000, v85
	v_mul_f32_e32 v85, 0x3fb8aa3b, v85
	v_exp_f32_e32 v101, v85
	v_sub_f32_e32 v85, v106, v182
	v_mul_f32_e32 v85, 0x3d800000, v85
	v_mul_f32_e32 v85, 0x3fb8aa3b, v85
	v_exp_f32_e32 v102, v85
	v_sub_f32_e32 v85, v107, v182
	v_mul_f32_e32 v85, 0x3d800000, v85
	v_mul_f32_e32 v85, 0x3fb8aa3b, v85
	v_exp_f32_e32 v103, v85
	v_sub_f32_e32 v85, v112, v182
	v_mul_f32_e32 v85, 0x3d800000, v85
	v_mul_f32_e32 v85, 0x3fb8aa3b, v85
	v_exp_f32_e32 v104, v85
	v_sub_f32_e32 v85, v113, v182
	v_mul_f32_e32 v85, 0x3d800000, v85
	v_mul_f32_e32 v85, 0x3fb8aa3b, v85
	v_exp_f32_e32 v105, v85
	v_sub_f32_e32 v85, v114, v182
	v_mul_f32_e32 v85, 0x3d800000, v85
	v_mul_f32_e32 v85, 0x3fb8aa3b, v85
	v_exp_f32_e32 v106, v85
	v_sub_f32_e32 v85, v115, v182
	v_mul_f32_e32 v85, 0x3d800000, v85
	v_mul_f32_e32 v85, 0x3fb8aa3b, v85
	v_exp_f32_e32 v107, v85
	v_sub_f32_e32 v85, v128, v182
	v_mul_f32_e32 v85, 0x3d800000, v85
	v_mul_f32_e32 v85, 0x3fb8aa3b, v85
	v_exp_f32_e32 v108, v85
	v_sub_f32_e32 v85, v129, v182
	v_mul_f32_e32 v85, 0x3d800000, v85
	v_mul_f32_e32 v85, 0x3fb8aa3b, v85
	v_exp_f32_e32 v109, v85
	v_sub_f32_e32 v85, v130, v182
	v_mul_f32_e32 v85, 0x3d800000, v85
	v_mul_f32_e32 v85, 0x3fb8aa3b, v85
	v_exp_f32_e32 v110, v85
	v_sub_f32_e32 v85, v131, v182
	v_mul_f32_e32 v85, 0x3d800000, v85
	v_mul_f32_e32 v85, 0x3fb8aa3b, v85
	v_exp_f32_e32 v111, v85
	v_sub_f32_e32 v85, v132, v182
	v_mul_f32_e32 v85, 0x3d800000, v85
	v_mul_f32_e32 v85, 0x3fb8aa3b, v85
	v_exp_f32_e32 v112, v85
	v_sub_f32_e32 v85, v133, v182
	v_mul_f32_e32 v85, 0x3d800000, v85
	v_mul_f32_e32 v85, 0x3fb8aa3b, v85
	v_mul_f32_e32 v79, 0x3d800000, v79
	v_exp_f32_e32 v113, v85
	v_sub_f32_e32 v85, v134, v182
	v_mul_f32_e32 v79, 0x3fb8aa3b, v79
	v_mul_f32_e32 v85, 0x3d800000, v85
	v_exp_f32_e32 v79, v79
	v_mul_f32_e32 v85, 0x3fb8aa3b, v85
	v_exp_f32_e32 v114, v85
	v_sub_f32_e32 v85, v135, v182
	v_mul_f32_e32 v85, 0x3d800000, v85
	v_mul_f32_e32 v85, 0x3fb8aa3b, v85
	v_add_f32_e32 v81, v79, v80
	v_sub_f32_e32 v80, v92, v182
	v_exp_f32_e32 v115, v85
	v_sub_f32_e32 v85, v136, v182
	v_mul_f32_e32 v80, 0x3d800000, v80
	v_mul_f32_e32 v85, 0x3d800000, v85
	v_mul_f32_e32 v80, 0x3fb8aa3b, v80
	v_mul_f32_e32 v85, 0x3fb8aa3b, v85
	v_exp_f32_e32 v80, v80
	v_exp_f32_e32 v116, v85
	v_sub_f32_e32 v85, v137, v182
	v_mul_f32_e32 v85, 0x3d800000, v85
	v_mul_f32_e32 v85, 0x3fb8aa3b, v85
	v_exp_f32_e32 v117, v85
	v_sub_f32_e32 v85, v138, v182
	v_add_f32_e32 v82, v80, v81
	v_sub_f32_e32 v81, v93, v182
	v_mul_f32_e32 v85, 0x3d800000, v85
	v_mul_f32_e32 v81, 0x3d800000, v81
	v_mul_f32_e32 v85, 0x3fb8aa3b, v85
	v_mul_f32_e32 v81, 0x3fb8aa3b, v81
	v_exp_f32_e32 v118, v85
	v_sub_f32_e32 v85, v139, v182
	v_exp_f32_e32 v81, v81
	v_mul_f32_e32 v85, 0x3d800000, v85
	v_mul_f32_e32 v85, 0x3fb8aa3b, v85
	v_exp_f32_e32 v119, v85
	v_sub_f32_e32 v85, v140, v182
	v_mul_f32_e32 v85, 0x3d800000, v85
	v_add_f32_e32 v83, v81, v82
	v_sub_f32_e32 v82, v94, v182
	v_mul_f32_e32 v85, 0x3fb8aa3b, v85
	v_mul_f32_e32 v82, 0x3d800000, v82
	v_exp_f32_e32 v120, v85
	v_sub_f32_e32 v85, v141, v182
	v_mul_f32_e32 v82, 0x3fb8aa3b, v82
	v_mul_f32_e32 v85, 0x3d800000, v85
	v_exp_f32_e32 v82, v82
	v_mul_f32_e32 v85, 0x3fb8aa3b, v85
	v_exp_f32_e32 v121, v85
	v_sub_f32_e32 v85, v142, v182
	v_mul_f32_e32 v85, 0x3d800000, v85
	v_mul_f32_e32 v85, 0x3fb8aa3b, v85
	v_add_f32_e32 v84, v82, v83
	v_sub_f32_e32 v83, v95, v182
	v_exp_f32_e32 v122, v85
	v_sub_f32_e32 v85, v143, v182
	v_mul_f32_e32 v83, 0x3d800000, v83
	v_mul_f32_e32 v85, 0x3d800000, v85
	v_mul_f32_e32 v83, 0x3fb8aa3b, v83
	v_mul_f32_e32 v85, 0x3fb8aa3b, v85
	v_exp_f32_e32 v83, v83
	v_exp_f32_e32 v123, v85
	v_sub_f32_e32 v85, v144, v182
	v_mul_f32_e32 v85, 0x3d800000, v85
	v_mul_f32_e32 v85, 0x3fb8aa3b, v85
	v_exp_f32_e32 v124, v85
	v_sub_f32_e32 v85, v145, v182
	v_add_f32_e32 v84, v83, v84
	v_mul_f32_e32 v85, 0x3d800000, v85
	v_add_f32_e32 v84, v88, v84
	v_mul_f32_e32 v85, 0x3fb8aa3b, v85
	v_add_f32_e32 v84, v89, v84
	v_exp_f32_e32 v125, v85
	v_sub_f32_e32 v85, v146, v182
	v_add_f32_e32 v84, v90, v84
	v_mul_f32_e32 v85, 0x3d800000, v85
	v_add_f32_e32 v84, v91, v84
	v_mul_f32_e32 v85, 0x3fb8aa3b, v85
	v_add_f32_e32 v84, v96, v84
	v_exp_f32_e32 v126, v85
	v_sub_f32_e32 v85, v147, v182
	v_add_f32_e32 v84, v97, v84
	v_mul_f32_e32 v85, 0x3d800000, v85
	v_add_f32_e32 v84, v98, v84
	v_mul_f32_e32 v85, 0x3fb8aa3b, v85
	v_add_f32_e32 v84, v99, v84
	v_exp_f32_e32 v127, v85
	v_sub_f32_e32 v85, v148, v182
	v_add_f32_e32 v84, v100, v84
	v_mul_f32_e32 v85, 0x3d800000, v85
	v_add_f32_e32 v84, v101, v84
	v_mul_f32_e32 v85, 0x3fb8aa3b, v85
	v_add_f32_e32 v84, v102, v84
	v_exp_f32_e32 v177, v85
	v_sub_f32_e32 v85, v149, v182
	v_add_f32_e32 v84, v103, v84
	v_mul_f32_e32 v85, 0x3d800000, v85
	v_add_f32_e32 v84, v104, v84
	v_mul_f32_e32 v85, 0x3fb8aa3b, v85
	v_add_f32_e32 v84, v105, v84
	v_exp_f32_e32 v178, v85
	v_sub_f32_e32 v85, v150, v182
	v_add_f32_e32 v84, v106, v84
	v_mul_f32_e32 v85, 0x3d800000, v85
	v_add_f32_e32 v84, v107, v84
	v_mul_f32_e32 v85, 0x3fb8aa3b, v85
	v_add_f32_e32 v84, v108, v84
	v_exp_f32_e32 v179, v85
	v_sub_f32_e32 v85, v151, v182
	v_add_f32_e32 v84, v109, v84
	v_mul_f32_e32 v85, 0x3d800000, v85
	v_add_f32_e32 v84, v110, v84
	v_mul_f32_e32 v85, 0x3fb8aa3b, v85
	v_add_f32_e32 v84, v111, v84
	v_exp_f32_e32 v180, v85
	v_sub_f32_e32 v85, v152, v182
	v_add_f32_e32 v84, v112, v84
	v_mul_f32_e32 v85, 0x3d800000, v85
	v_add_f32_e32 v84, v113, v84
	v_mul_f32_e32 v85, 0x3fb8aa3b, v85
	v_add_f32_e32 v84, v114, v84
	v_exp_f32_e32 v187, v85
	v_sub_f32_e32 v85, v153, v182
	v_add_f32_e32 v84, v115, v84
	v_mul_f32_e32 v85, 0x3d800000, v85
	v_add_f32_e32 v84, v116, v84
	v_mul_f32_e32 v85, 0x3fb8aa3b, v85
	v_add_f32_e32 v84, v117, v84
	v_exp_f32_e32 v190, v85
	v_sub_f32_e32 v85, v154, v182
	v_add_f32_e32 v84, v118, v84
	v_mul_f32_e32 v85, 0x3d800000, v85
	v_add_f32_e32 v84, v119, v84
	v_mul_f32_e32 v85, 0x3fb8aa3b, v85
	v_add_f32_e32 v84, v120, v84
	v_exp_f32_e32 v191, v85
	v_sub_f32_e32 v85, v155, v182
	v_add_f32_e32 v84, v121, v84
	v_mul_f32_e32 v85, 0x3d800000, v85
	v_add_f32_e32 v84, v122, v84
	v_mul_f32_e32 v85, 0x3fb8aa3b, v85
	v_add_f32_e32 v84, v123, v84
	v_exp_f32_e32 v192, v85
	v_sub_f32_e32 v85, v156, v182
	v_add_f32_e32 v84, v124, v84
	v_mul_f32_e32 v85, 0x3d800000, v85
	v_add_f32_e32 v84, v125, v84
	v_mul_f32_e32 v85, 0x3fb8aa3b, v85
	v_add_f32_e32 v84, v126, v84
	v_exp_f32_e32 v193, v85
	v_sub_f32_e32 v85, v157, v182
	v_add_f32_e32 v84, v127, v84
	v_mul_f32_e32 v85, 0x3d800000, v85
	v_add_f32_e32 v84, v177, v84
	v_mul_f32_e32 v85, 0x3fb8aa3b, v85
	v_add_f32_e32 v84, v178, v84
	v_exp_f32_e32 v194, v85
	v_sub_f32_e32 v85, v158, v182
	v_add_f32_e32 v84, v179, v84
	v_mul_f32_e32 v85, 0x3d800000, v85
	v_add_f32_e32 v84, v180, v84
	v_mul_f32_e32 v85, 0x3fb8aa3b, v85
	v_add_f32_e32 v84, v187, v84
	v_exp_f32_e32 v158, v85
	v_sub_f32_e32 v85, v159, v182
	v_add_f32_e32 v84, v190, v84
	v_mul_f32_e32 v85, 0x3d800000, v85
	v_add_f32_e32 v84, v191, v84
	v_mul_f32_e32 v85, 0x3fb8aa3b, v85
	v_add_f32_e32 v84, v192, v84
	v_exp_f32_e32 v159, v85
	v_add_f32_e32 v84, v193, v84
	v_add_f32_e32 v84, v194, v84
	v_add_f32_e32 v84, v158, v84
	v_cvt_pk_bf16_f32 v92, v80, v81
	v_cvt_pk_bf16_f32 v93, v82, v83
	v_cvt_pk_bf16_f32 v94, v88, v89
	v_cvt_pk_bf16_f32 v95, v90, v91
	v_cvt_pk_bf16_f32 v80, v96, v97
	v_cvt_pk_bf16_f32 v81, v98, v99
	v_cvt_pk_bf16_f32 v82, v100, v101
	ds_read_b64_tr_b16 v[88:89], v169
	ds_read_b64_tr_b16 v[96:97], v169 offset:32
	ds_read_b64_tr_b16 v[90:91], v169 offset:8448
	ds_read_b64_tr_b16 v[98:99], v169 offset:16896
	ds_read_b64_tr_b16 v[100:101], v169 offset:25344
	v_add_f32_e32 v84, v159, v84
	v_add_f32_e32 v36, v195, v84
	v_cvt_pk_bf16_f32 v84, v40, v41
	v_cvt_pk_bf16_f32 v85, v42, v43
	v_cvt_pk_bf16_f32 v86, v76, v77
	v_cvt_pk_bf16_f32 v87, v78, v79
	v_cvt_pk_bf16_f32 v83, v102, v103
	v_mul_f32_e32 v37, 0x3d800000, v37
	s_waitcnt lgkmcnt(2)
	v_mfma_f32_16x16x32_bf16 v[88:91], v[88:91], v[84:87], 0
	v_mul_f32_e32 v37, 0x3fb8aa3b, v37
	v_exp_f32_e32 v196, v37
	v_sub_f32_e32 v37, v38, v182
	s_waitcnt lgkmcnt(0)
	v_mfma_f32_16x16x32_bf16 v[152:155], v[98:101], v[92:95], v[88:91]
	ds_read_b64_tr_b16 v[98:99], v169 offset:8480
	s_nop 1
	ds_read_b64_tr_b16 v[88:89], v169 offset:16928
	ds_read_b64_tr_b16 v[90:91], v169 offset:25376
	v_mul_f32_e32 v37, 0x3d800000, v37
	v_mul_f32_e32 v37, 0x3fb8aa3b, v37
	s_waitcnt lgkmcnt(2)
	v_mfma_f32_16x16x32_bf16 v[96:99], v[96:99], v[84:87], 0
	v_cvt_pk_bf16_f32 v76, v104, v105
	v_cvt_pk_bf16_f32 v77, v106, v107
	v_exp_f32_e32 v197, v37
	s_waitcnt lgkmcnt(0)
	v_mfma_f32_16x16x32_bf16 v[88:91], v[88:91], v[92:95], v[96:99]
	s_nop 2
	ds_read_b64_tr_b16 v[96:97], v169 offset:64
	ds_read_b64_tr_b16 v[98:99], v169 offset:8512
	ds_read_b64_tr_b16 v[100:101], v169 offset:16960
	ds_read_b64_tr_b16 v[102:103], v169 offset:25408
	v_sub_f32_e32 v37, v39, v182
	v_mul_f32_e32 v37, 0x3d800000, v37
	s_waitcnt lgkmcnt(2)
	v_mfma_f32_16x16x32_bf16 v[96:99], v[96:99], v[84:87], 0
	v_mul_f32_e32 v37, 0x3fb8aa3b, v37
	v_exp_f32_e32 v198, v37
	v_add_f32_e32 v36, v196, v36
	s_waitcnt lgkmcnt(0)
	v_mfma_f32_16x16x32_bf16 v[128:131], v[100:103], v[92:95], v[96:99]
	s_nop 2
	ds_read_b64_tr_b16 v[96:97], v169 offset:96
	ds_read_b64_tr_b16 v[98:99], v169 offset:8544
	ds_read_b64_tr_b16 v[100:101], v169 offset:16992
	ds_read_b64_tr_b16 v[102:103], v169 offset:25440
	v_add_f32_e32 v36, v197, v36
	v_add_f32_e32 v36, v198, v36
	s_waitcnt lgkmcnt(2)
	v_mfma_f32_16x16x32_bf16 v[96:99], v[96:99], v[84:87], 0
	ds_bpermute_b32 v37, v171, v36
	v_cvt_pk_bf16_f32 v38, v124, v125
	v_cvt_pk_bf16_f32 v39, v126, v127
	s_waitcnt lgkmcnt(1)
	v_mfma_f32_16x16x32_bf16 v[104:107], v[100:103], v[92:95], v[96:99]
	s_nop 2
	ds_read_b64_tr_b16 v[96:97], v169 offset:128
	ds_read_b64_tr_b16 v[98:99], v169 offset:8576
	ds_read_b64_tr_b16 v[100:101], v169 offset:17024
	ds_read_b64_tr_b16 v[102:103], v169 offset:25472
	s_waitcnt lgkmcnt(4)
	v_add_f32_e32 v156, v36, v37
	v_cvt_pk_bf16_f32 v36, v120, v121
	s_waitcnt lgkmcnt(2)
	v_mfma_f32_16x16x32_bf16 v[96:99], v[96:99], v[84:87], 0
	v_cvt_pk_bf16_f32 v37, v122, v123
	v_cvt_pk_bf16_f32 v78, v108, v109
	v_cvt_pk_bf16_f32 v79, v110, v111
	s_waitcnt lgkmcnt(0)
	v_mfma_f32_16x16x32_bf16 v[148:151], v[100:103], v[92:95], v[96:99]
	s_nop 2
	ds_read_b64_tr_b16 v[96:97], v169 offset:160
	ds_read_b64_tr_b16 v[98:99], v169 offset:8608
	ds_read_b64_tr_b16 v[100:101], v169 offset:17056
	ds_read_b64_tr_b16 v[102:103], v169 offset:25504
	v_cvt_pk_bf16_f32 v40, v112, v113
	v_cvt_pk_bf16_f32 v41, v114, v115
	s_waitcnt lgkmcnt(2)
	v_mfma_f32_16x16x32_bf16 v[96:99], v[96:99], v[84:87], 0
	v_cvt_pk_bf16_f32 v42, v116, v117
	v_cvt_pk_bf16_f32 v43, v118, v119
	ds_bpermute_b32 v157, v172, v156
	s_waitcnt lgkmcnt(1)
	v_mfma_f32_16x16x32_bf16 v[120:123], v[100:103], v[92:95], v[96:99]
	s_nop 2
	ds_read_b64_tr_b16 v[96:97], v169 offset:192
	ds_read_b64_tr_b16 v[98:99], v169 offset:8640
	ds_read_b64_tr_b16 v[100:101], v169 offset:17088
	ds_read_b64_tr_b16 v[102:103], v169 offset:25536
	s_waitcnt lgkmcnt(2)
	v_mfma_f32_16x16x32_bf16 v[96:99], v[96:99], v[84:87], 0
	s_waitcnt lgkmcnt(0)
	v_mfma_f32_16x16x32_bf16 v[124:127], v[100:103], v[92:95], v[96:99]
	s_nop 5
	ds_read_b64_tr_b16 v[96:97], v169 offset:224
	ds_read_b64_tr_b16 v[98:99], v169 offset:8672
	ds_read_b64_tr_b16 v[100:101], v169 offset:17120
	ds_read_b64_tr_b16 v[102:103], v169 offset:25568
	s_waitcnt lgkmcnt(2)
	v_mfma_f32_16x16x32_bf16 v[96:99], v[96:99], v[84:87], 0
	s_waitcnt lgkmcnt(0)
	v_mfma_f32_16x16x32_bf16 v[108:111], v[100:103], v[92:95], v[96:99]
	s_nop 5
	ds_read_b64_tr_b16 v[96:97], v169 offset:256
	ds_read_b64_tr_b16 v[98:99], v169 offset:8704
	ds_read_b64_tr_b16 v[100:101], v169 offset:17152
	ds_read_b64_tr_b16 v[102:103], v169 offset:25600
	s_waitcnt lgkmcnt(2)
	v_mfma_f32_16x16x32_bf16 v[96:99], v[96:99], v[84:87], 0
	s_waitcnt lgkmcnt(0)
	v_mfma_f32_16x16x32_bf16 v[100:103], v[100:103], v[92:95], v[96:99]
	s_nop 5
	ds_read_b64_tr_b16 v[96:97], v169 offset:288
	ds_read_b64_tr_b16 v[98:99], v169 offset:8736
	ds_read_b64_tr_b16 v[112:113], v169 offset:17184
	ds_read_b64_tr_b16 v[114:115], v169 offset:25632
	s_waitcnt lgkmcnt(2)
	v_mfma_f32_16x16x32_bf16 v[96:99], v[96:99], v[84:87], 0
	s_waitcnt lgkmcnt(0)
	v_mfma_f32_16x16x32_bf16 v[112:115], v[112:115], v[92:95], v[96:99]
	s_nop 5
	ds_read_b64_tr_b16 v[96:97], v169 offset:320
	ds_read_b64_tr_b16 v[98:99], v169 offset:8768
	ds_read_b64_tr_b16 v[116:117], v169 offset:17216
	ds_read_b64_tr_b16 v[118:119], v169 offset:25664
	s_waitcnt lgkmcnt(2)
	v_mfma_f32_16x16x32_bf16 v[96:99], v[96:99], v[84:87], 0
	s_waitcnt lgkmcnt(0)
	v_mfma_f32_16x16x32_bf16 v[116:119], v[116:119], v[92:95], v[96:99]
	s_nop 5
	ds_read_b64_tr_b16 v[96:97], v169 offset:352
	ds_read_b64_tr_b16 v[98:99], v169 offset:8800
	ds_read_b64_tr_b16 v[132:133], v169 offset:17248
	ds_read_b64_tr_b16 v[134:135], v169 offset:25696
	s_waitcnt lgkmcnt(2)
	v_mfma_f32_16x16x32_bf16 v[96:99], v[96:99], v[84:87], 0
	s_waitcnt lgkmcnt(0)
	v_mfma_f32_16x16x32_bf16 v[132:135], v[132:135], v[92:95], v[96:99]
	s_nop 5
	ds_read_b64_tr_b16 v[96:97], v169 offset:384
	ds_read_b64_tr_b16 v[98:99], v169 offset:8832
	ds_read_b64_tr_b16 v[136:137], v169 offset:17280
	ds_read_b64_tr_b16 v[138:139], v169 offset:25728
	s_waitcnt lgkmcnt(2)
	v_mfma_f32_16x16x32_bf16 v[96:99], v[96:99], v[84:87], 0
	s_waitcnt lgkmcnt(0)
	v_mfma_f32_16x16x32_bf16 v[136:139], v[136:139], v[92:95], v[96:99]
	s_nop 5
	ds_read_b64_tr_b16 v[96:97], v169 offset:416
	ds_read_b64_tr_b16 v[98:99], v169 offset:8864
	ds_read_b64_tr_b16 v[140:141], v169 offset:17312
	ds_read_b64_tr_b16 v[142:143], v169 offset:25760
	s_waitcnt lgkmcnt(2)
	v_mfma_f32_16x16x32_bf16 v[96:99], v[96:99], v[84:87], 0
	s_waitcnt lgkmcnt(0)
	v_mfma_f32_16x16x32_bf16 v[140:143], v[140:143], v[92:95], v[96:99]
	s_nop 5
	ds_read_b64_tr_b16 v[96:97], v169 offset:448
	ds_read_b64_tr_b16 v[98:99], v169 offset:8896
	ds_read_b64_tr_b16 v[144:145], v169 offset:17344
	ds_read_b64_tr_b16 v[146:147], v169 offset:25792
	s_waitcnt lgkmcnt(2)
	v_mfma_f32_16x16x32_bf16 v[96:99], v[96:99], v[84:87], 0
	s_waitcnt lgkmcnt(0)
	v_mfma_f32_16x16x32_bf16 v[144:147], v[144:147], v[92:95], v[96:99]
	s_nop 5
	ds_read_b64_tr_b16 v[96:97], v169 offset:480
	ds_read_b64_tr_b16 v[98:99], v169 offset:8928
	ds_read_b64_tr_b16 v[200:201], v169 offset:17376
	ds_read_b64_tr_b16 v[202:203], v169 offset:25824
	s_waitcnt vmcnt(7)
	ds_write_b128 v168, v[44:47]
	s_waitcnt vmcnt(6)
	ds_write_b128 v168, v[48:51] offset:128
	s_waitcnt vmcnt(5)
	ds_write_b128 v168, v[52:55] offset:256
	s_waitcnt vmcnt(4)
	ds_write_b128 v168, v[56:59] offset:384
	global_load_dwordx4 v[44:47], v[160:161], off offset:2048
	global_load_dwordx4 v[48:51], v[160:161], off offset:2176
	global_load_dwordx4 v[52:55], v[160:161], off offset:2304
	global_load_dwordx4 v[56:59], v[160:161], off offset:2432
	s_waitcnt lgkmcnt(6)
	v_mfma_f32_16x16x32_bf16 v[84:87], v[96:99], v[84:87], 0
	s_waitcnt lgkmcnt(0)
	s_barrier
	s_waitcnt lgkmcnt(4)
	v_mfma_f32_16x16x32_bf16 v[96:99], v[200:203], v[92:95], v[84:87]
	s_nop 4
	ds_read_b64_tr_b16 v[204:205], v3
	ds_read_b64_tr_b16 v[206:207], v3 offset:8448
	ds_read_b64_tr_b16 v[208:209], v3 offset:32
	ds_read_b64_tr_b16 v[210:211], v3 offset:8480
	ds_read_b64_tr_b16 v[218:219], v3 offset:16928
	ds_read_b64_tr_b16 v[220:221], v3 offset:25376
	ds_read_b64_tr_b16 v[224:225], v3 offset:64
	ds_read_b64_tr_b16 v[226:227], v3 offset:8512
	ds_read_b64_tr_b16 v[228:229], v3 offset:16960
	ds_read_b64_tr_b16 v[230:231], v3 offset:25408
	ds_read_b64_tr_b16 v[232:233], v3 offset:96
	ds_read_b64_tr_b16 v[234:235], v3 offset:8544
	ds_read_b64_tr_b16 v[236:237], v3 offset:16992
	ds_read_b64_tr_b16 v[238:239], v3 offset:25440
	ds_read_b64_tr_b16 v[240:241], v3 offset:128
	ds_read_b64_tr_b16 v[242:243], v3 offset:8576
	s_waitcnt lgkmcnt(14)
	v_mfma_f32_16x16x32_bf16 v[84:87], v[204:207], v[80:83], v[152:155]
	ds_read_b64_tr_b16 v[204:205], v3 offset:17024
	ds_read_b64_tr_b16 v[206:207], v3 offset:25472
	s_nop 1
	s_waitcnt lgkmcnt(14)
	v_mfma_f32_16x16x32_bf16 v[88:91], v[208:211], v[80:83], v[88:91]
	ds_read_b64_tr_b16 v[208:209], v3 offset:160
	ds_read_b64_tr_b16 v[210:211], v3 offset:8608
	s_waitcnt lgkmcnt(14)
	v_mfma_f32_16x16x32_bf16 v[92:95], v[218:221], v[76:79], v[88:91]
	ds_read_b64_tr_b16 v[218:219], v3 offset:17056
	ds_read_b64_tr_b16 v[220:221], v3 offset:25504
	s_nop 5
	s_waitcnt lgkmcnt(14)
	v_mfma_f32_16x16x32_bf16 v[88:91], v[224:227], v[80:83], v[128:131]
	ds_read_b64_tr_b16 v[224:225], v3 offset:192
	ds_read_b64_tr_b16 v[226:227], v3 offset:8640
	s_waitcnt lgkmcnt(14)
	v_mfma_f32_16x16x32_bf16 v[88:91], v[228:231], v[76:79], v[88:91]
	ds_read_b64_tr_b16 v[228:229], v3 offset:17088
	ds_read_b64_tr_b16 v[230:231], v3 offset:25536
	s_nop 0
	s_waitcnt lgkmcnt(14)
	v_mfma_f32_16x16x32_bf16 v[104:107], v[232:235], v[80:83], v[104:107]
	ds_read_b64_tr_b16 v[232:233], v3 offset:224
	ds_read_b64_tr_b16 v[234:235], v3 offset:8672
	s_waitcnt lgkmcnt(14)
	v_mfma_f32_16x16x32_bf16 v[128:131], v[236:239], v[76:79], v[104:107]
	ds_read_b64_tr_b16 v[236:237], v3 offset:17120
	ds_read_b64_tr_b16 v[238:239], v3 offset:25568
	s_nop 5
	s_waitcnt lgkmcnt(14)
	v_mfma_f32_16x16x32_bf16 v[104:107], v[240:243], v[80:83], v[148:151]
	ds_read_b64_tr_b16 v[240:241], v3 offset:256
	ds_read_b64_tr_b16 v[242:243], v3 offset:8704
	s_waitcnt lgkmcnt(14)
	v_mfma_f32_16x16x32_bf16 v[104:107], v[204:207], v[76:79], v[104:107]
	ds_read_b64_tr_b16 v[204:205], v3 offset:17152
	ds_read_b64_tr_b16 v[206:207], v3 offset:25600
	s_nop 0
	s_waitcnt lgkmcnt(14)
	v_mfma_f32_16x16x32_bf16 v[120:123], v[208:211], v[80:83], v[120:123]
	ds_read_b64_tr_b16 v[208:209], v3 offset:288
	ds_read_b64_tr_b16 v[210:211], v3 offset:8736
	s_waitcnt lgkmcnt(14)
	v_mfma_f32_16x16x32_bf16 v[120:123], v[218:221], v[76:79], v[120:123]
	ds_read_b64_tr_b16 v[218:219], v3 offset:17184
	ds_read_b64_tr_b16 v[220:221], v3 offset:25632
	s_waitcnt lgkmcnt(14)
	v_mfma_f32_16x16x32_bf16 v[124:127], v[224:227], v[80:83], v[124:127]
	ds_read_b64_tr_b16 v[224:225], v3 offset:320
	ds_read_b64_tr_b16 v[226:227], v3 offset:8768
	s_waitcnt lgkmcnt(14)
	v_mfma_f32_16x16x32_bf16 v[124:127], v[228:231], v[76:79], v[124:127]
	ds_read_b64_tr_b16 v[228:229], v3 offset:17216
	ds_read_b64_tr_b16 v[230:231], v3 offset:25664
	s_waitcnt lgkmcnt(14)
	v_mfma_f32_16x16x32_bf16 v[108:111], v[232:235], v[80:83], v[108:111]
	ds_read_b64_tr_b16 v[232:233], v3 offset:352
	ds_read_b64_tr_b16 v[234:235], v3 offset:8800
	s_waitcnt lgkmcnt(14)
	v_mfma_f32_16x16x32_bf16 v[108:111], v[236:239], v[76:79], v[108:111]
	ds_read_b64_tr_b16 v[236:237], v3 offset:17248
	ds_read_b64_tr_b16 v[238:239], v3 offset:25696
	s_waitcnt lgkmcnt(14)
	v_mfma_f32_16x16x32_bf16 v[100:103], v[240:243], v[80:83], v[100:103]
	ds_read_b64_tr_b16 v[240:241], v3 offset:384
	ds_read_b64_tr_b16 v[242:243], v3 offset:8832
	s_waitcnt lgkmcnt(14)
	v_mfma_f32_16x16x32_bf16 v[100:103], v[204:207], v[76:79], v[100:103]
	ds_read_b64_tr_b16 v[204:205], v3 offset:17280
	ds_read_b64_tr_b16 v[206:207], v3 offset:25728
	s_waitcnt lgkmcnt(14)
	v_mfma_f32_16x16x32_bf16 v[112:115], v[208:211], v[80:83], v[112:115]
	ds_read_b64_tr_b16 v[208:209], v3 offset:416
	ds_read_b64_tr_b16 v[210:211], v3 offset:8864
	s_waitcnt lgkmcnt(14)
	v_mfma_f32_16x16x32_bf16 v[112:115], v[218:221], v[76:79], v[112:115]
	ds_read_b64_tr_b16 v[218:219], v3 offset:17312
	ds_read_b64_tr_b16 v[220:221], v3 offset:25760
	s_waitcnt lgkmcnt(14)
	v_mfma_f32_16x16x32_bf16 v[116:119], v[224:227], v[80:83], v[116:119]
	ds_read_b64_tr_b16 v[224:225], v3 offset:448
	ds_read_b64_tr_b16 v[226:227], v3 offset:8896
	s_waitcnt lgkmcnt(14)
	v_mfma_f32_16x16x32_bf16 v[116:119], v[228:231], v[76:79], v[116:119]
	ds_read_b64_tr_b16 v[228:229], v3 offset:17344
	ds_read_b64_tr_b16 v[230:231], v3 offset:25792
	s_waitcnt lgkmcnt(14)
	v_mfma_f32_16x16x32_bf16 v[132:135], v[232:235], v[80:83], v[132:135]
	ds_read_b64_tr_b16 v[232:233], v3 offset:16896
	ds_read_b64_tr_b16 v[234:235], v3 offset:25344
	s_waitcnt lgkmcnt(14)
	v_mfma_f32_16x16x32_bf16 v[132:135], v[236:239], v[76:79], v[132:135]
	s_waitcnt lgkmcnt(12)
	v_mfma_f32_16x16x32_bf16 v[136:139], v[240:243], v[80:83], v[136:139]
	s_waitcnt lgkmcnt(10)
	v_mfma_f32_16x16x32_bf16 v[136:139], v[204:207], v[76:79], v[136:139]
	s_waitcnt lgkmcnt(8)
	v_mfma_f32_16x16x32_bf16 v[140:143], v[208:211], v[80:83], v[140:143]
	s_waitcnt lgkmcnt(6)
	v_mfma_f32_16x16x32_bf16 v[140:143], v[218:221], v[76:79], v[140:143]
	s_waitcnt lgkmcnt(4)
	v_mfma_f32_16x16x32_bf16 v[144:147], v[224:227], v[80:83], v[144:147]
	s_waitcnt lgkmcnt(2)
	v_mfma_f32_16x16x32_bf16 v[144:147], v[228:231], v[76:79], v[144:147]
	ds_read_b64_tr_b16 v[152:153], v3 offset:480
	ds_read_b64_tr_b16 v[154:155], v3 offset:8928
	ds_read_b64_tr_b16 v[148:149], v3 offset:17376
	ds_read_b64_tr_b16 v[150:151], v3 offset:25824
	s_waitcnt vmcnt(7)
	ds_write_b128 v170, v[60:63]
	s_waitcnt vmcnt(6)
	ds_write_b128 v170, v[64:67] offset:128
	s_waitcnt vmcnt(5)
	ds_write_b128 v170, v[68:71] offset:256
	s_waitcnt vmcnt(4)
	ds_write_b128 v170, v[72:75] offset:384
	s_waitcnt lgkmcnt(0)
	s_waitcnt lgkmcnt(8)
	v_mfma_f32_16x16x32_bf16 v[84:87], v[232:235], v[76:79], v[84:87]
	s_nop 7
	s_barrier
	ds_read_b64_tr_b16 v[204:205], v169
	ds_read_b64_tr_b16 v[206:207], v169 offset:8448
	ds_read_b64_tr_b16 v[208:209], v169 offset:16896
	ds_read_b64_tr_b16 v[210:211], v169 offset:25344
	ds_read_b64_tr_b16 v[218:219], v169 offset:32
	ds_read_b64_tr_b16 v[220:221], v169 offset:8480
	ds_read_b64_tr_b16 v[224:225], v169 offset:16928
	ds_read_b64_tr_b16 v[226:227], v169 offset:25376
	ds_read_b64_tr_b16 v[228:229], v169 offset:64
	ds_read_b64_tr_b16 v[230:231], v169 offset:8512
	ds_read_b64_tr_b16 v[232:233], v169 offset:16960
	ds_read_b64_tr_b16 v[234:235], v169 offset:25408
	ds_read_b64_tr_b16 v[236:237], v169 offset:96
	ds_read_b64_tr_b16 v[238:239], v169 offset:8544
	ds_read_b64_tr_b16 v[240:241], v169 offset:16992
	ds_read_b64_tr_b16 v[242:243], v169 offset:25440
	s_waitcnt lgkmcnt(14)
	v_mfma_f32_16x16x32_bf16 v[60:63], v[204:207], v[40:43], v[84:87]
	ds_read_b64_tr_b16 v[204:205], v169 offset:128
	ds_read_b64_tr_b16 v[206:207], v169 offset:8576
	s_waitcnt lgkmcnt(14)
	v_mfma_f32_16x16x32_bf16 v[60:63], v[208:211], v[36:39], v[60:63]
	ds_read_b64_tr_b16 v[208:209], v169 offset:17024
	ds_read_b64_tr_b16 v[210:211], v169 offset:25472
	s_waitcnt lgkmcnt(14)
	v_mfma_f32_16x16x32_bf16 v[64:67], v[218:221], v[40:43], v[92:95]
	ds_read_b64_tr_b16 v[218:219], v169 offset:160
	ds_read_b64_tr_b16 v[220:221], v169 offset:8608
	s_waitcnt lgkmcnt(14)
	v_mfma_f32_16x16x32_bf16 v[64:67], v[224:227], v[36:39], v[64:67]
	ds_read_b64_tr_b16 v[224:225], v169 offset:17056
	ds_read_b64_tr_b16 v[226:227], v169 offset:25504
	v_mfma_f32_16x16x32_bf16 v[80:83], v[152:155], v[80:83], v[96:99]
	v_mov_b32_e32 v155, 0xa00000
	s_nop 1
	s_waitcnt lgkmcnt(14)
	v_mfma_f32_16x16x32_bf16 v[68:71], v[228:231], v[40:43], v[88:91]
	ds_read_b64_tr_b16 v[228:229], v169 offset:192
	ds_read_b64_tr_b16 v[230:231], v169 offset:8640
	v_mfma_f32_16x16x32_bf16 v[76:79], v[148:151], v[76:79], v[80:83]
	s_waitcnt lgkmcnt(14)
	v_mfma_f32_16x16x32_bf16 v[68:71], v[232:235], v[36:39], v[68:71]
	ds_read_b64_tr_b16 v[232:233], v169 offset:17088
	ds_read_b64_tr_b16 v[234:235], v169 offset:25536
	s_waitcnt lgkmcnt(14)
	v_mfma_f32_16x16x32_bf16 v[72:75], v[236:239], v[40:43], v[128:131]
	ds_read_b64_tr_b16 v[236:237], v169 offset:224
	ds_read_b64_tr_b16 v[238:239], v169 offset:8672
	s_waitcnt lgkmcnt(14)
	v_mfma_f32_16x16x32_bf16 v[128:131], v[240:243], v[36:39], v[72:75]
	ds_read_b64_tr_b16 v[240:241], v169 offset:17120
	ds_read_b64_tr_b16 v[242:243], v169 offset:25568
	s_nop 5
	s_waitcnt lgkmcnt(14)
	v_mfma_f32_16x16x32_bf16 v[72:75], v[204:207], v[40:43], v[104:107]
	ds_read_b64_tr_b16 v[204:205], v169 offset:256
	ds_read_b64_tr_b16 v[206:207], v169 offset:8704
	s_waitcnt lgkmcnt(14)
	v_mfma_f32_16x16x32_bf16 v[72:75], v[208:211], v[36:39], v[72:75]
	ds_read_b64_tr_b16 v[208:209], v169 offset:17152
	ds_read_b64_tr_b16 v[210:211], v169 offset:25600
	s_waitcnt lgkmcnt(14)
	v_mfma_f32_16x16x32_bf16 v[80:83], v[218:221], v[40:43], v[120:123]
	ds_read_b64_tr_b16 v[218:219], v169 offset:288
	ds_read_b64_tr_b16 v[220:221], v169 offset:8736
	s_waitcnt lgkmcnt(14)
	v_mfma_f32_16x16x32_bf16 v[80:83], v[224:227], v[36:39], v[80:83]
	ds_read_b64_tr_b16 v[224:225], v169 offset:17184
	ds_read_b64_tr_b16 v[226:227], v169 offset:25632
	s_waitcnt lgkmcnt(14)
	v_mfma_f32_16x16x32_bf16 v[84:87], v[228:231], v[40:43], v[124:127]
	ds_read_b64_tr_b16 v[228:229], v169 offset:320
	ds_read_b64_tr_b16 v[230:231], v169 offset:8768
	s_waitcnt lgkmcnt(14)
	v_mfma_f32_16x16x32_bf16 v[84:87], v[232:235], v[36:39], v[84:87]
	ds_read_b64_tr_b16 v[232:233], v169 offset:17216
	ds_read_b64_tr_b16 v[234:235], v169 offset:25664
	s_waitcnt lgkmcnt(14)
	v_mfma_f32_16x16x32_bf16 v[88:91], v[236:239], v[40:43], v[108:111]
	ds_read_b64_tr_b16 v[236:237], v169 offset:352
	ds_read_b64_tr_b16 v[238:239], v169 offset:8800
	s_waitcnt lgkmcnt(14)
	v_mfma_f32_16x16x32_bf16 v[120:123], v[240:243], v[36:39], v[88:91]
	ds_read_b64_tr_b16 v[240:241], v169 offset:17248
	ds_read_b64_tr_b16 v[242:243], v169 offset:25696
	s_nop 5
	s_waitcnt lgkmcnt(14)
	v_mfma_f32_16x16x32_bf16 v[88:91], v[204:207], v[40:43], v[100:103]
	ds_read_b64_tr_b16 v[204:205], v169 offset:384
	ds_read_b64_tr_b16 v[206:207], v169 offset:8832
	s_waitcnt lgkmcnt(14)
	v_mfma_f32_16x16x32_bf16 v[88:91], v[208:211], v[36:39], v[88:91]
	ds_read_b64_tr_b16 v[208:209], v169 offset:17280
	ds_read_b64_tr_b16 v[210:211], v169 offset:25728
	s_waitcnt lgkmcnt(14)
	v_mfma_f32_16x16x32_bf16 v[92:95], v[218:221], v[40:43], v[112:115]
	ds_read_b64_tr_b16 v[218:219], v169 offset:416
	ds_read_b64_tr_b16 v[220:221], v169 offset:8864
	s_waitcnt lgkmcnt(14)
	v_mfma_f32_16x16x32_bf16 v[92:95], v[224:227], v[36:39], v[92:95]
	ds_read_b64_tr_b16 v[224:225], v169 offset:17312
	ds_read_b64_tr_b16 v[226:227], v169 offset:25760
	s_waitcnt lgkmcnt(14)
	v_mfma_f32_16x16x32_bf16 v[96:99], v[228:231], v[40:43], v[116:119]
	ds_read_b64_tr_b16 v[228:229], v169 offset:448
	ds_read_b64_tr_b16 v[230:231], v169 offset:8896
	s_waitcnt lgkmcnt(14)
	v_mfma_f32_16x16x32_bf16 v[96:99], v[232:235], v[36:39], v[96:99]
	ds_read_b64_tr_b16 v[232:233], v169 offset:17344
	ds_read_b64_tr_b16 v[234:235], v169 offset:25792
	s_waitcnt lgkmcnt(14)
	v_mfma_f32_16x16x32_bf16 v[100:103], v[236:239], v[40:43], v[132:135]
	ds_read_b64_tr_b16 v[236:237], v169 offset:480
	ds_read_b64_tr_b16 v[238:239], v169 offset:8928
	s_waitcnt lgkmcnt(14)
	v_mfma_f32_16x16x32_bf16 v[112:115], v[240:243], v[36:39], v[100:103]
	s_nop 5
	s_waitcnt lgkmcnt(12)
	v_mfma_f32_16x16x32_bf16 v[100:103], v[204:207], v[40:43], v[136:139]
	s_waitcnt lgkmcnt(10)
	v_mfma_f32_16x16x32_bf16 v[100:103], v[208:211], v[36:39], v[100:103]
	v_add_u32_e32 v136, s14, v1
	v_add_f32_e32 v1, v156, v157
	s_nop 1
	s_waitcnt lgkmcnt(8)
	v_mfma_f32_16x16x32_bf16 v[104:107], v[218:221], v[40:43], v[140:143]
	v_ashrrev_i32_e32 v137, 31, v136
	s_nop 1
	s_waitcnt lgkmcnt(6)
	v_mfma_f32_16x16x32_bf16 v[104:107], v[224:227], v[36:39], v[104:107]
	s_waitcnt lgkmcnt(4)
	v_mfma_f32_16x16x32_bf16 v[108:111], v[228:231], v[40:43], v[144:147]
	s_waitcnt lgkmcnt(2)
	v_mfma_f32_16x16x32_bf16 v[108:111], v[232:235], v[36:39], v[108:111]
	ds_read_b64_tr_b16 v[124:125], v169 offset:17376
	ds_read_b64_tr_b16 v[126:127], v169 offset:25824
	s_waitcnt vmcnt(3)
	ds_write_b128 v168, v[44:47]
	s_waitcnt vmcnt(2)
	ds_write_b128 v168, v[48:51] offset:128
	s_waitcnt vmcnt(1)
	ds_write_b128 v168, v[52:55] offset:256
	s_waitcnt vmcnt(0)
	ds_write_b128 v168, v[56:59] offset:384
	s_waitcnt lgkmcnt(0)
	s_waitcnt lgkmcnt(6)
	v_mfma_f32_16x16x32_bf16 v[40:43], v[236:239], v[40:43], v[76:79]
	s_nop 7
	s_barrier
	v_cvt_pk_bf16_f32 v52, v177, v178
	s_waitcnt lgkmcnt(4)
	v_mfma_f32_16x16x32_bf16 v[36:39], v[124:127], v[36:39], v[40:43]
	s_nop 3
	ds_read_b64_tr_b16 v[204:205], v3
	ds_read_b64_tr_b16 v[206:207], v3 offset:8448
	ds_read_b64_tr_b16 v[208:209], v3 offset:16896
	ds_read_b64_tr_b16 v[210:211], v3 offset:25344
	ds_read_b64_tr_b16 v[218:219], v3 offset:32
	ds_read_b64_tr_b16 v[220:221], v3 offset:8480
	ds_read_b64_tr_b16 v[224:225], v3 offset:16928
	ds_read_b64_tr_b16 v[226:227], v3 offset:25376
	ds_read_b64_tr_b16 v[228:229], v3 offset:64
	ds_read_b64_tr_b16 v[230:231], v3 offset:8512
	ds_read_b64_tr_b16 v[232:233], v3 offset:16960
	ds_read_b64_tr_b16 v[234:235], v3 offset:25408
	ds_read_b64_tr_b16 v[236:237], v3 offset:96
	ds_read_b64_tr_b16 v[238:239], v3 offset:8544
	ds_read_b64_tr_b16 v[240:241], v3 offset:16992
	ds_read_b64_tr_b16 v[242:243], v3 offset:25440
	v_cvt_pk_bf16_f32 v53, v179, v180
	v_cvt_pk_bf16_f32 v54, v187, v190
	v_cvt_pk_bf16_f32 v55, v191, v192
	v_cvt_pk_bf16_f32 v48, v193, v194
	v_cvt_pk_bf16_f32 v49, v158, v159
	s_nop 1
	s_waitcnt lgkmcnt(14)
	v_mfma_f32_16x16x32_bf16 v[40:43], v[204:207], v[52:55], v[60:63]
	ds_read_b64_tr_b16 v[204:205], v3 offset:128
	ds_read_b64_tr_b16 v[206:207], v3 offset:8576
	v_cvt_pk_bf16_f32 v50, v195, v196
	v_cvt_pk_bf16_f32 v51, v197, v198
	s_nop 0
	s_waitcnt lgkmcnt(14)
	v_mfma_f32_16x16x32_bf16 v[44:47], v[208:211], v[48:51], v[40:43]
	ds_read_b64_tr_b16 v[208:209], v3 offset:17024
	ds_read_b64_tr_b16 v[210:211], v3 offset:25472
	s_nop 1
	s_waitcnt lgkmcnt(14)
	v_mfma_f32_16x16x32_bf16 v[56:59], v[218:221], v[52:55], v[64:67]
	ds_read_b64_tr_b16 v[218:219], v3 offset:160
	ds_read_b64_tr_b16 v[220:221], v3 offset:8608
	s_waitcnt lgkmcnt(14)
	v_mfma_f32_16x16x32_bf16 v[40:43], v[224:227], v[48:51], v[56:59]
	ds_read_b64_tr_b16 v[224:225], v3 offset:17056
	ds_read_b64_tr_b16 v[226:227], v3 offset:25504
	s_nop 5
	s_waitcnt lgkmcnt(14)
	v_mfma_f32_16x16x32_bf16 v[56:59], v[228:231], v[52:55], v[68:71]
	ds_read_b64_tr_b16 v[228:229], v3 offset:192
	ds_read_b64_tr_b16 v[230:231], v3 offset:8640
	s_waitcnt lgkmcnt(14)
	v_mfma_f32_16x16x32_bf16 v[56:59], v[232:235], v[48:51], v[56:59]
	ds_read_b64_tr_b16 v[232:233], v3 offset:17088
	ds_read_b64_tr_b16 v[234:235], v3 offset:25536
	s_waitcnt lgkmcnt(14)
	v_mfma_f32_16x16x32_bf16 v[60:63], v[236:239], v[52:55], v[128:131]
	ds_read_b64_tr_b16 v[236:237], v3 offset:224
	ds_read_b64_tr_b16 v[238:239], v3 offset:8672
	s_waitcnt lgkmcnt(14)
	v_mfma_f32_16x16x32_bf16 v[60:63], v[240:243], v[48:51], v[60:63]
	ds_read_b64_tr_b16 v[240:241], v3 offset:17120
	ds_read_b64_tr_b16 v[242:243], v3 offset:25568
	s_waitcnt lgkmcnt(14)
	v_mfma_f32_16x16x32_bf16 v[64:67], v[204:207], v[52:55], v[72:75]
	ds_read_b64_tr_b16 v[204:205], v3 offset:256
	ds_read_b64_tr_b16 v[206:207], v3 offset:8704
	s_waitcnt lgkmcnt(14)
	v_mfma_f32_16x16x32_bf16 v[64:67], v[208:211], v[48:51], v[64:67]
	ds_read_b64_tr_b16 v[208:209], v3 offset:17152
	ds_read_b64_tr_b16 v[210:211], v3 offset:25600
	s_waitcnt lgkmcnt(14)
	v_mfma_f32_16x16x32_bf16 v[68:71], v[218:221], v[52:55], v[80:83]
	ds_read_b64_tr_b16 v[218:219], v3 offset:288
	ds_read_b64_tr_b16 v[220:221], v3 offset:8736
	s_waitcnt lgkmcnt(14)
	v_mfma_f32_16x16x32_bf16 v[68:71], v[224:227], v[48:51], v[68:71]
	ds_read_b64_tr_b16 v[224:225], v3 offset:17184
	ds_read_b64_tr_b16 v[226:227], v3 offset:25632
	s_waitcnt lgkmcnt(14)
	v_mfma_f32_16x16x32_bf16 v[72:75], v[228:231], v[52:55], v[84:87]
	ds_read_b64_tr_b16 v[228:229], v3 offset:320
	ds_read_b64_tr_b16 v[230:231], v3 offset:8768
	s_waitcnt lgkmcnt(14)
	v_mfma_f32_16x16x32_bf16 v[72:75], v[232:235], v[48:51], v[72:75]
	ds_read_b64_tr_b16 v[232:233], v3 offset:17216
	ds_read_b64_tr_b16 v[234:235], v3 offset:25664
	s_waitcnt lgkmcnt(14)
	v_mfma_f32_16x16x32_bf16 v[76:79], v[236:239], v[52:55], v[120:123]
	ds_read_b64_tr_b16 v[236:237], v3 offset:352
	ds_read_b64_tr_b16 v[238:239], v3 offset:8800
	s_waitcnt lgkmcnt(14)
	v_mfma_f32_16x16x32_bf16 v[76:79], v[240:243], v[48:51], v[76:79]
	ds_read_b64_tr_b16 v[240:241], v3 offset:17248
	ds_read_b64_tr_b16 v[242:243], v3 offset:25696
	s_waitcnt lgkmcnt(14)
	v_mfma_f32_16x16x32_bf16 v[80:83], v[204:207], v[52:55], v[88:91]
	ds_read_b64_tr_b16 v[204:205], v3 offset:384
	ds_read_b64_tr_b16 v[206:207], v3 offset:8832
	s_waitcnt lgkmcnt(14)
	v_mfma_f32_16x16x32_bf16 v[80:83], v[208:211], v[48:51], v[80:83]
	ds_read_b64_tr_b16 v[208:209], v3 offset:17280
	ds_read_b64_tr_b16 v[210:211], v3 offset:25728
	s_waitcnt lgkmcnt(14)
	v_mfma_f32_16x16x32_bf16 v[84:87], v[218:221], v[52:55], v[92:95]
	ds_read_b64_tr_b16 v[218:219], v3 offset:416
	ds_read_b64_tr_b16 v[220:221], v3 offset:8864
	s_waitcnt lgkmcnt(14)
	v_mfma_f32_16x16x32_bf16 v[84:87], v[224:227], v[48:51], v[84:87]
	ds_read_b64_tr_b16 v[224:225], v3 offset:17312
	ds_read_b64_tr_b16 v[226:227], v3 offset:25760
	s_waitcnt lgkmcnt(14)
	v_mfma_f32_16x16x32_bf16 v[88:91], v[228:231], v[52:55], v[96:99]
	ds_read_b64_tr_b16 v[228:229], v3 offset:448
	ds_read_b64_tr_b16 v[230:231], v3 offset:8896
	s_waitcnt lgkmcnt(14)
	v_mfma_f32_16x16x32_bf16 v[88:91], v[232:235], v[48:51], v[88:91]
	ds_read_b64_tr_b16 v[232:233], v3 offset:17344
	ds_read_b64_tr_b16 v[234:235], v3 offset:25792
	s_waitcnt lgkmcnt(14)
	v_mfma_f32_16x16x32_bf16 v[92:95], v[236:239], v[52:55], v[112:115]
	ds_read_b64_tr_b16 v[236:237], v3 offset:480
	ds_read_b64_tr_b16 v[238:239], v3 offset:8928
	s_waitcnt lgkmcnt(14)
	v_mfma_f32_16x16x32_bf16 v[92:95], v[240:243], v[48:51], v[92:95]
	ds_read_b64_tr_b16 v[240:241], v3 offset:17376
	ds_read_b64_tr_b16 v[242:243], v3 offset:25824
	s_waitcnt lgkmcnt(14)
	v_mfma_f32_16x16x32_bf16 v[96:99], v[204:207], v[52:55], v[100:103]
	s_waitcnt lgkmcnt(12)
	v_mfma_f32_16x16x32_bf16 v[96:99], v[208:211], v[48:51], v[96:99]
	s_nop 0
	s_waitcnt lgkmcnt(10)
	v_mfma_f32_16x16x32_bf16 v[100:103], v[218:221], v[52:55], v[104:107]
	s_waitcnt lgkmcnt(8)
	v_mfma_f32_16x16x32_bf16 v[100:103], v[224:227], v[48:51], v[100:103]
	s_nop 0
	s_waitcnt lgkmcnt(6)
	v_mfma_f32_16x16x32_bf16 v[104:107], v[228:231], v[52:55], v[108:111]
	s_waitcnt lgkmcnt(4)
	v_mfma_f32_16x16x32_bf16 v[104:107], v[232:235], v[48:51], v[104:107]
	s_nop 0
	s_waitcnt lgkmcnt(2)
	v_mfma_f32_16x16x32_bf16 v[36:39], v[236:239], v[52:55], v[36:39]
	s_waitcnt lgkmcnt(0)
	v_mfma_f32_16x16x32_bf16 v[36:39], v[240:243], v[48:51], v[36:39]
	s_nop 7
	v_div_scale_f32 v48, s[12:13], v1, v1, 1.0
	v_rcp_f32_e32 v49, v48
	v_readlane_b32 s12, v253, 35
	v_readlane_b32 s13, v253, 36
	s_add_u32 s10, s12, s10
	v_fma_f32 v50, -v48, v49, 1.0
	v_fmac_f32_e32 v49, v50, v49
	v_div_scale_f32 v50, vcc, 1.0, v1, 1.0
	v_mul_f32_e32 v51, v50, v49
	v_fma_f32 v52, -v48, v51, v50
	v_fmac_f32_e32 v51, v52, v49
	v_fma_f32 v48, -v48, v51, v50
	v_div_fmas_f32 v48, v48, v49, v51
	s_addc_u32 s11, s13, s11
	v_lshlrev_b64 v[50:51], 11, v[136:137]
	v_lshl_add_u64 v[50:51], s[10:11], 0, v[50:51]
	v_div_fixup_f32 v48, v48, v1, 1.0
	v_mad_i64_i32 v[50:51], s[12:13], s6, v155, v[50:51]
	v_lshl_add_u64 v[50:51], v[50:51], 0, s[8:9]
	v_mov_b32_e32 v1, v181
	v_pk_mul_f32 v[40:41], v[48:49], v[40:41] op_sel_hi:[0,1]
	v_pk_mul_f32 v[42:43], v[48:49], v[42:43] op_sel_hi:[0,1]
	v_lshl_add_u64 v[50:51], v[50:51], 0, v[0:1]
	v_cvt_pk_bf16_f32 v40, v40, v41
	v_cvt_pk_bf16_f32 v41, v42, v43
	global_store_dwordx2 v[50:51], v[40:41], off offset:32
	v_pk_mul_f32 v[40:41], v[48:49], v[56:57] op_sel_hi:[0,1]
	v_pk_mul_f32 v[42:43], v[48:49], v[58:59] op_sel_hi:[0,1]
	v_cvt_pk_bf16_f32 v40, v40, v41
	v_cvt_pk_bf16_f32 v41, v42, v43
	global_store_dwordx2 v[50:51], v[40:41], off offset:64
	v_pk_mul_f32 v[40:41], v[48:49], v[60:61] op_sel_hi:[0,1]
	v_pk_mul_f32 v[42:43], v[48:49], v[62:63] op_sel_hi:[0,1]
	v_cvt_pk_bf16_f32 v40, v40, v41
	v_cvt_pk_bf16_f32 v41, v42, v43
	global_store_dwordx2 v[50:51], v[40:41], off offset:96
	v_pk_mul_f32 v[40:41], v[48:49], v[64:65] op_sel_hi:[0,1]
	v_pk_mul_f32 v[42:43], v[48:49], v[66:67] op_sel_hi:[0,1]
	v_cvt_pk_bf16_f32 v40, v40, v41
	v_cvt_pk_bf16_f32 v41, v42, v43
	global_store_dwordx2 v[50:51], v[40:41], off offset:128
	v_pk_mul_f32 v[40:41], v[48:49], v[68:69] op_sel_hi:[0,1]
	v_pk_mul_f32 v[42:43], v[48:49], v[70:71] op_sel_hi:[0,1]
	v_cvt_pk_bf16_f32 v40, v40, v41
	v_cvt_pk_bf16_f32 v41, v42, v43
	global_store_dwordx2 v[50:51], v[40:41], off offset:160
	v_pk_mul_f32 v[40:41], v[48:49], v[72:73] op_sel_hi:[0,1]
	v_pk_mul_f32 v[42:43], v[48:49], v[74:75] op_sel_hi:[0,1]
	v_cvt_pk_bf16_f32 v40, v40, v41
	v_cvt_pk_bf16_f32 v41, v42, v43
	global_store_dwordx2 v[50:51], v[40:41], off offset:192
	v_pk_mul_f32 v[40:41], v[48:49], v[76:77] op_sel_hi:[0,1]
	v_pk_mul_f32 v[42:43], v[48:49], v[78:79] op_sel_hi:[0,1]
	v_cvt_pk_bf16_f32 v40, v40, v41
	v_cvt_pk_bf16_f32 v41, v42, v43
	global_store_dwordx2 v[50:51], v[40:41], off offset:224
	v_pk_mul_f32 v[40:41], v[48:49], v[80:81] op_sel_hi:[0,1]
	v_pk_mul_f32 v[42:43], v[48:49], v[82:83] op_sel_hi:[0,1]
	v_cvt_pk_bf16_f32 v40, v40, v41
	v_cvt_pk_bf16_f32 v41, v42, v43
	global_store_dwordx2 v[50:51], v[40:41], off offset:256
	v_pk_mul_f32 v[40:41], v[48:49], v[84:85] op_sel_hi:[0,1]
	v_pk_mul_f32 v[42:43], v[48:49], v[86:87] op_sel_hi:[0,1]
	v_cvt_pk_bf16_f32 v40, v40, v41
	v_cvt_pk_bf16_f32 v41, v42, v43
	global_store_dwordx2 v[50:51], v[40:41], off offset:288
	v_pk_mul_f32 v[40:41], v[48:49], v[88:89] op_sel_hi:[0,1]
	v_pk_mul_f32 v[42:43], v[48:49], v[90:91] op_sel_hi:[0,1]
	v_cvt_pk_bf16_f32 v40, v40, v41
	v_cvt_pk_bf16_f32 v41, v42, v43
	global_store_dwordx2 v[50:51], v[40:41], off offset:320
	v_pk_mul_f32 v[40:41], v[48:49], v[92:93] op_sel_hi:[0,1]
	v_pk_mul_f32 v[42:43], v[48:49], v[94:95] op_sel_hi:[0,1]
	v_cvt_pk_bf16_f32 v40, v40, v41
	v_cvt_pk_bf16_f32 v41, v42, v43
	global_store_dwordx2 v[50:51], v[40:41], off offset:352
	v_pk_mul_f32 v[40:41], v[48:49], v[96:97] op_sel_hi:[0,1]
	v_pk_mul_f32 v[42:43], v[48:49], v[98:99] op_sel_hi:[0,1]
	v_cvt_pk_bf16_f32 v40, v40, v41
	v_cvt_pk_bf16_f32 v41, v42, v43
	global_store_dwordx2 v[50:51], v[40:41], off offset:384
	v_pk_mul_f32 v[40:41], v[48:49], v[100:101] op_sel_hi:[0,1]
	v_pk_mul_f32 v[42:43], v[48:49], v[102:103] op_sel_hi:[0,1]
	v_cvt_pk_bf16_f32 v40, v40, v41
	v_cvt_pk_bf16_f32 v41, v42, v43
	v_pk_mul_f32 v[44:45], v[48:49], v[44:45] op_sel_hi:[0,1]
	v_pk_mul_f32 v[46:47], v[48:49], v[46:47] op_sel_hi:[0,1]
	global_store_dwordx2 v[50:51], v[40:41], off offset:416
	v_pk_mul_f32 v[40:41], v[48:49], v[104:105] op_sel_hi:[0,1]
	v_pk_mul_f32 v[42:43], v[48:49], v[106:107] op_sel_hi:[0,1]
	v_pk_mul_f32 v[36:37], v[48:49], v[36:37] op_sel_hi:[0,1]
	v_pk_mul_f32 v[38:39], v[48:49], v[38:39] op_sel_hi:[0,1]
	v_cvt_pk_bf16_f32 v44, v44, v45
	v_cvt_pk_bf16_f32 v45, v46, v47
	v_cvt_pk_bf16_f32 v40, v40, v41
	v_cvt_pk_bf16_f32 v41, v42, v43
	v_cvt_pk_bf16_f32 v36, v36, v37
	v_cvt_pk_bf16_f32 v37, v38, v39
	global_store_dwordx2 v[50:51], v[44:45], off
	global_store_dwordx2 v[50:51], v[40:41], off offset:448
	global_store_dwordx2 v[50:51], v[36:37], off offset:480
	s_waitcnt lgkmcnt(0)
	s_barrier
	s_waitcnt lgkmcnt(0)
	s_barrier
	ds_write_b128 v176, v[4:7]
	ds_write_b128 v176, v[8:11] offset:256
	ds_write_b128 v176, v[12:15] offset:8448
	ds_write_b128 v176, v[16:19] offset:8704
	ds_write_b128 v176, v[20:23] offset:16896
	ds_write_b128 v176, v[24:27] offset:17152
	ds_write_b128 v176, v[28:31] offset:25344
	ds_write_b128 v176, v[32:35] offset:25600
	s_waitcnt lgkmcnt(0)
	s_barrier
	ds_read_b128 v[64:67], v175
	ds_read_b128 v[60:63], v175 offset:64
	ds_read_b128 v[56:59], v175 offset:128
	ds_read_b128 v[52:55], v175 offset:192
	ds_read_b128 v[48:51], v175 offset:256
	ds_read_b128 v[44:47], v175 offset:320
	ds_read_b128 v[8:11], v175 offset:384
	ds_read_b128 v[4:7], v175 offset:448
	global_load_dwordx4 v[28:31], v[166:167], off
	global_load_dwordx4 v[12:15], v[164:165], off
	global_load_dwordx4 v[32:35], v[166:167], off offset:128
	global_load_dwordx4 v[16:19], v[164:165], off offset:128
	global_load_dwordx4 v[36:39], v[166:167], off offset:256
	global_load_dwordx4 v[20:23], v[164:165], off offset:256
	global_load_dwordx4 v[40:43], v[166:167], off offset:384
	global_load_dwordx4 v[24:27], v[164:165], off offset:384
	s_waitcnt vmcnt(7)
	ds_write_b128 v170, v[28:31]
	s_waitcnt vmcnt(5)
	ds_write_b128 v170, v[32:35] offset:128
	s_waitcnt vmcnt(3)
	ds_write_b128 v170, v[36:39] offset:256
	s_waitcnt vmcnt(1)
	ds_write_b128 v170, v[40:43] offset:384
	global_load_dwordx4 v[28:31], v[162:163], off
	global_load_dwordx4 v[32:35], v[162:163], off offset:128
	global_load_dwordx4 v[36:39], v[162:163], off offset:256
	global_load_dwordx4 v[40:43], v[162:163], off offset:384
	s_waitcnt lgkmcnt(0)
	s_barrier
	ds_read_b128 v[204:207], v174
	ds_read_b128 v[208:211], v174 offset:8448
	ds_read_b128 v[218:221], v174 offset:16896
	ds_read_b128 v[224:227], v174 offset:25344
	ds_read_b128 v[228:231], v174 offset:64
	ds_read_b128 v[232:235], v174 offset:8512
	ds_read_b128 v[236:239], v174 offset:16960
	ds_read_b128 v[240:243], v174 offset:25408
	s_waitcnt lgkmcnt(7)
	v_mfma_f32_16x16x32_bf16 v[68:71], v[204:207], v[64:67], 0
	ds_read_b128 v[204:207], v174 offset:128
	s_waitcnt lgkmcnt(7)
	v_mfma_f32_16x16x32_bf16 v[72:75], v[208:211], v[64:67], 0
	ds_read_b128 v[208:211], v174 offset:8576
	s_waitcnt lgkmcnt(7)
	v_mfma_f32_16x16x32_bf16 v[76:79], v[218:221], v[64:67], 0
	ds_read_b128 v[218:221], v174 offset:17024
	s_waitcnt lgkmcnt(7)
	v_mfma_f32_16x16x32_bf16 v[80:83], v[224:227], v[64:67], 0
	ds_read_b128 v[224:227], v174 offset:25472
	s_waitcnt lgkmcnt(7)
	v_mfma_f32_16x16x32_bf16 v[68:71], v[228:231], v[60:63], v[68:71]
	ds_read_b128 v[228:231], v174 offset:192
	s_waitcnt lgkmcnt(7)
	v_mfma_f32_16x16x32_bf16 v[72:75], v[232:235], v[60:63], v[72:75]
	ds_read_b128 v[232:235], v174 offset:8640
	s_waitcnt lgkmcnt(7)
	v_mfma_f32_16x16x32_bf16 v[76:79], v[236:239], v[60:63], v[76:79]
	ds_read_b128 v[236:239], v174 offset:17088
	s_waitcnt lgkmcnt(7)
	v_mfma_f32_16x16x32_bf16 v[80:83], v[240:243], v[60:63], v[80:83]
	ds_read_b128 v[240:243], v174 offset:25536
	s_waitcnt lgkmcnt(7)
	v_mfma_f32_16x16x32_bf16 v[68:71], v[204:207], v[56:59], v[68:71]
	ds_read_b128 v[204:207], v174 offset:256
	s_waitcnt lgkmcnt(7)
	v_mfma_f32_16x16x32_bf16 v[72:75], v[208:211], v[56:59], v[72:75]
	ds_read_b128 v[208:211], v174 offset:8704
	s_waitcnt lgkmcnt(7)
	v_mfma_f32_16x16x32_bf16 v[76:79], v[218:221], v[56:59], v[76:79]
	ds_read_b128 v[218:221], v174 offset:17152
	s_waitcnt lgkmcnt(7)
	v_mfma_f32_16x16x32_bf16 v[80:83], v[224:227], v[56:59], v[80:83]
	ds_read_b128 v[224:227], v174 offset:25600
	s_waitcnt lgkmcnt(7)
	v_mfma_f32_16x16x32_bf16 v[68:71], v[228:231], v[52:55], v[68:71]
	ds_read_b128 v[228:231], v174 offset:320
	s_waitcnt lgkmcnt(7)
	v_mfma_f32_16x16x32_bf16 v[72:75], v[232:235], v[52:55], v[72:75]
	ds_read_b128 v[232:235], v174 offset:8768
	s_waitcnt lgkmcnt(7)
	v_mfma_f32_16x16x32_bf16 v[76:79], v[236:239], v[52:55], v[76:79]
	ds_read_b128 v[236:239], v174 offset:17216
	s_waitcnt lgkmcnt(7)
	v_mfma_f32_16x16x32_bf16 v[80:83], v[240:243], v[52:55], v[80:83]
	ds_read_b128 v[240:243], v174 offset:25664
	s_waitcnt lgkmcnt(7)
	v_mfma_f32_16x16x32_bf16 v[68:71], v[204:207], v[48:51], v[68:71]
	ds_read_b128 v[204:207], v174 offset:384
	s_waitcnt lgkmcnt(7)
	v_mfma_f32_16x16x32_bf16 v[72:75], v[208:211], v[48:51], v[72:75]
	ds_read_b128 v[208:211], v174 offset:8832
	s_waitcnt lgkmcnt(7)
	v_mfma_f32_16x16x32_bf16 v[76:79], v[218:221], v[48:51], v[76:79]
	ds_read_b128 v[218:221], v174 offset:17280
	s_waitcnt lgkmcnt(7)
	v_mfma_f32_16x16x32_bf16 v[80:83], v[224:227], v[48:51], v[80:83]
	ds_read_b128 v[224:227], v174 offset:25728
	s_waitcnt lgkmcnt(7)
	v_mfma_f32_16x16x32_bf16 v[68:71], v[228:231], v[44:47], v[68:71]
	ds_read_b128 v[228:231], v174 offset:448
	s_waitcnt lgkmcnt(7)
	v_mfma_f32_16x16x32_bf16 v[72:75], v[232:235], v[44:47], v[72:75]
	ds_read_b128 v[232:235], v174 offset:8896
	s_waitcnt lgkmcnt(7)
	v_mfma_f32_16x16x32_bf16 v[76:79], v[236:239], v[44:47], v[76:79]
	ds_read_b128 v[236:239], v174 offset:17344
	s_waitcnt lgkmcnt(7)
	v_mfma_f32_16x16x32_bf16 v[80:83], v[240:243], v[44:47], v[80:83]
	s_waitcnt lgkmcnt(6)
	v_mfma_f32_16x16x32_bf16 v[68:71], v[204:207], v[8:11], v[68:71]
	s_waitcnt lgkmcnt(5)
	v_mfma_f32_16x16x32_bf16 v[72:75], v[208:211], v[8:11], v[72:75]
	s_waitcnt lgkmcnt(4)
	v_mfma_f32_16x16x32_bf16 v[76:79], v[218:221], v[8:11], v[76:79]
	s_waitcnt lgkmcnt(3)
	v_mfma_f32_16x16x32_bf16 v[80:83], v[224:227], v[8:11], v[80:83]
	s_waitcnt lgkmcnt(2)
	v_mfma_f32_16x16x32_bf16 v[68:71], v[228:231], v[4:7], v[68:71]
	s_waitcnt lgkmcnt(1)
	v_mfma_f32_16x16x32_bf16 v[72:75], v[232:235], v[4:7], v[72:75]
	s_waitcnt lgkmcnt(0)
	v_mfma_f32_16x16x32_bf16 v[76:79], v[236:239], v[4:7], v[76:79]
	s_nop 7
	ds_read_b128 v[84:87], v174 offset:25792
	ds_write_b128 v168, v[12:15]
	ds_write_b128 v168, v[16:19] offset:128
	ds_write_b128 v168, v[20:23] offset:256
	s_waitcnt vmcnt(4)
	ds_write_b128 v168, v[24:27] offset:384
	global_load_dwordx4 v[12:15], v[160:161], off
	global_load_dwordx4 v[16:19], v[160:161], off offset:128
	global_load_dwordx4 v[20:23], v[160:161], off offset:256
	global_load_dwordx4 v[24:27], v[160:161], off offset:384
	s_waitcnt lgkmcnt(0)
	s_barrier
	s_waitcnt lgkmcnt(4)
	v_mfma_f32_16x16x32_bf16 v[80:83], v[84:87], v[4:7], v[80:83]
	ds_read_b128 v[204:207], v173
	ds_read_b128 v[208:211], v173 offset:8448
	ds_read_b128 v[218:221], v173 offset:16896
	ds_read_b128 v[224:227], v173 offset:25344
	ds_read_b128 v[228:231], v173 offset:64
	ds_read_b128 v[232:235], v173 offset:8512
	ds_read_b128 v[236:239], v173 offset:16960
	ds_read_b128 v[240:243], v173 offset:25408
	s_waitcnt lgkmcnt(7)
	v_mfma_f32_16x16x32_bf16 v[84:87], v[204:207], v[64:67], 0
	ds_read_b128 v[204:207], v173 offset:128
	s_waitcnt lgkmcnt(7)
	v_mfma_f32_16x16x32_bf16 v[88:91], v[208:211], v[64:67], 0
	ds_read_b128 v[208:211], v173 offset:8576
	s_waitcnt lgkmcnt(7)
	v_mfma_f32_16x16x32_bf16 v[92:95], v[218:221], v[64:67], 0
	ds_read_b128 v[218:221], v173 offset:17024
	s_waitcnt lgkmcnt(7)
	v_mfma_f32_16x16x32_bf16 v[96:99], v[224:227], v[64:67], 0
	ds_read_b128 v[224:227], v173 offset:25472
	s_waitcnt lgkmcnt(7)
	v_mfma_f32_16x16x32_bf16 v[84:87], v[228:231], v[60:63], v[84:87]
	ds_read_b128 v[228:231], v173 offset:192
	s_waitcnt lgkmcnt(7)
	v_mfma_f32_16x16x32_bf16 v[88:91], v[232:235], v[60:63], v[88:91]
	ds_read_b128 v[232:235], v173 offset:8640
	s_waitcnt lgkmcnt(7)
	v_mfma_f32_16x16x32_bf16 v[92:95], v[236:239], v[60:63], v[92:95]
	ds_read_b128 v[236:239], v173 offset:17088
	s_waitcnt lgkmcnt(7)
	v_mfma_f32_16x16x32_bf16 v[96:99], v[240:243], v[60:63], v[96:99]
	ds_read_b128 v[240:243], v173 offset:25536
	s_waitcnt lgkmcnt(7)
	v_mfma_f32_16x16x32_bf16 v[84:87], v[204:207], v[56:59], v[84:87]
	ds_read_b128 v[204:207], v173 offset:256
	s_waitcnt lgkmcnt(7)
	v_mfma_f32_16x16x32_bf16 v[88:91], v[208:211], v[56:59], v[88:91]
	ds_read_b128 v[208:211], v173 offset:8704
	s_waitcnt lgkmcnt(7)
	v_mfma_f32_16x16x32_bf16 v[92:95], v[218:221], v[56:59], v[92:95]
	ds_read_b128 v[218:221], v173 offset:17152
	s_waitcnt lgkmcnt(7)
	v_mfma_f32_16x16x32_bf16 v[96:99], v[224:227], v[56:59], v[96:99]
	ds_read_b128 v[224:227], v173 offset:25600
	s_waitcnt lgkmcnt(7)
	v_mfma_f32_16x16x32_bf16 v[84:87], v[228:231], v[52:55], v[84:87]
	ds_read_b128 v[228:231], v173 offset:320
	s_waitcnt lgkmcnt(7)
	v_mfma_f32_16x16x32_bf16 v[88:91], v[232:235], v[52:55], v[88:91]
	ds_read_b128 v[232:235], v173 offset:8768
	s_waitcnt lgkmcnt(7)
	v_mfma_f32_16x16x32_bf16 v[92:95], v[236:239], v[52:55], v[92:95]
	ds_read_b128 v[236:239], v173 offset:17216
	s_waitcnt lgkmcnt(7)
	v_mfma_f32_16x16x32_bf16 v[96:99], v[240:243], v[52:55], v[96:99]
	ds_read_b128 v[240:243], v173 offset:25664
	s_waitcnt lgkmcnt(7)
	v_mfma_f32_16x16x32_bf16 v[84:87], v[204:207], v[48:51], v[84:87]
	ds_read_b128 v[204:207], v173 offset:384
	s_waitcnt lgkmcnt(7)
	v_mfma_f32_16x16x32_bf16 v[88:91], v[208:211], v[48:51], v[88:91]
	ds_read_b128 v[208:211], v173 offset:8832
	s_waitcnt lgkmcnt(7)
	v_mfma_f32_16x16x32_bf16 v[92:95], v[218:221], v[48:51], v[92:95]
	ds_read_b128 v[218:221], v173 offset:17280
	s_waitcnt lgkmcnt(7)
	v_mfma_f32_16x16x32_bf16 v[96:99], v[224:227], v[48:51], v[96:99]
	ds_read_b128 v[224:227], v173 offset:25728
	s_waitcnt lgkmcnt(7)
	v_mfma_f32_16x16x32_bf16 v[84:87], v[228:231], v[44:47], v[84:87]
	ds_read_b128 v[228:231], v173 offset:448
	s_waitcnt lgkmcnt(7)
	v_mfma_f32_16x16x32_bf16 v[88:91], v[232:235], v[44:47], v[88:91]
	ds_read_b128 v[232:235], v173 offset:8896
	s_waitcnt lgkmcnt(7)
	v_mfma_f32_16x16x32_bf16 v[92:95], v[236:239], v[44:47], v[92:95]
	ds_read_b128 v[236:239], v173 offset:17344
	s_waitcnt lgkmcnt(7)
	v_mfma_f32_16x16x32_bf16 v[96:99], v[240:243], v[44:47], v[96:99]
	s_waitcnt lgkmcnt(6)
	v_mfma_f32_16x16x32_bf16 v[84:87], v[204:207], v[8:11], v[84:87]
	s_waitcnt lgkmcnt(5)
	v_mfma_f32_16x16x32_bf16 v[88:91], v[208:211], v[8:11], v[88:91]
	s_waitcnt lgkmcnt(4)
	v_mfma_f32_16x16x32_bf16 v[92:95], v[218:221], v[8:11], v[92:95]
	s_waitcnt lgkmcnt(3)
	v_mfma_f32_16x16x32_bf16 v[96:99], v[224:227], v[8:11], v[96:99]
	s_waitcnt lgkmcnt(2)
	v_mfma_f32_16x16x32_bf16 v[84:87], v[228:231], v[4:7], v[84:87]
	s_waitcnt lgkmcnt(1)
	v_mfma_f32_16x16x32_bf16 v[88:91], v[232:235], v[4:7], v[88:91]
	s_waitcnt lgkmcnt(0)
	v_mfma_f32_16x16x32_bf16 v[92:95], v[236:239], v[4:7], v[92:95]
	s_nop 7
	ds_read_b128 v[100:103], v173 offset:25792
	s_waitcnt vmcnt(7)
	ds_write_b128 v170, v[28:31]
	s_waitcnt vmcnt(6)
	ds_write_b128 v170, v[32:35] offset:128
	s_waitcnt vmcnt(5)
	ds_write_b128 v170, v[36:39] offset:256
	s_waitcnt vmcnt(4)
	ds_write_b128 v170, v[40:43] offset:384
	global_load_dwordx4 v[28:31], v[166:167], off offset:2048
	global_load_dwordx4 v[32:35], v[166:167], off offset:2176
	global_load_dwordx4 v[36:39], v[166:167], off offset:2304
	global_load_dwordx4 v[40:43], v[166:167], off offset:2432
	s_waitcnt lgkmcnt(0)
	s_barrier
	s_waitcnt lgkmcnt(4)
	v_mfma_f32_16x16x32_bf16 v[96:99], v[100:103], v[4:7], v[96:99]
	ds_read_b128 v[204:207], v174
	ds_read_b128 v[208:211], v174 offset:8448
	ds_read_b128 v[218:221], v174 offset:16896
	ds_read_b128 v[224:227], v174 offset:25344
	ds_read_b128 v[228:231], v174 offset:64
	ds_read_b128 v[232:235], v174 offset:8512
	ds_read_b128 v[236:239], v174 offset:16960
	ds_read_b128 v[240:243], v174 offset:25408
	s_waitcnt lgkmcnt(7)
	v_mfma_f32_16x16x32_bf16 v[100:103], v[204:207], v[64:67], 0
	ds_read_b128 v[204:207], v174 offset:128
	s_waitcnt lgkmcnt(7)
	v_mfma_f32_16x16x32_bf16 v[104:107], v[208:211], v[64:67], 0
	ds_read_b128 v[208:211], v174 offset:8576
	s_waitcnt lgkmcnt(7)
	v_mfma_f32_16x16x32_bf16 v[108:111], v[218:221], v[64:67], 0
	ds_read_b128 v[218:221], v174 offset:17024
	s_waitcnt lgkmcnt(7)
	v_mfma_f32_16x16x32_bf16 v[112:115], v[224:227], v[64:67], 0
	ds_read_b128 v[224:227], v174 offset:25472
	s_waitcnt lgkmcnt(7)
	v_mfma_f32_16x16x32_bf16 v[100:103], v[228:231], v[60:63], v[100:103]
	ds_read_b128 v[228:231], v174 offset:192
	s_waitcnt lgkmcnt(7)
	v_mfma_f32_16x16x32_bf16 v[104:107], v[232:235], v[60:63], v[104:107]
	ds_read_b128 v[232:235], v174 offset:8640
	s_waitcnt lgkmcnt(7)
	v_mfma_f32_16x16x32_bf16 v[108:111], v[236:239], v[60:63], v[108:111]
	ds_read_b128 v[236:239], v174 offset:17088
	s_waitcnt lgkmcnt(7)
	v_mfma_f32_16x16x32_bf16 v[112:115], v[240:243], v[60:63], v[112:115]
	ds_read_b128 v[240:243], v174 offset:25536
	s_waitcnt lgkmcnt(7)
	v_mfma_f32_16x16x32_bf16 v[100:103], v[204:207], v[56:59], v[100:103]
	ds_read_b128 v[204:207], v174 offset:256
	s_waitcnt lgkmcnt(7)
	v_mfma_f32_16x16x32_bf16 v[104:107], v[208:211], v[56:59], v[104:107]
	ds_read_b128 v[208:211], v174 offset:8704
	s_waitcnt lgkmcnt(7)
	v_mfma_f32_16x16x32_bf16 v[108:111], v[218:221], v[56:59], v[108:111]
	ds_read_b128 v[218:221], v174 offset:17152
	s_waitcnt lgkmcnt(7)
	v_mfma_f32_16x16x32_bf16 v[112:115], v[224:227], v[56:59], v[112:115]
	ds_read_b128 v[224:227], v174 offset:25600
	s_waitcnt lgkmcnt(7)
	v_mfma_f32_16x16x32_bf16 v[100:103], v[228:231], v[52:55], v[100:103]
	ds_read_b128 v[228:231], v174 offset:320
	s_waitcnt lgkmcnt(7)
	v_mfma_f32_16x16x32_bf16 v[104:107], v[232:235], v[52:55], v[104:107]
	ds_read_b128 v[232:235], v174 offset:8768
	s_waitcnt lgkmcnt(7)
	v_mfma_f32_16x16x32_bf16 v[108:111], v[236:239], v[52:55], v[108:111]
	ds_read_b128 v[236:239], v174 offset:17216
	s_waitcnt lgkmcnt(7)
	v_mfma_f32_16x16x32_bf16 v[112:115], v[240:243], v[52:55], v[112:115]
	ds_read_b128 v[240:243], v174 offset:25664
	s_waitcnt lgkmcnt(7)
	v_mfma_f32_16x16x32_bf16 v[100:103], v[204:207], v[48:51], v[100:103]
	ds_read_b128 v[204:207], v174 offset:384
	s_waitcnt lgkmcnt(7)
	v_mfma_f32_16x16x32_bf16 v[104:107], v[208:211], v[48:51], v[104:107]
	ds_read_b128 v[208:211], v174 offset:8832
	s_waitcnt lgkmcnt(7)
	v_mfma_f32_16x16x32_bf16 v[108:111], v[218:221], v[48:51], v[108:111]
	ds_read_b128 v[218:221], v174 offset:17280
	s_waitcnt lgkmcnt(7)
	v_mfma_f32_16x16x32_bf16 v[112:115], v[224:227], v[48:51], v[112:115]
	ds_read_b128 v[224:227], v174 offset:25728
	s_waitcnt lgkmcnt(7)
	v_mfma_f32_16x16x32_bf16 v[100:103], v[228:231], v[44:47], v[100:103]
	ds_read_b128 v[228:231], v174 offset:448
	s_waitcnt lgkmcnt(7)
	v_mfma_f32_16x16x32_bf16 v[104:107], v[232:235], v[44:47], v[104:107]
	ds_read_b128 v[232:235], v174 offset:8896
	s_waitcnt lgkmcnt(7)
	v_mfma_f32_16x16x32_bf16 v[108:111], v[236:239], v[44:47], v[108:111]
	ds_read_b128 v[236:239], v174 offset:17344
	s_waitcnt lgkmcnt(7)
	v_mfma_f32_16x16x32_bf16 v[112:115], v[240:243], v[44:47], v[112:115]
	s_waitcnt lgkmcnt(6)
	v_mfma_f32_16x16x32_bf16 v[100:103], v[204:207], v[8:11], v[100:103]
	s_waitcnt lgkmcnt(5)
	v_mfma_f32_16x16x32_bf16 v[104:107], v[208:211], v[8:11], v[104:107]
	s_waitcnt lgkmcnt(4)
	v_mfma_f32_16x16x32_bf16 v[108:111], v[218:221], v[8:11], v[108:111]
	s_waitcnt lgkmcnt(3)
	v_mfma_f32_16x16x32_bf16 v[112:115], v[224:227], v[8:11], v[112:115]
	s_waitcnt lgkmcnt(2)
	v_mfma_f32_16x16x32_bf16 v[100:103], v[228:231], v[4:7], v[100:103]
	s_waitcnt lgkmcnt(1)
	v_mfma_f32_16x16x32_bf16 v[104:107], v[232:235], v[4:7], v[104:107]
	s_waitcnt lgkmcnt(0)
	v_mfma_f32_16x16x32_bf16 v[108:111], v[236:239], v[4:7], v[108:111]
	s_nop 7
	ds_read_b128 v[116:119], v174 offset:25792
	s_waitcnt vmcnt(7)
	ds_write_b128 v168, v[12:15]
	s_waitcnt vmcnt(6)
	ds_write_b128 v168, v[16:19] offset:128
	s_waitcnt vmcnt(5)
	ds_write_b128 v168, v[20:23] offset:256
	s_waitcnt vmcnt(4)
	ds_write_b128 v168, v[24:27] offset:384
	global_load_dwordx4 v[12:15], v[164:165], off offset:2048
	global_load_dwordx4 v[16:19], v[164:165], off offset:2176
	global_load_dwordx4 v[20:23], v[164:165], off offset:2304
	global_load_dwordx4 v[24:27], v[164:165], off offset:2432
	s_waitcnt lgkmcnt(0)
	s_barrier
	s_waitcnt lgkmcnt(4)
	v_mfma_f32_16x16x32_bf16 v[112:115], v[116:119], v[4:7], v[112:115]
	ds_read_b128 v[116:119], v173
	ds_read_b128 v[120:123], v173 offset:64
	ds_read_b128 v[124:127], v173 offset:8512
	s_waitcnt lgkmcnt(2)
	v_mfma_f32_16x16x32_bf16 v[116:119], v[116:119], v[64:67], 0
	ds_read_b128 v[128:131], v173 offset:16960
	s_waitcnt lgkmcnt(2)
	v_mfma_f32_16x16x32_bf16 v[116:119], v[120:123], v[60:63], v[116:119]
	ds_read_b128 v[120:123], v173 offset:128
	s_waitcnt lgkmcnt(0)
	v_mfma_f32_16x16x32_bf16 v[116:119], v[120:123], v[56:59], v[116:119]
	ds_read_b128 v[120:123], v173 offset:192
	s_waitcnt lgkmcnt(0)
	v_mfma_f32_16x16x32_bf16 v[116:119], v[120:123], v[52:55], v[116:119]
	ds_read_b128 v[120:123], v173 offset:256
	s_waitcnt lgkmcnt(0)
	v_mfma_f32_16x16x32_bf16 v[116:119], v[120:123], v[48:51], v[116:119]
	ds_read_b128 v[120:123], v173 offset:320
	s_waitcnt lgkmcnt(0)
	v_mfma_f32_16x16x32_bf16 v[116:119], v[120:123], v[44:47], v[116:119]
	ds_read_b128 v[120:123], v173 offset:384
	s_waitcnt lgkmcnt(0)
	v_mfma_f32_16x16x32_bf16 v[116:119], v[120:123], v[8:11], v[116:119]
	ds_read_b128 v[120:123], v173 offset:448
	s_waitcnt lgkmcnt(0)
	v_mfma_f32_16x16x32_bf16 v[116:119], v[120:123], v[4:7], v[116:119]
	ds_read_b128 v[120:123], v173 offset:8448
	s_waitcnt lgkmcnt(0)
	v_mfma_f32_16x16x32_bf16 v[120:123], v[120:123], v[64:67], 0
	v_mfma_f32_16x16x32_bf16 v[120:123], v[124:127], v[60:63], v[120:123]
	ds_read_b128 v[124:127], v173 offset:8576
	s_waitcnt lgkmcnt(0)
	v_mfma_f32_16x16x32_bf16 v[120:123], v[124:127], v[56:59], v[120:123]
	ds_read_b128 v[124:127], v173 offset:8640
	s_waitcnt lgkmcnt(0)
	v_mfma_f32_16x16x32_bf16 v[120:123], v[124:127], v[52:55], v[120:123]
	ds_read_b128 v[124:127], v173 offset:8704
	s_waitcnt lgkmcnt(0)
	v_mfma_f32_16x16x32_bf16 v[120:123], v[124:127], v[48:51], v[120:123]
	ds_read_b128 v[124:127], v173 offset:8768
	s_waitcnt lgkmcnt(0)
	v_mfma_f32_16x16x32_bf16 v[120:123], v[124:127], v[44:47], v[120:123]
	ds_read_b128 v[124:127], v173 offset:8832
	s_waitcnt lgkmcnt(0)
	v_mfma_f32_16x16x32_bf16 v[120:123], v[124:127], v[8:11], v[120:123]
	ds_read_b128 v[124:127], v173 offset:8896
	s_waitcnt lgkmcnt(0)
	v_mfma_f32_16x16x32_bf16 v[120:123], v[124:127], v[4:7], v[120:123]
	ds_read_b128 v[124:127], v173 offset:16896
	s_waitcnt lgkmcnt(0)
	v_mfma_f32_16x16x32_bf16 v[124:127], v[124:127], v[64:67], 0
	v_mfma_f32_16x16x32_bf16 v[124:127], v[128:131], v[60:63], v[124:127]
	ds_read_b128 v[128:131], v173 offset:17024
	s_waitcnt lgkmcnt(0)
	v_mfma_f32_16x16x32_bf16 v[124:127], v[128:131], v[56:59], v[124:127]
	ds_read_b128 v[128:131], v173 offset:17088
	s_waitcnt lgkmcnt(0)
	v_mfma_f32_16x16x32_bf16 v[124:127], v[128:131], v[52:55], v[124:127]
	ds_read_b128 v[128:131], v173 offset:17152
	s_waitcnt lgkmcnt(0)
	v_mfma_f32_16x16x32_bf16 v[124:127], v[128:131], v[48:51], v[124:127]
	ds_read_b128 v[128:131], v173 offset:17216
	s_waitcnt lgkmcnt(0)
	v_mfma_f32_16x16x32_bf16 v[124:127], v[128:131], v[44:47], v[124:127]
	ds_read_b128 v[128:131], v173 offset:17280
	s_waitcnt lgkmcnt(0)
	v_mfma_f32_16x16x32_bf16 v[124:127], v[128:131], v[8:11], v[124:127]
	ds_read_b128 v[128:131], v173 offset:17344
	s_waitcnt lgkmcnt(0)
	v_mfma_f32_16x16x32_bf16 v[124:127], v[128:131], v[4:7], v[124:127]
	ds_read_b128 v[128:131], v173 offset:25344
	s_waitcnt lgkmcnt(0)
	v_mfma_f32_16x16x32_bf16 v[64:67], v[128:131], v[64:67], 0
	ds_read_b128 v[128:131], v173 offset:25408
	s_waitcnt lgkmcnt(0)
	v_mfma_f32_16x16x32_bf16 v[60:63], v[128:131], v[60:63], v[64:67]
	s_nop 4
	ds_read_b128 v[64:67], v173 offset:25472
	s_waitcnt lgkmcnt(0)
	v_mfma_f32_16x16x32_bf16 v[56:59], v[64:67], v[56:59], v[60:63]
	s_nop 2
	ds_read_b128 v[60:63], v173 offset:25536
	s_waitcnt lgkmcnt(0)
	v_mfma_f32_16x16x32_bf16 v[52:55], v[60:63], v[52:55], v[56:59]
	s_nop 2
	ds_read_b128 v[56:59], v173 offset:25600
	s_waitcnt lgkmcnt(0)
	v_mfma_f32_16x16x32_bf16 v[48:51], v[56:59], v[48:51], v[52:55]
	s_nop 2
	ds_read_b128 v[52:55], v173 offset:25664
	s_waitcnt lgkmcnt(0)
	v_mfma_f32_16x16x32_bf16 v[44:47], v[52:55], v[44:47], v[48:51]
	s_nop 2
	ds_read_b128 v[48:51], v173 offset:25728
	s_waitcnt lgkmcnt(0)
	v_mfma_f32_16x16x32_bf16 v[8:11], v[48:51], v[8:11], v[44:47]
	s_nop 2
	ds_read_b128 v[44:47], v173 offset:25792
	s_waitcnt vmcnt(7)
	ds_write_b128 v170, v[28:31]
	s_waitcnt vmcnt(6)
	ds_write_b128 v170, v[32:35] offset:128
	s_waitcnt vmcnt(5)
	ds_write_b128 v170, v[36:39] offset:256
	s_waitcnt vmcnt(4)
	ds_write_b128 v170, v[40:43] offset:384
	global_load_dwordx4 v[28:31], v[162:163], off offset:2048
	global_load_dwordx4 v[32:35], v[162:163], off offset:2176
	global_load_dwordx4 v[36:39], v[162:163], off offset:2304
	global_load_dwordx4 v[40:43], v[162:163], off offset:2432
	s_waitcnt lgkmcnt(4)
	v_mfma_f32_16x16x32_bf16 v[4:7], v[44:47], v[4:7], v[8:11]
	s_nop 2
	v_max_f32_e32 v8, v71, v71
	v_max_f32_e32 v9, v70, v70
	v_max_f32_e32 v8, v9, v8
	v_max_f32_e32 v9, v75, v75
	v_max_f32_e32 v10, v74, v74
	v_max_f32_e32 v9, v10, v9
	v_max3_f32 v8, v68, v69, v8
	v_max3_f32 v9, v72, v73, v9
	v_max3_f32 v8, v8, s7, v9
	v_max_f32_e32 v9, v79, v79
	v_max_f32_e32 v10, v78, v78
	v_max_f32_e32 v9, v10, v9
	v_max_f32_e32 v10, v83, v83
	v_max_f32_e32 v11, v82, v82
	v_max_f32_e32 v10, v11, v10
	v_max3_f32 v9, v76, v77, v9
	v_max3_f32 v10, v80, v81, v10
	v_max3_f32 v8, v8, v9, v10
	v_max_f32_e32 v9, v87, v87
	v_max_f32_e32 v10, v86, v86
	v_max_f32_e32 v9, v10, v9
	v_max_f32_e32 v10, v91, v91
	v_max_f32_e32 v11, v90, v90
	v_max_f32_e32 v10, v11, v10
	v_max3_f32 v9, v84, v85, v9
	v_max3_f32 v10, v88, v89, v10
	v_max3_f32 v8, v8, v9, v10
	v_max_f32_e32 v9, v95, v95
	v_max_f32_e32 v10, v94, v94
	v_max_f32_e32 v9, v10, v9
	v_max_f32_e32 v10, v99, v99
	v_max_f32_e32 v11, v98, v98
	v_max_f32_e32 v10, v11, v10
	v_max3_f32 v9, v92, v93, v9
	v_max3_f32 v10, v96, v97, v10
	v_max3_f32 v8, v8, v9, v10
	v_max_f32_e32 v9, v103, v103
	v_max_f32_e32 v10, v102, v102
	v_max_f32_e32 v9, v10, v9
	v_max_f32_e32 v10, v107, v107
	v_max_f32_e32 v11, v106, v106
	v_max_f32_e32 v10, v11, v10
	v_max3_f32 v9, v100, v101, v9
	v_max3_f32 v10, v104, v105, v10
	v_max3_f32 v8, v8, v9, v10
	v_max_f32_e32 v9, v111, v111
	v_max_f32_e32 v10, v110, v110
	v_max_f32_e32 v9, v10, v9
	v_max_f32_e32 v10, v115, v115
	v_max_f32_e32 v11, v114, v114
	v_max_f32_e32 v10, v11, v10
	v_max3_f32 v9, v108, v109, v9
	v_max3_f32 v10, v112, v113, v10
	v_max3_f32 v8, v8, v9, v10
	v_max_f32_e32 v9, v119, v119
	v_max_f32_e32 v10, v118, v118
	v_max_f32_e32 v9, v10, v9
	v_max_f32_e32 v10, v123, v123
	v_max_f32_e32 v11, v122, v122
	v_max_f32_e32 v10, v11, v10
	v_max3_f32 v9, v116, v117, v9
	v_max3_f32 v10, v120, v121, v10
	v_max3_f32 v8, v8, v9, v10
	v_max_f32_e32 v9, v127, v127
	v_max_f32_e32 v10, v126, v126
	v_max_f32_e32 v9, v10, v9
	v_max_f32_e32 v10, v7, v7
	v_max_f32_e32 v11, v6, v6
	v_max_f32_e32 v10, v11, v10
	v_max3_f32 v9, v124, v125, v9
	v_max3_f32 v10, v4, v5, v10
	v_max3_f32 v8, v8, v9, v10
	ds_bpermute_b32 v9, v171, v8
	s_waitcnt lgkmcnt(0)
	s_barrier
	s_waitcnt lgkmcnt(0)
	v_max_f32_e32 v9, v9, v9
	v_max_f32_e32 v8, v8, v9
	ds_bpermute_b32 v9, v172, v8
	s_waitcnt lgkmcnt(0)
	v_max_f32_e32 v9, v9, v9
	v_max_f32_e32 v52, v8, v9
	v_sub_f32_e32 v8, v68, v52
	v_mul_f32_e32 v8, 0x3d800000, v8
	v_sub_f32_e32 v9, v69, v52
	v_mul_f32_e32 v8, 0x3fb8aa3b, v8
	v_mul_f32_e32 v9, 0x3d800000, v9
	v_exp_f32_e32 v8, v8
	v_mul_f32_e32 v9, 0x3fb8aa3b, v9
	v_exp_f32_e32 v9, v9
	v_sub_f32_e32 v56, v82, v52
	v_add_f32_e32 v10, 0, v8
	v_mul_f32_e32 v56, 0x3d800000, v56
	v_add_f32_e32 v11, v9, v10
	v_sub_f32_e32 v10, v70, v52
	v_mul_f32_e32 v10, 0x3d800000, v10
	v_mul_f32_e32 v10, 0x3fb8aa3b, v10
	v_exp_f32_e32 v10, v10
	v_mul_f32_e32 v56, 0x3fb8aa3b, v56
	v_exp_f32_e32 v60, v56
	v_sub_f32_e32 v56, v83, v52
	v_add_f32_e32 v44, v10, v11
	v_sub_f32_e32 v11, v71, v52
	v_mul_f32_e32 v56, 0x3d800000, v56
	v_mul_f32_e32 v11, 0x3d800000, v11
	v_mul_f32_e32 v56, 0x3fb8aa3b, v56
	v_mul_f32_e32 v11, 0x3fb8aa3b, v11
	v_exp_f32_e32 v61, v56
	v_sub_f32_e32 v56, v84, v52
	v_exp_f32_e32 v11, v11
	v_mul_f32_e32 v56, 0x3d800000, v56
	v_mul_f32_e32 v56, 0x3fb8aa3b, v56
	v_exp_f32_e32 v62, v56
	v_sub_f32_e32 v56, v85, v52
	v_mul_f32_e32 v56, 0x3d800000, v56
	v_add_f32_e32 v45, v11, v44
	v_sub_f32_e32 v44, v72, v52
	v_mul_f32_e32 v56, 0x3fb8aa3b, v56
	v_mul_f32_e32 v44, 0x3d800000, v44
	v_exp_f32_e32 v63, v56
	v_sub_f32_e32 v56, v86, v52
	v_mul_f32_e32 v44, 0x3fb8aa3b, v44
	v_mul_f32_e32 v56, 0x3d800000, v56
	v_exp_f32_e32 v44, v44
	v_mul_f32_e32 v56, 0x3fb8aa3b, v56
	v_exp_f32_e32 v64, v56
	v_sub_f32_e32 v56, v87, v52
	v_mul_f32_e32 v56, 0x3d800000, v56
	v_mul_f32_e32 v56, 0x3fb8aa3b, v56
	v_add_f32_e32 v46, v44, v45
	v_sub_f32_e32 v45, v73, v52
	v_exp_f32_e32 v65, v56
	v_sub_f32_e32 v56, v88, v52
	v_mul_f32_e32 v45, 0x3d800000, v45
	v_mul_f32_e32 v56, 0x3d800000, v56
	v_mul_f32_e32 v45, 0x3fb8aa3b, v45
	v_mul_f32_e32 v56, 0x3fb8aa3b, v56
	v_exp_f32_e32 v45, v45
	v_exp_f32_e32 v66, v56
	v_sub_f32_e32 v56, v89, v52
	v_mul_f32_e32 v56, 0x3d800000, v56
	v_mul_f32_e32 v56, 0x3fb8aa3b, v56
	v_exp_f32_e32 v67, v56
	v_sub_f32_e32 v56, v90, v52
	v_add_f32_e32 v47, v45, v46
	v_sub_f32_e32 v46, v74, v52
	v_mul_f32_e32 v56, 0x3d800000, v56
	v_mul_f32_e32 v46, 0x3d800000, v46
	v_mul_f32_e32 v56, 0x3fb8aa3b, v56
	v_mul_f32_e32 v46, 0x3fb8aa3b, v46
	v_exp_f32_e32 v68, v56
	v_sub_f32_e32 v56, v91, v52
	v_exp_f32_e32 v46, v46
	v_mul_f32_e32 v56, 0x3d800000, v56
	v_mul_f32_e32 v56, 0x3fb8aa3b, v56
	v_exp_f32_e32 v69, v56
	v_sub_f32_e32 v56, v92, v52
	v_mul_f32_e32 v56, 0x3d800000, v56
	v_add_f32_e32 v48, v46, v47
	v_sub_f32_e32 v47, v75, v52
	v_mul_f32_e32 v56, 0x3fb8aa3b, v56
	v_mul_f32_e32 v47, 0x3d800000, v47
	v_exp_f32_e32 v70, v56
	v_sub_f32_e32 v56, v93, v52
	v_mul_f32_e32 v47, 0x3fb8aa3b, v47
	v_mul_f32_e32 v56, 0x3d800000, v56
	v_exp_f32_e32 v47, v47
	v_mul_f32_e32 v56, 0x3fb8aa3b, v56
	v_exp_f32_e32 v71, v56
	v_sub_f32_e32 v56, v94, v52
	v_mul_f32_e32 v56, 0x3d800000, v56
	v_mul_f32_e32 v56, 0x3fb8aa3b, v56
	v_add_f32_e32 v49, v47, v48
	v_sub_f32_e32 v48, v76, v52
	v_exp_f32_e32 v72, v56
	v_sub_f32_e32 v56, v95, v52
	v_mul_f32_e32 v48, 0x3d800000, v48
	v_mul_f32_e32 v56, 0x3d800000, v56
	v_mul_f32_e32 v48, 0x3fb8aa3b, v48
	v_mul_f32_e32 v56, 0x3fb8aa3b, v56
	v_exp_f32_e32 v48, v48
	v_exp_f32_e32 v73, v56
	v_sub_f32_e32 v56, v96, v52
	v_mul_f32_e32 v56, 0x3d800000, v56
	v_mul_f32_e32 v56, 0x3fb8aa3b, v56
	v_exp_f32_e32 v74, v56
	v_sub_f32_e32 v56, v97, v52
	v_add_f32_e32 v50, v48, v49
	v_sub_f32_e32 v49, v77, v52
	v_mul_f32_e32 v56, 0x3d800000, v56
	v_mul_f32_e32 v49, 0x3d800000, v49
	v_mul_f32_e32 v56, 0x3fb8aa3b, v56
	v_mul_f32_e32 v49, 0x3fb8aa3b, v49
	v_exp_f32_e32 v75, v56
	v_sub_f32_e32 v56, v98, v52
	v_exp_f32_e32 v49, v49
	v_mul_f32_e32 v56, 0x3d800000, v56
	v_mul_f32_e32 v56, 0x3fb8aa3b, v56
	v_exp_f32_e32 v76, v56
	v_sub_f32_e32 v56, v99, v52
	v_mul_f32_e32 v56, 0x3d800000, v56
	v_add_f32_e32 v51, v49, v50
	v_sub_f32_e32 v50, v78, v52
	v_mul_f32_e32 v56, 0x3fb8aa3b, v56
	v_mul_f32_e32 v50, 0x3d800000, v50
	v_exp_f32_e32 v77, v56
	v_sub_f32_e32 v56, v100, v52
	v_mul_f32_e32 v50, 0x3fb8aa3b, v50
	v_mul_f32_e32 v56, 0x3d800000, v56
	v_exp_f32_e32 v50, v50
	v_mul_f32_e32 v56, 0x3fb8aa3b, v56
	v_exp_f32_e32 v78, v56
	v_sub_f32_e32 v56, v101, v52
	v_mul_f32_e32 v56, 0x3d800000, v56
	v_mul_f32_e32 v56, 0x3fb8aa3b, v56
	v_add_f32_e32 v53, v50, v51
	v_sub_f32_e32 v51, v79, v52
	v_exp_f32_e32 v79, v56
	v_sub_f32_e32 v56, v102, v52
	v_mul_f32_e32 v56, 0x3d800000, v56
	v_mul_f32_e32 v56, 0x3fb8aa3b, v56
	v_sub_f32_e32 v54, v80, v52
	v_exp_f32_e32 v80, v56
	v_sub_f32_e32 v56, v103, v52
	v_mul_f32_e32 v56, 0x3d800000, v56
	v_mul_f32_e32 v56, 0x3fb8aa3b, v56
	v_sub_f32_e32 v55, v81, v52
	v_exp_f32_e32 v81, v56
	v_sub_f32_e32 v56, v104, v52
	v_mul_f32_e32 v56, 0x3d800000, v56
	v_mul_f32_e32 v56, 0x3fb8aa3b, v56
	v_exp_f32_e32 v82, v56
	v_sub_f32_e32 v56, v105, v52
	v_mul_f32_e32 v56, 0x3d800000, v56
	v_mul_f32_e32 v56, 0x3fb8aa3b, v56
	v_exp_f32_e32 v83, v56
	v_sub_f32_e32 v56, v106, v52
	v_mul_f32_e32 v56, 0x3d800000, v56
	v_mul_f32_e32 v56, 0x3fb8aa3b, v56
	v_exp_f32_e32 v84, v56
	v_sub_f32_e32 v56, v107, v52
	v_mul_f32_e32 v56, 0x3d800000, v56
	v_mul_f32_e32 v56, 0x3fb8aa3b, v56
	v_exp_f32_e32 v85, v56
	v_sub_f32_e32 v56, v108, v52
	v_mul_f32_e32 v56, 0x3d800000, v56
	v_mul_f32_e32 v56, 0x3fb8aa3b, v56
	v_exp_f32_e32 v86, v56
	v_sub_f32_e32 v56, v109, v52
	v_mul_f32_e32 v56, 0x3d800000, v56
	v_mul_f32_e32 v56, 0x3fb8aa3b, v56
	v_exp_f32_e32 v87, v56
	v_sub_f32_e32 v56, v110, v52
	v_mul_f32_e32 v56, 0x3d800000, v56
	v_mul_f32_e32 v56, 0x3fb8aa3b, v56
	v_exp_f32_e32 v88, v56
	v_sub_f32_e32 v56, v111, v52
	v_mul_f32_e32 v51, 0x3d800000, v51
	v_mul_f32_e32 v56, 0x3d800000, v56
	v_mul_f32_e32 v51, 0x3fb8aa3b, v51
	v_mul_f32_e32 v54, 0x3d800000, v54
	v_mul_f32_e32 v56, 0x3fb8aa3b, v56
	v_exp_f32_e32 v51, v51
	v_mul_f32_e32 v54, 0x3fb8aa3b, v54
	v_mul_f32_e32 v55, 0x3d800000, v55
	v_exp_f32_e32 v89, v56
	v_sub_f32_e32 v56, v112, v52
	v_exp_f32_e32 v54, v54
	v_mul_f32_e32 v55, 0x3fb8aa3b, v55
	v_mul_f32_e32 v56, 0x3d800000, v56
	v_exp_f32_e32 v55, v55
	v_mul_f32_e32 v56, 0x3fb8aa3b, v56
	v_exp_f32_e32 v90, v56
	v_sub_f32_e32 v56, v113, v52
	v_add_f32_e32 v53, v51, v53
	v_mul_f32_e32 v56, 0x3d800000, v56
	v_add_f32_e32 v53, v54, v53
	v_mul_f32_e32 v56, 0x3fb8aa3b, v56
	v_add_f32_e32 v53, v55, v53
	v_exp_f32_e32 v91, v56
	v_sub_f32_e32 v56, v114, v52
	v_add_f32_e32 v53, v60, v53
	v_mul_f32_e32 v56, 0x3d800000, v56
	v_add_f32_e32 v53, v61, v53
	v_mul_f32_e32 v56, 0x3fb8aa3b, v56
	v_add_f32_e32 v53, v62, v53
	v_exp_f32_e32 v92, v56
	v_sub_f32_e32 v56, v115, v52
	v_add_f32_e32 v53, v63, v53
	v_mul_f32_e32 v56, 0x3d800000, v56
	v_add_f32_e32 v53, v64, v53
	v_mul_f32_e32 v56, 0x3fb8aa3b, v56
	v_add_f32_e32 v53, v65, v53
	v_exp_f32_e32 v93, v56
	v_sub_f32_e32 v56, v116, v52
	v_add_f32_e32 v53, v66, v53
	v_mul_f32_e32 v56, 0x3d800000, v56
	v_add_f32_e32 v53, v67, v53
	v_mul_f32_e32 v56, 0x3fb8aa3b, v56
	v_add_f32_e32 v53, v68, v53
	v_exp_f32_e32 v139, v56
	v_sub_f32_e32 v56, v117, v52
	v_add_f32_e32 v53, v69, v53
	v_mul_f32_e32 v56, 0x3d800000, v56
	v_add_f32_e32 v53, v70, v53
	v_mul_f32_e32 v56, 0x3fb8aa3b, v56
	v_add_f32_e32 v53, v71, v53
	v_exp_f32_e32 v140, v56
	v_sub_f32_e32 v56, v118, v52
	v_add_f32_e32 v53, v72, v53
	v_mul_f32_e32 v56, 0x3d800000, v56
	v_add_f32_e32 v53, v73, v53
	v_mul_f32_e32 v56, 0x3fb8aa3b, v56
	v_add_f32_e32 v53, v74, v53
	v_exp_f32_e32 v141, v56
	v_sub_f32_e32 v56, v119, v52
	v_add_f32_e32 v53, v75, v53
	v_mul_f32_e32 v56, 0x3d800000, v56
	v_add_f32_e32 v53, v76, v53
	v_mul_f32_e32 v56, 0x3fb8aa3b, v56
	v_add_f32_e32 v53, v77, v53
	v_exp_f32_e32 v142, v56
	v_sub_f32_e32 v56, v120, v52
	v_add_f32_e32 v53, v78, v53
	v_mul_f32_e32 v56, 0x3d800000, v56
	v_add_f32_e32 v53, v79, v53
	v_mul_f32_e32 v56, 0x3fb8aa3b, v56
	v_add_f32_e32 v53, v80, v53
	v_exp_f32_e32 v143, v56
	v_sub_f32_e32 v56, v121, v52
	v_add_f32_e32 v53, v81, v53
	v_mul_f32_e32 v56, 0x3d800000, v56
	v_add_f32_e32 v53, v82, v53
	v_mul_f32_e32 v56, 0x3fb8aa3b, v56
	v_add_f32_e32 v53, v83, v53
	v_exp_f32_e32 v144, v56
	v_sub_f32_e32 v56, v122, v52
	v_add_f32_e32 v53, v84, v53
	v_mul_f32_e32 v56, 0x3d800000, v56
	v_add_f32_e32 v53, v85, v53
	v_mul_f32_e32 v56, 0x3fb8aa3b, v56
	v_add_f32_e32 v53, v86, v53
	v_exp_f32_e32 v145, v56
	v_sub_f32_e32 v56, v123, v52
	v_add_f32_e32 v53, v87, v53
	v_mul_f32_e32 v56, 0x3d800000, v56
	v_add_f32_e32 v53, v88, v53
	v_mul_f32_e32 v56, 0x3fb8aa3b, v56
	v_add_f32_e32 v53, v89, v53
	v_exp_f32_e32 v146, v56
	v_sub_f32_e32 v56, v124, v52
	v_add_f32_e32 v53, v90, v53
	v_mul_f32_e32 v56, 0x3d800000, v56
	v_add_f32_e32 v53, v91, v53
	v_mul_f32_e32 v56, 0x3fb8aa3b, v56
	v_add_f32_e32 v53, v92, v53
	v_exp_f32_e32 v147, v56
	v_sub_f32_e32 v56, v125, v52
	v_add_f32_e32 v53, v93, v53
	v_mul_f32_e32 v56, 0x3d800000, v56
	v_add_f32_e32 v53, v139, v53
	v_mul_f32_e32 v56, 0x3fb8aa3b, v56
	v_add_f32_e32 v53, v140, v53
	v_exp_f32_e32 v148, v56
	v_sub_f32_e32 v56, v126, v52
	v_add_f32_e32 v53, v141, v53
	v_mul_f32_e32 v56, 0x3d800000, v56
	v_add_f32_e32 v53, v142, v53
	v_mul_f32_e32 v56, 0x3fb8aa3b, v56
	v_add_f32_e32 v53, v143, v53
	v_exp_f32_e32 v149, v56
	v_sub_f32_e32 v56, v127, v52
	v_add_f32_e32 v53, v144, v53
	v_mul_f32_e32 v56, 0x3d800000, v56
	v_sub_f32_e32 v4, v4, v52
	v_add_f32_e32 v53, v145, v53
	v_mul_f32_e32 v56, 0x3fb8aa3b, v56
	v_mul_f32_e32 v4, 0x3d800000, v4
	v_sub_f32_e32 v5, v5, v52
	v_add_f32_e32 v53, v146, v53
	v_exp_f32_e32 v150, v56
	v_mul_f32_e32 v4, 0x3fb8aa3b, v4
	v_mul_f32_e32 v5, 0x3d800000, v5
	v_add_f32_e32 v53, v147, v53
	v_exp_f32_e32 v151, v4
	v_mul_f32_e32 v5, 0x3fb8aa3b, v5
	v_add_f32_e32 v53, v148, v53
	v_exp_f32_e32 v152, v5
	v_sub_f32_e32 v5, v6, v52
	v_add_f32_e32 v53, v149, v53
	v_mul_f32_e32 v5, 0x3d800000, v5
	v_add_f32_e32 v53, v150, v53
	v_mul_f32_e32 v5, 0x3fb8aa3b, v5
	v_add_f32_e32 v4, v151, v53
	v_exp_f32_e32 v153, v5
	v_sub_f32_e32 v5, v7, v52
	v_cvt_pk_bf16_f32 v52, v48, v49
	v_cvt_pk_bf16_f32 v53, v50, v51
	v_cvt_pk_bf16_f32 v54, v54, v55
	v_cvt_pk_bf16_f32 v55, v60, v61
	v_cvt_pk_bf16_f32 v48, v62, v63
	v_cvt_pk_bf16_f32 v49, v64, v65
	v_cvt_pk_bf16_f32 v50, v66, v67
	v_cvt_pk_bf16_f32 v51, v68, v69
	ds_read_b64_tr_b16 v[60:61], v169
	ds_read_b64_tr_b16 v[64:65], v169 offset:32
	ds_read_b64_tr_b16 v[62:63], v169 offset:8448
	ds_read_b64_tr_b16 v[66:67], v169 offset:16896
	ds_read_b64_tr_b16 v[68:69], v169 offset:25344
	v_cvt_pk_bf16_f32 v56, v8, v9
	v_cvt_pk_bf16_f32 v57, v10, v11
	v_cvt_pk_bf16_f32 v58, v44, v45
	v_cvt_pk_bf16_f32 v59, v46, v47
	v_cvt_pk_bf16_f32 v44, v70, v71
	v_cvt_pk_bf16_f32 v45, v72, v73
	s_waitcnt lgkmcnt(2)
	v_mfma_f32_16x16x32_bf16 v[60:63], v[60:63], v[56:59], 0
	v_cvt_pk_bf16_f32 v46, v74, v75
	v_cvt_pk_bf16_f32 v47, v76, v77
	v_cvt_pk_bf16_f32 v8, v78, v79
	s_waitcnt lgkmcnt(0)
	v_mfma_f32_16x16x32_bf16 v[60:63], v[66:69], v[52:55], v[60:63]
	ds_read_b64_tr_b16 v[66:67], v169 offset:8480
	ds_read_b64_tr_b16 v[68:69], v169 offset:16928
	ds_read_b64_tr_b16 v[70:71], v169 offset:25376
	v_mul_f32_e32 v5, 0x3d800000, v5
	v_mul_f32_e32 v5, 0x3fb8aa3b, v5
	s_waitcnt lgkmcnt(2)
	v_mfma_f32_16x16x32_bf16 v[64:67], v[64:67], v[56:59], 0
	v_exp_f32_e32 v154, v5
	v_add_f32_e32 v4, v152, v4
	v_add_f32_e32 v4, v153, v4
	s_waitcnt lgkmcnt(0)
	v_mfma_f32_16x16x32_bf16 v[64:67], v[68:71], v[52:55], v[64:67]
	ds_read_b64_tr_b16 v[68:69], v169 offset:64
	ds_read_b64_tr_b16 v[70:71], v169 offset:8512
	ds_read_b64_tr_b16 v[72:73], v169 offset:16960
	ds_read_b64_tr_b16 v[74:75], v169 offset:25408
	v_cvt_pk_bf16_f32 v9, v80, v81
	v_cvt_pk_bf16_f32 v10, v82, v83
	s_waitcnt lgkmcnt(2)
	v_mfma_f32_16x16x32_bf16 v[68:71], v[68:71], v[56:59], 0
	v_add_f32_e32 v4, v154, v4
	ds_bpermute_b32 v5, v171, v4
	v_cvt_pk_bf16_f32 v11, v84, v85
	s_waitcnt lgkmcnt(1)
	v_mfma_f32_16x16x32_bf16 v[68:71], v[72:75], v[52:55], v[68:71]
	ds_read_b64_tr_b16 v[72:73], v169 offset:96
	ds_read_b64_tr_b16 v[74:75], v169 offset:8544
	ds_read_b64_tr_b16 v[76:77], v169 offset:16992
	ds_read_b64_tr_b16 v[78:79], v169 offset:25440
	v_cvt_pk_bf16_f32 v6, v90, v91
	s_waitcnt lgkmcnt(4)
	v_add_f32_e32 v137, v4, v5
	s_waitcnt lgkmcnt(2)
	v_mfma_f32_16x16x32_bf16 v[72:75], v[72:75], v[56:59], 0
	v_cvt_pk_bf16_f32 v4, v86, v87
	v_cvt_pk_bf16_f32 v5, v88, v89
	v_cvt_pk_bf16_f32 v7, v92, v93
	s_waitcnt lgkmcnt(0)
	v_mfma_f32_16x16x32_bf16 v[108:111], v[76:79], v[52:55], v[72:75]
	s_nop 2
	ds_read_b64_tr_b16 v[72:73], v169 offset:128
	ds_read_b64_tr_b16 v[74:75], v169 offset:8576
	ds_read_b64_tr_b16 v[76:77], v169 offset:17024
	ds_read_b64_tr_b16 v[78:79], v169 offset:25472
	ds_bpermute_b32 v138, v172, v137
	s_waitcnt lgkmcnt(3)
	v_mfma_f32_16x16x32_bf16 v[72:75], v[72:75], v[56:59], 0
	s_waitcnt lgkmcnt(1)
	v_mfma_f32_16x16x32_bf16 v[72:75], v[76:79], v[52:55], v[72:75]
	ds_read_b64_tr_b16 v[76:77], v169 offset:160
	ds_read_b64_tr_b16 v[78:79], v169 offset:8608
	ds_read_b64_tr_b16 v[80:81], v169 offset:17056
	ds_read_b64_tr_b16 v[82:83], v169 offset:25504
	s_waitcnt lgkmcnt(2)
	v_mfma_f32_16x16x32_bf16 v[76:79], v[76:79], v[56:59], 0
	s_waitcnt lgkmcnt(0)
	v_mfma_f32_16x16x32_bf16 v[76:79], v[80:83], v[52:55], v[76:79]
	ds_read_b64_tr_b16 v[80:81], v169 offset:192
	ds_read_b64_tr_b16 v[82:83], v169 offset:8640
	ds_read_b64_tr_b16 v[84:85], v169 offset:17088
	ds_read_b64_tr_b16 v[86:87], v169 offset:25536
	s_waitcnt lgkmcnt(2)
	v_mfma_f32_16x16x32_bf16 v[80:83], v[80:83], v[56:59], 0
	s_waitcnt lgkmcnt(0)
	v_mfma_f32_16x16x32_bf16 v[80:83], v[84:87], v[52:55], v[80:83]
	ds_read_b64_tr_b16 v[84:85], v169 offset:224
	ds_read_b64_tr_b16 v[86:87], v169 offset:8672
	ds_read_b64_tr_b16 v[88:89], v169 offset:17120
	ds_read_b64_tr_b16 v[90:91], v169 offset:25568
	s_waitcnt lgkmcnt(2)
	v_mfma_f32_16x16x32_bf16 v[84:87], v[84:87], v[56:59], 0
	s_waitcnt lgkmcnt(0)
	v_mfma_f32_16x16x32_bf16 v[112:115], v[88:91], v[52:55], v[84:87]
	s_nop 5
	ds_read_b64_tr_b16 v[84:85], v169 offset:256
	ds_read_b64_tr_b16 v[86:87], v169 offset:8704
	ds_read_b64_tr_b16 v[88:89], v169 offset:17152
	ds_read_b64_tr_b16 v[90:91], v169 offset:25600
	s_waitcnt lgkmcnt(2)
	v_mfma_f32_16x16x32_bf16 v[84:87], v[84:87], v[56:59], 0
	s_waitcnt lgkmcnt(0)
	v_mfma_f32_16x16x32_bf16 v[84:87], v[88:91], v[52:55], v[84:87]
	ds_read_b64_tr_b16 v[88:89], v169 offset:288
	ds_read_b64_tr_b16 v[90:91], v169 offset:8736
	ds_read_b64_tr_b16 v[92:93], v169 offset:17184
	ds_read_b64_tr_b16 v[94:95], v169 offset:25632
	s_waitcnt lgkmcnt(2)
	v_mfma_f32_16x16x32_bf16 v[88:91], v[88:91], v[56:59], 0
	s_waitcnt lgkmcnt(0)
	v_mfma_f32_16x16x32_bf16 v[88:91], v[92:95], v[52:55], v[88:91]
	ds_read_b64_tr_b16 v[92:93], v169 offset:320
	ds_read_b64_tr_b16 v[94:95], v169 offset:8768
	ds_read_b64_tr_b16 v[96:97], v169 offset:17216
	ds_read_b64_tr_b16 v[98:99], v169 offset:25664
	s_waitcnt lgkmcnt(2)
	v_mfma_f32_16x16x32_bf16 v[92:95], v[92:95], v[56:59], 0
	s_waitcnt lgkmcnt(0)
	v_mfma_f32_16x16x32_bf16 v[92:95], v[96:99], v[52:55], v[92:95]
	ds_read_b64_tr_b16 v[96:97], v169 offset:352
	ds_read_b64_tr_b16 v[98:99], v169 offset:8800
	ds_read_b64_tr_b16 v[100:101], v169 offset:17248
	ds_read_b64_tr_b16 v[102:103], v169 offset:25696
	s_waitcnt lgkmcnt(2)
	v_mfma_f32_16x16x32_bf16 v[96:99], v[96:99], v[56:59], 0
	s_waitcnt lgkmcnt(0)
	v_mfma_f32_16x16x32_bf16 v[116:119], v[100:103], v[52:55], v[96:99]
	s_nop 5
	ds_read_b64_tr_b16 v[96:97], v169 offset:384
	ds_read_b64_tr_b16 v[98:99], v169 offset:8832
	ds_read_b64_tr_b16 v[100:101], v169 offset:17280
	ds_read_b64_tr_b16 v[102:103], v169 offset:25728
	s_waitcnt lgkmcnt(2)
	v_mfma_f32_16x16x32_bf16 v[96:99], v[96:99], v[56:59], 0
	s_waitcnt lgkmcnt(0)
	v_mfma_f32_16x16x32_bf16 v[96:99], v[100:103], v[52:55], v[96:99]
	ds_read_b64_tr_b16 v[100:101], v169 offset:416
	ds_read_b64_tr_b16 v[102:103], v169 offset:8864
	ds_read_b64_tr_b16 v[104:105], v169 offset:17312
	ds_read_b64_tr_b16 v[106:107], v169 offset:25760
	s_waitcnt lgkmcnt(2)
	v_mfma_f32_16x16x32_bf16 v[100:103], v[100:103], v[56:59], 0
	s_waitcnt lgkmcnt(0)
	v_mfma_f32_16x16x32_bf16 v[100:103], v[104:107], v[52:55], v[100:103]
	ds_read_b64_tr_b16 v[104:105], v169 offset:448
	ds_read_b64_tr_b16 v[106:107], v169 offset:8896
	ds_read_b64_tr_b16 v[120:121], v169 offset:17344
	ds_read_b64_tr_b16 v[122:123], v169 offset:25792
	s_waitcnt lgkmcnt(2)
	v_mfma_f32_16x16x32_bf16 v[104:107], v[104:107], v[56:59], 0
	s_waitcnt lgkmcnt(0)
	v_mfma_f32_16x16x32_bf16 v[104:107], v[120:123], v[52:55], v[104:107]
	ds_read_b64_tr_b16 v[120:121], v169 offset:480
	ds_read_b64_tr_b16 v[122:123], v169 offset:8928
	ds_read_b64_tr_b16 v[124:125], v169 offset:17376
	ds_read_b64_tr_b16 v[126:127], v169 offset:25824
	s_waitcnt vmcnt(7)
	ds_write_b128 v168, v[12:15]
	s_waitcnt vmcnt(6)
	ds_write_b128 v168, v[16:19] offset:128
	s_waitcnt vmcnt(5)
	ds_write_b128 v168, v[20:23] offset:256
	s_waitcnt vmcnt(4)
	ds_write_b128 v168, v[24:27] offset:384
	global_load_dwordx4 v[12:15], v[160:161], off offset:2048
	global_load_dwordx4 v[16:19], v[160:161], off offset:2176
	global_load_dwordx4 v[20:23], v[160:161], off offset:2304
	global_load_dwordx4 v[24:27], v[160:161], off offset:2432
	s_waitcnt lgkmcnt(6)
	v_mfma_f32_16x16x32_bf16 v[56:59], v[120:123], v[56:59], 0
	s_waitcnt lgkmcnt(0)
	s_barrier
	s_waitcnt lgkmcnt(4)
	v_mfma_f32_16x16x32_bf16 v[120:123], v[124:127], v[52:55], v[56:59]
	ds_read_b64_tr_b16 v[204:205], v3
	ds_read_b64_tr_b16 v[206:207], v3 offset:8448
	ds_read_b64_tr_b16 v[208:209], v3 offset:32
	ds_read_b64_tr_b16 v[210:211], v3 offset:8480
	ds_read_b64_tr_b16 v[218:219], v3 offset:16928
	ds_read_b64_tr_b16 v[220:221], v3 offset:25376
	ds_read_b64_tr_b16 v[224:225], v3 offset:64
	ds_read_b64_tr_b16 v[226:227], v3 offset:8512
	ds_read_b64_tr_b16 v[228:229], v3 offset:16960
	ds_read_b64_tr_b16 v[230:231], v3 offset:25408
	ds_read_b64_tr_b16 v[232:233], v3 offset:96
	ds_read_b64_tr_b16 v[234:235], v3 offset:8544
	ds_read_b64_tr_b16 v[236:237], v3 offset:16992
	ds_read_b64_tr_b16 v[238:239], v3 offset:25440
	ds_read_b64_tr_b16 v[240:241], v3 offset:128
	ds_read_b64_tr_b16 v[242:243], v3 offset:8576
	s_nop 3
	s_waitcnt lgkmcnt(14)
	v_mfma_f32_16x16x32_bf16 v[52:55], v[204:207], v[48:51], v[60:63]
	ds_read_b64_tr_b16 v[204:205], v3 offset:17024
	ds_read_b64_tr_b16 v[206:207], v3 offset:25472
	s_nop 1
	s_waitcnt lgkmcnt(14)
	v_mfma_f32_16x16x32_bf16 v[56:59], v[208:211], v[48:51], v[64:67]
	ds_read_b64_tr_b16 v[208:209], v3 offset:160
	ds_read_b64_tr_b16 v[210:211], v3 offset:8608
	s_waitcnt lgkmcnt(14)
	v_mfma_f32_16x16x32_bf16 v[56:59], v[218:221], v[44:47], v[56:59]
	ds_read_b64_tr_b16 v[218:219], v3 offset:17056
	ds_read_b64_tr_b16 v[220:221], v3 offset:25504
	s_waitcnt lgkmcnt(14)
	v_mfma_f32_16x16x32_bf16 v[60:63], v[224:227], v[48:51], v[68:71]
	ds_read_b64_tr_b16 v[224:225], v3 offset:192
	ds_read_b64_tr_b16 v[226:227], v3 offset:8640
	s_waitcnt lgkmcnt(14)
	v_mfma_f32_16x16x32_bf16 v[60:63], v[228:231], v[44:47], v[60:63]
	ds_read_b64_tr_b16 v[228:229], v3 offset:16896
	ds_read_b64_tr_b16 v[230:231], v3 offset:25344
	s_waitcnt lgkmcnt(14)
	v_mfma_f32_16x16x32_bf16 v[64:67], v[232:235], v[48:51], v[108:111]
	ds_read_b64_tr_b16 v[232:233], v3 offset:17088
	ds_read_b64_tr_b16 v[234:235], v3 offset:25536
	s_waitcnt lgkmcnt(14)
	v_mfma_f32_16x16x32_bf16 v[64:67], v[236:239], v[44:47], v[64:67]
	ds_read_b64_tr_b16 v[236:237], v3 offset:224
	ds_read_b64_tr_b16 v[238:239], v3 offset:8672
	s_waitcnt lgkmcnt(14)
	v_mfma_f32_16x16x32_bf16 v[68:71], v[240:243], v[48:51], v[72:75]
	ds_read_b64_tr_b16 v[240:241], v3 offset:17120
	ds_read_b64_tr_b16 v[242:243], v3 offset:25568
	s_waitcnt lgkmcnt(14)
	v_mfma_f32_16x16x32_bf16 v[68:71], v[204:207], v[44:47], v[68:71]
	ds_read_b64_tr_b16 v[204:205], v3 offset:256
	ds_read_b64_tr_b16 v[206:207], v3 offset:8704
	s_nop 0
	s_waitcnt lgkmcnt(14)
	v_mfma_f32_16x16x32_bf16 v[72:75], v[208:211], v[48:51], v[76:79]
	ds_read_b64_tr_b16 v[208:209], v3 offset:17152
	ds_read_b64_tr_b16 v[210:211], v3 offset:25600
	s_waitcnt lgkmcnt(14)
	v_mfma_f32_16x16x32_bf16 v[108:111], v[218:221], v[44:47], v[72:75]
	ds_read_b64_tr_b16 v[218:219], v3 offset:288
	ds_read_b64_tr_b16 v[220:221], v3 offset:8736
	s_nop 5
	s_waitcnt lgkmcnt(14)
	v_mfma_f32_16x16x32_bf16 v[72:75], v[224:227], v[48:51], v[80:83]
	ds_read_b64_tr_b16 v[224:225], v3 offset:17184
	ds_read_b64_tr_b16 v[226:227], v3 offset:25632
	s_waitcnt lgkmcnt(14)
	v_mfma_f32_16x16x32_bf16 v[52:55], v[228:231], v[44:47], v[52:55]
	ds_read_b64_tr_b16 v[228:229], v3 offset:320
	ds_read_b64_tr_b16 v[230:231], v3 offset:8768
	s_waitcnt lgkmcnt(14)
	v_mfma_f32_16x16x32_bf16 v[124:127], v[232:235], v[44:47], v[72:75]
	ds_read_b64_tr_b16 v[232:233], v3 offset:17216
	ds_read_b64_tr_b16 v[234:235], v3 offset:25664
	s_nop 4
	s_waitcnt lgkmcnt(14)
	v_mfma_f32_16x16x32_bf16 v[72:75], v[236:239], v[48:51], v[112:115]
	ds_read_b64_tr_b16 v[236:237], v3 offset:352
	ds_read_b64_tr_b16 v[238:239], v3 offset:8800
	s_waitcnt lgkmcnt(14)
	v_mfma_f32_16x16x32_bf16 v[132:135], v[240:243], v[44:47], v[72:75]
	ds_read_b64_tr_b16 v[240:241], v3 offset:17248
	ds_read_b64_tr_b16 v[242:243], v3 offset:25696
	s_nop 5
	s_waitcnt lgkmcnt(14)
	v_mfma_f32_16x16x32_bf16 v[72:75], v[204:207], v[48:51], v[84:87]
	ds_read_b64_tr_b16 v[204:205], v3 offset:384
	ds_read_b64_tr_b16 v[206:207], v3 offset:8832
	s_waitcnt lgkmcnt(14)
	v_mfma_f32_16x16x32_bf16 v[112:115], v[208:211], v[44:47], v[72:75]
	ds_read_b64_tr_b16 v[208:209], v3 offset:17280
	ds_read_b64_tr_b16 v[210:211], v3 offset:25728
	s_nop 5
	s_waitcnt lgkmcnt(14)
	v_mfma_f32_16x16x32_bf16 v[72:75], v[218:221], v[48:51], v[88:91]
	ds_read_b64_tr_b16 v[218:219], v3 offset:416
	ds_read_b64_tr_b16 v[220:221], v3 offset:8864
	s_waitcnt lgkmcnt(14)
	v_mfma_f32_16x16x32_bf16 v[128:131], v[224:227], v[44:47], v[72:75]
	ds_read_b64_tr_b16 v[224:225], v3 offset:17312
	ds_read_b64_tr_b16 v[226:227], v3 offset:25760
	s_nop 5
	s_waitcnt lgkmcnt(14)
	v_mfma_f32_16x16x32_bf16 v[72:75], v[228:231], v[48:51], v[92:95]
	ds_read_b64_tr_b16 v[228:229], v3 offset:448
	ds_read_b64_tr_b16 v[230:231], v3 offset:8896
	s_waitcnt lgkmcnt(14)
	v_mfma_f32_16x16x32_bf16 v[92:95], v[232:235], v[44:47], v[72:75]
	ds_read_b64_tr_b16 v[232:233], v3 offset:17344
	ds_read_b64_tr_b16 v[234:235], v3 offset:25792
	s_nop 5
	s_waitcnt lgkmcnt(14)
	v_mfma_f32_16x16x32_bf16 v[72:75], v[236:239], v[48:51], v[116:119]
	s_waitcnt lgkmcnt(12)
	v_mfma_f32_16x16x32_bf16 v[116:119], v[240:243], v[44:47], v[72:75]
	s_nop 5
	s_waitcnt lgkmcnt(10)
	v_mfma_f32_16x16x32_bf16 v[72:75], v[204:207], v[48:51], v[96:99]
	s_waitcnt lgkmcnt(8)
	v_mfma_f32_16x16x32_bf16 v[96:99], v[208:211], v[44:47], v[72:75]
	s_nop 5
	s_waitcnt lgkmcnt(6)
	v_mfma_f32_16x16x32_bf16 v[72:75], v[218:221], v[48:51], v[100:103]
	s_waitcnt lgkmcnt(4)
	v_mfma_f32_16x16x32_bf16 v[100:103], v[224:227], v[44:47], v[72:75]
	s_nop 5
	s_waitcnt lgkmcnt(2)
	v_mfma_f32_16x16x32_bf16 v[72:75], v[228:231], v[48:51], v[104:107]
	s_waitcnt lgkmcnt(0)
	v_mfma_f32_16x16x32_bf16 v[104:107], v[232:235], v[44:47], v[72:75]
	s_nop 7
	s_nop 5
	ds_read_b64_tr_b16 v[72:73], v3 offset:480
	ds_read_b64_tr_b16 v[74:75], v3 offset:8928
	ds_read_b64_tr_b16 v[76:77], v3 offset:17376
	ds_read_b64_tr_b16 v[78:79], v3 offset:25824
	s_waitcnt vmcnt(7)
	ds_write_b128 v170, v[28:31]
	s_waitcnt vmcnt(6)
	ds_write_b128 v170, v[32:35] offset:128
	s_waitcnt vmcnt(5)
	ds_write_b128 v170, v[36:39] offset:256
	s_waitcnt vmcnt(4)
	ds_write_b128 v170, v[40:43] offset:384
	s_waitcnt lgkmcnt(0)
	s_barrier
	ds_read_b64_tr_b16 v[204:205], v169
	ds_read_b64_tr_b16 v[206:207], v169 offset:8448
	ds_read_b64_tr_b16 v[208:209], v169 offset:16896
	ds_read_b64_tr_b16 v[210:211], v169 offset:25344
	ds_read_b64_tr_b16 v[218:219], v169 offset:32
	ds_read_b64_tr_b16 v[220:221], v169 offset:8480
	ds_read_b64_tr_b16 v[224:225], v169 offset:16928
	ds_read_b64_tr_b16 v[226:227], v169 offset:25376
	ds_read_b64_tr_b16 v[228:229], v169 offset:64
	ds_read_b64_tr_b16 v[230:231], v169 offset:8512
	ds_read_b64_tr_b16 v[232:233], v169 offset:16960
	ds_read_b64_tr_b16 v[234:235], v169 offset:25408
	ds_read_b64_tr_b16 v[236:237], v169 offset:96
	ds_read_b64_tr_b16 v[238:239], v169 offset:8544
	ds_read_b64_tr_b16 v[240:241], v169 offset:16992
	ds_read_b64_tr_b16 v[242:243], v169 offset:25440
	v_mfma_f32_16x16x32_bf16 v[48:51], v[72:75], v[48:51], v[120:123]
	s_waitcnt lgkmcnt(14)
	v_mfma_f32_16x16x32_bf16 v[28:31], v[204:207], v[8:11], v[52:55]
	ds_read_b64_tr_b16 v[204:205], v169 offset:128
	ds_read_b64_tr_b16 v[206:207], v169 offset:8576
	v_mfma_f32_16x16x32_bf16 v[88:91], v[76:79], v[44:47], v[48:51]
	s_waitcnt lgkmcnt(14)
	v_mfma_f32_16x16x32_bf16 v[76:79], v[208:211], v[4:7], v[28:31]
	ds_read_b64_tr_b16 v[208:209], v169 offset:17024
	ds_read_b64_tr_b16 v[210:211], v169 offset:25472
	s_nop 3
	s_waitcnt lgkmcnt(14)
	v_mfma_f32_16x16x32_bf16 v[32:35], v[218:221], v[8:11], v[56:59]
	ds_read_b64_tr_b16 v[218:219], v169 offset:160
	ds_read_b64_tr_b16 v[220:221], v169 offset:8608
	s_waitcnt lgkmcnt(14)
	v_mfma_f32_16x16x32_bf16 v[80:83], v[224:227], v[4:7], v[32:35]
	ds_read_b64_tr_b16 v[224:225], v169 offset:17056
	ds_read_b64_tr_b16 v[226:227], v169 offset:25504
	s_nop 3
	s_waitcnt lgkmcnt(14)
	v_mfma_f32_16x16x32_bf16 v[28:31], v[228:231], v[8:11], v[60:63]
	ds_read_b64_tr_b16 v[228:229], v169 offset:192
	ds_read_b64_tr_b16 v[230:231], v169 offset:8640
	s_waitcnt lgkmcnt(14)
	v_mfma_f32_16x16x32_bf16 v[84:87], v[232:235], v[4:7], v[28:31]
	ds_read_b64_tr_b16 v[232:233], v169 offset:17088
	ds_read_b64_tr_b16 v[234:235], v169 offset:25536
	s_nop 5
	s_waitcnt lgkmcnt(14)
	v_mfma_f32_16x16x32_bf16 v[28:31], v[236:239], v[8:11], v[64:67]
	ds_read_b64_tr_b16 v[236:237], v169 offset:224
	ds_read_b64_tr_b16 v[238:239], v169 offset:8672
	s_waitcnt lgkmcnt(14)
	v_mfma_f32_16x16x32_bf16 v[72:75], v[240:243], v[4:7], v[28:31]
	ds_read_b64_tr_b16 v[240:241], v169 offset:17120
	ds_read_b64_tr_b16 v[242:243], v169 offset:25568
	s_nop 5
	s_waitcnt lgkmcnt(14)
	v_mfma_f32_16x16x32_bf16 v[28:31], v[204:207], v[8:11], v[68:71]
	ds_read_b64_tr_b16 v[204:205], v169 offset:256
	ds_read_b64_tr_b16 v[206:207], v169 offset:8704
	s_waitcnt lgkmcnt(14)
	v_mfma_f32_16x16x32_bf16 v[28:31], v[208:211], v[4:7], v[28:31]
	ds_read_b64_tr_b16 v[208:209], v169 offset:17152
	ds_read_b64_tr_b16 v[210:211], v169 offset:25600
	s_waitcnt lgkmcnt(14)
	v_mfma_f32_16x16x32_bf16 v[32:35], v[218:221], v[8:11], v[108:111]
	ds_read_b64_tr_b16 v[218:219], v169 offset:288
	ds_read_b64_tr_b16 v[220:221], v169 offset:8736
	s_waitcnt lgkmcnt(14)
	v_mfma_f32_16x16x32_bf16 v[32:35], v[224:227], v[4:7], v[32:35]
	ds_read_b64_tr_b16 v[224:225], v169 offset:17184
	ds_read_b64_tr_b16 v[226:227], v169 offset:25632
	s_waitcnt lgkmcnt(14)
	v_mfma_f32_16x16x32_bf16 v[36:39], v[228:231], v[8:11], v[124:127]
	ds_read_b64_tr_b16 v[228:229], v169 offset:320
	ds_read_b64_tr_b16 v[230:231], v169 offset:8768
	s_waitcnt lgkmcnt(14)
	v_mfma_f32_16x16x32_bf16 v[36:39], v[232:235], v[4:7], v[36:39]
	ds_read_b64_tr_b16 v[232:233], v169 offset:17216
	ds_read_b64_tr_b16 v[234:235], v169 offset:25664
	s_waitcnt lgkmcnt(14)
	v_mfma_f32_16x16x32_bf16 v[40:43], v[236:239], v[8:11], v[132:135]
	ds_read_b64_tr_b16 v[236:237], v169 offset:352
	ds_read_b64_tr_b16 v[238:239], v169 offset:8800
	s_waitcnt lgkmcnt(14)
	v_mfma_f32_16x16x32_bf16 v[64:67], v[240:243], v[4:7], v[40:43]
	ds_read_b64_tr_b16 v[240:241], v169 offset:17248
	ds_read_b64_tr_b16 v[242:243], v169 offset:25696
	s_nop 5
	s_waitcnt lgkmcnt(14)
	v_mfma_f32_16x16x32_bf16 v[40:43], v[204:207], v[8:11], v[112:115]
	ds_read_b64_tr_b16 v[204:205], v169 offset:384
	ds_read_b64_tr_b16 v[206:207], v169 offset:8832
	s_waitcnt lgkmcnt(14)
	v_mfma_f32_16x16x32_bf16 v[40:43], v[208:211], v[4:7], v[40:43]
	ds_read_b64_tr_b16 v[208:209], v169 offset:17280
	ds_read_b64_tr_b16 v[210:211], v169 offset:25728
	s_waitcnt lgkmcnt(14)
	v_mfma_f32_16x16x32_bf16 v[44:47], v[218:221], v[8:11], v[128:131]
	ds_read_b64_tr_b16 v[218:219], v169 offset:416
	ds_read_b64_tr_b16 v[220:221], v169 offset:8864
	s_waitcnt lgkmcnt(14)
	v_mfma_f32_16x16x32_bf16 v[44:47], v[224:227], v[4:7], v[44:47]
	ds_read_b64_tr_b16 v[224:225], v169 offset:17312
	ds_read_b64_tr_b16 v[226:227], v169 offset:25760
	s_waitcnt lgkmcnt(14)
	v_mfma_f32_16x16x32_bf16 v[48:51], v[228:231], v[8:11], v[92:95]
	ds_read_b64_tr_b16 v[228:229], v169 offset:448
	ds_read_b64_tr_b16 v[230:231], v169 offset:8896
	s_waitcnt lgkmcnt(14)
	v_mfma_f32_16x16x32_bf16 v[48:51], v[232:235], v[4:7], v[48:51]
	ds_read_b64_tr_b16 v[232:233], v169 offset:17344
	ds_read_b64_tr_b16 v[234:235], v169 offset:25792
	s_waitcnt lgkmcnt(14)
	v_mfma_f32_16x16x32_bf16 v[52:55], v[236:239], v[8:11], v[116:119]
	ds_read_b64_tr_b16 v[236:237], v169 offset:480
	ds_read_b64_tr_b16 v[238:239], v169 offset:8928
	s_waitcnt lgkmcnt(14)
	v_mfma_f32_16x16x32_bf16 v[68:71], v[240:243], v[4:7], v[52:55]
	s_nop 5
	s_waitcnt lgkmcnt(12)
	v_mfma_f32_16x16x32_bf16 v[52:55], v[204:207], v[8:11], v[96:99]
	s_waitcnt lgkmcnt(10)
	v_mfma_f32_16x16x32_bf16 v[52:55], v[208:211], v[4:7], v[52:55]
	s_waitcnt lgkmcnt(8)
	v_mfma_f32_16x16x32_bf16 v[56:59], v[218:221], v[8:11], v[100:103]
	s_waitcnt lgkmcnt(6)
	v_mfma_f32_16x16x32_bf16 v[56:59], v[224:227], v[4:7], v[56:59]
	s_waitcnt lgkmcnt(4)
	v_mfma_f32_16x16x32_bf16 v[60:63], v[228:231], v[8:11], v[104:107]
	s_waitcnt lgkmcnt(2)
	v_mfma_f32_16x16x32_bf16 v[60:63], v[232:235], v[4:7], v[60:63]
	ds_read_b64_tr_b16 v[96:97], v169 offset:17376
	ds_read_b64_tr_b16 v[98:99], v169 offset:25824
	s_waitcnt vmcnt(3)
	ds_write_b128 v168, v[12:15]
	s_waitcnt vmcnt(2)
	ds_write_b128 v168, v[16:19] offset:128
	s_waitcnt vmcnt(1)
	ds_write_b128 v168, v[20:23] offset:256
	s_waitcnt vmcnt(0)
	ds_write_b128 v168, v[24:27] offset:384
	s_waitcnt lgkmcnt(0)
	s_waitcnt lgkmcnt(6)
	v_mfma_f32_16x16x32_bf16 v[8:11], v[236:239], v[8:11], v[88:91]
	s_nop 7
	s_barrier
	v_cvt_pk_bf16_f32 v20, v139, v140
	s_waitcnt lgkmcnt(4)
	v_mfma_f32_16x16x32_bf16 v[4:7], v[96:99], v[4:7], v[8:11]
	s_nop 3
	ds_read_b64_tr_b16 v[204:205], v3
	ds_read_b64_tr_b16 v[206:207], v3 offset:8448
	ds_read_b64_tr_b16 v[208:209], v3 offset:16896
	ds_read_b64_tr_b16 v[210:211], v3 offset:25344
	ds_read_b64_tr_b16 v[218:219], v3 offset:32
	ds_read_b64_tr_b16 v[220:221], v3 offset:8480
	ds_read_b64_tr_b16 v[224:225], v3 offset:16928
	ds_read_b64_tr_b16 v[226:227], v3 offset:25376
	ds_read_b64_tr_b16 v[228:229], v3 offset:64
	ds_read_b64_tr_b16 v[230:231], v3 offset:8512
	ds_read_b64_tr_b16 v[232:233], v3 offset:16960
	ds_read_b64_tr_b16 v[234:235], v3 offset:25408
	ds_read_b64_tr_b16 v[236:237], v3 offset:96
	ds_read_b64_tr_b16 v[238:239], v3 offset:8544
	ds_read_b64_tr_b16 v[240:241], v3 offset:16992
	ds_read_b64_tr_b16 v[242:243], v3 offset:25440
	v_cvt_pk_bf16_f32 v21, v141, v142
	v_cvt_pk_bf16_f32 v22, v143, v144
	v_cvt_pk_bf16_f32 v23, v145, v146
	v_cvt_pk_bf16_f32 v16, v147, v148
	v_cvt_pk_bf16_f32 v17, v149, v150
	s_nop 1
	s_waitcnt lgkmcnt(14)
	v_mfma_f32_16x16x32_bf16 v[8:11], v[204:207], v[20:23], v[76:79]
	ds_read_b64_tr_b16 v[204:205], v3 offset:128
	ds_read_b64_tr_b16 v[206:207], v3 offset:8576
	v_cvt_pk_bf16_f32 v18, v151, v152
	v_cvt_pk_bf16_f32 v19, v153, v154
	v_add_u32_e32 v88, 0x80, v136
	v_ashrrev_i32_e32 v89, 31, v88
	s_nop 1
	s_waitcnt lgkmcnt(14)
	v_mfma_f32_16x16x32_bf16 v[12:15], v[208:211], v[16:19], v[8:11]
	ds_read_b64_tr_b16 v[208:209], v3 offset:17024
	ds_read_b64_tr_b16 v[210:211], v3 offset:25472
	s_nop 1
	s_waitcnt lgkmcnt(14)
	v_mfma_f32_16x16x32_bf16 v[24:27], v[218:221], v[20:23], v[80:83]
	ds_read_b64_tr_b16 v[218:219], v3 offset:160
	ds_read_b64_tr_b16 v[220:221], v3 offset:8608
	s_waitcnt lgkmcnt(14)
	v_mfma_f32_16x16x32_bf16 v[8:11], v[224:227], v[16:19], v[24:27]
	ds_read_b64_tr_b16 v[224:225], v3 offset:17056
	ds_read_b64_tr_b16 v[226:227], v3 offset:25504
	s_nop 5
	s_waitcnt lgkmcnt(14)
	v_mfma_f32_16x16x32_bf16 v[24:27], v[228:231], v[20:23], v[84:87]
	ds_read_b64_tr_b16 v[228:229], v3 offset:192
	ds_read_b64_tr_b16 v[230:231], v3 offset:8640
	s_waitcnt lgkmcnt(14)
	v_mfma_f32_16x16x32_bf16 v[24:27], v[232:235], v[16:19], v[24:27]
	ds_read_b64_tr_b16 v[232:233], v3 offset:17088
	ds_read_b64_tr_b16 v[234:235], v3 offset:25536
	s_waitcnt lgkmcnt(14)
	v_mfma_f32_16x16x32_bf16 v[72:75], v[236:239], v[20:23], v[72:75]
	ds_read_b64_tr_b16 v[236:237], v3 offset:224
	ds_read_b64_tr_b16 v[238:239], v3 offset:8672
	s_waitcnt lgkmcnt(14)
	v_mfma_f32_16x16x32_bf16 v[72:75], v[240:243], v[16:19], v[72:75]
	ds_read_b64_tr_b16 v[240:241], v3 offset:17120
	ds_read_b64_tr_b16 v[242:243], v3 offset:25568
	s_waitcnt lgkmcnt(14)
	v_mfma_f32_16x16x32_bf16 v[28:31], v[204:207], v[20:23], v[28:31]
	ds_read_b64_tr_b16 v[204:205], v3 offset:256
	ds_read_b64_tr_b16 v[206:207], v3 offset:8704
	s_waitcnt lgkmcnt(14)
	v_mfma_f32_16x16x32_bf16 v[28:31], v[208:211], v[16:19], v[28:31]
	ds_read_b64_tr_b16 v[208:209], v3 offset:17152
	ds_read_b64_tr_b16 v[210:211], v3 offset:25600
	s_waitcnt lgkmcnt(14)
	v_mfma_f32_16x16x32_bf16 v[32:35], v[218:221], v[20:23], v[32:35]
	ds_read_b64_tr_b16 v[218:219], v3 offset:288
	ds_read_b64_tr_b16 v[220:221], v3 offset:8736
	s_waitcnt lgkmcnt(14)
	v_mfma_f32_16x16x32_bf16 v[32:35], v[224:227], v[16:19], v[32:35]
	ds_read_b64_tr_b16 v[224:225], v3 offset:17184
	ds_read_b64_tr_b16 v[226:227], v3 offset:25632
	s_waitcnt lgkmcnt(14)
	v_mfma_f32_16x16x32_bf16 v[36:39], v[228:231], v[20:23], v[36:39]
	ds_read_b64_tr_b16 v[228:229], v3 offset:320
	ds_read_b64_tr_b16 v[230:231], v3 offset:8768
	s_waitcnt lgkmcnt(14)
	v_mfma_f32_16x16x32_bf16 v[36:39], v[232:235], v[16:19], v[36:39]
	ds_read_b64_tr_b16 v[232:233], v3 offset:17216
	ds_read_b64_tr_b16 v[234:235], v3 offset:25664
	s_waitcnt lgkmcnt(14)
	v_mfma_f32_16x16x32_bf16 v[64:67], v[236:239], v[20:23], v[64:67]
	ds_read_b64_tr_b16 v[236:237], v3 offset:352
	ds_read_b64_tr_b16 v[238:239], v3 offset:8800
	s_waitcnt lgkmcnt(14)
	v_mfma_f32_16x16x32_bf16 v[64:67], v[240:243], v[16:19], v[64:67]
	ds_read_b64_tr_b16 v[240:241], v3 offset:17248
	ds_read_b64_tr_b16 v[242:243], v3 offset:25696
	s_waitcnt lgkmcnt(14)
	v_mfma_f32_16x16x32_bf16 v[40:43], v[204:207], v[20:23], v[40:43]
	ds_read_b64_tr_b16 v[204:205], v3 offset:384
	ds_read_b64_tr_b16 v[206:207], v3 offset:8832
	s_waitcnt lgkmcnt(14)
	v_mfma_f32_16x16x32_bf16 v[40:43], v[208:211], v[16:19], v[40:43]
	ds_read_b64_tr_b16 v[208:209], v3 offset:17280
	ds_read_b64_tr_b16 v[210:211], v3 offset:25728
	s_waitcnt lgkmcnt(14)
	v_mfma_f32_16x16x32_bf16 v[44:47], v[218:221], v[20:23], v[44:47]
	ds_read_b64_tr_b16 v[218:219], v3 offset:416
	ds_read_b64_tr_b16 v[220:221], v3 offset:8864
	s_waitcnt lgkmcnt(14)
	v_mfma_f32_16x16x32_bf16 v[44:47], v[224:227], v[16:19], v[44:47]
	ds_read_b64_tr_b16 v[224:225], v3 offset:17312
	ds_read_b64_tr_b16 v[226:227], v3 offset:25760
	s_waitcnt lgkmcnt(14)
	v_mfma_f32_16x16x32_bf16 v[48:51], v[228:231], v[20:23], v[48:51]
	ds_read_b64_tr_b16 v[228:229], v3 offset:448
	ds_read_b64_tr_b16 v[230:231], v3 offset:8896
	s_waitcnt lgkmcnt(14)
	v_mfma_f32_16x16x32_bf16 v[48:51], v[232:235], v[16:19], v[48:51]
	ds_read_b64_tr_b16 v[232:233], v3 offset:17344
	ds_read_b64_tr_b16 v[234:235], v3 offset:25792
	s_waitcnt lgkmcnt(14)
	v_mfma_f32_16x16x32_bf16 v[68:71], v[236:239], v[20:23], v[68:71]
	ds_read_b64_tr_b16 v[236:237], v3 offset:480
	ds_read_b64_tr_b16 v[238:239], v3 offset:8928
	s_waitcnt lgkmcnt(14)
	v_mfma_f32_16x16x32_bf16 v[68:71], v[240:243], v[16:19], v[68:71]
	ds_read_b64_tr_b16 v[240:241], v3 offset:17376
	ds_read_b64_tr_b16 v[242:243], v3 offset:25824
	s_waitcnt lgkmcnt(14)
	v_mfma_f32_16x16x32_bf16 v[52:55], v[204:207], v[20:23], v[52:55]
	s_waitcnt lgkmcnt(12)
	v_mfma_f32_16x16x32_bf16 v[52:55], v[208:211], v[16:19], v[52:55]
	s_waitcnt lgkmcnt(10)
	v_mfma_f32_16x16x32_bf16 v[56:59], v[218:221], v[20:23], v[56:59]
	s_waitcnt lgkmcnt(8)
	v_mfma_f32_16x16x32_bf16 v[56:59], v[224:227], v[16:19], v[56:59]
	s_waitcnt lgkmcnt(6)
	v_mfma_f32_16x16x32_bf16 v[60:63], v[228:231], v[20:23], v[60:63]
	s_waitcnt lgkmcnt(4)
	v_mfma_f32_16x16x32_bf16 v[60:63], v[232:235], v[16:19], v[60:63]
	v_add_f32_e32 v3, v137, v138
	s_nop 1
	s_waitcnt lgkmcnt(2)
	v_mfma_f32_16x16x32_bf16 v[4:7], v[236:239], v[20:23], v[4:7]
	s_waitcnt lgkmcnt(0)
	v_mfma_f32_16x16x32_bf16 v[4:7], v[240:243], v[16:19], v[4:7]
	s_nop 7
	v_div_scale_f32 v16, s[12:13], v3, v3, 1.0
	v_rcp_f32_e32 v17, v16
	s_nop 0
	v_fma_f32 v18, -v16, v17, 1.0
	v_fmac_f32_e32 v17, v18, v17
	v_div_scale_f32 v18, vcc, 1.0, v3, 1.0
	v_mul_f32_e32 v19, v18, v17
	v_fma_f32 v20, -v16, v19, v18
	v_fmac_f32_e32 v19, v20, v17
	v_fma_f32 v16, -v16, v19, v18
	v_div_fmas_f32 v16, v16, v17, v19
	v_lshlrev_b64 v[18:19], 11, v[88:89]
	v_lshl_add_u64 v[18:19], s[10:11], 0, v[18:19]
	v_div_fixup_f32 v16, v16, v3, 1.0
	v_mad_i64_i32 v[18:19], s[6:7], s6, v155, v[18:19]
	v_lshl_add_u64 v[18:19], v[18:19], 0, s[8:9]
	v_pk_mul_f32 v[8:9], v[16:17], v[8:9] op_sel_hi:[0,1]
	v_pk_mul_f32 v[10:11], v[16:17], v[10:11] op_sel_hi:[0,1]
	v_lshl_add_u64 v[0:1], v[18:19], 0, v[0:1]
	v_cvt_pk_bf16_f32 v8, v8, v9
	v_cvt_pk_bf16_f32 v9, v10, v11
	global_store_dwordx2 v[0:1], v[8:9], off offset:32
	v_pk_mul_f32 v[8:9], v[16:17], v[24:25] op_sel_hi:[0,1]
	v_pk_mul_f32 v[10:11], v[16:17], v[26:27] op_sel_hi:[0,1]
	v_cvt_pk_bf16_f32 v8, v8, v9
	v_cvt_pk_bf16_f32 v9, v10, v11
	global_store_dwordx2 v[0:1], v[8:9], off offset:64
	v_pk_mul_f32 v[8:9], v[16:17], v[72:73] op_sel_hi:[0,1]
	v_pk_mul_f32 v[10:11], v[16:17], v[74:75] op_sel_hi:[0,1]
	v_cvt_pk_bf16_f32 v8, v8, v9
	v_cvt_pk_bf16_f32 v9, v10, v11
	global_store_dwordx2 v[0:1], v[8:9], off offset:96
	v_pk_mul_f32 v[8:9], v[16:17], v[28:29] op_sel_hi:[0,1]
	v_pk_mul_f32 v[10:11], v[16:17], v[30:31] op_sel_hi:[0,1]
	v_cvt_pk_bf16_f32 v8, v8, v9
	v_cvt_pk_bf16_f32 v9, v10, v11
	global_store_dwordx2 v[0:1], v[8:9], off offset:128
	v_pk_mul_f32 v[8:9], v[16:17], v[32:33] op_sel_hi:[0,1]
	v_pk_mul_f32 v[10:11], v[16:17], v[34:35] op_sel_hi:[0,1]
	v_cvt_pk_bf16_f32 v8, v8, v9
	v_cvt_pk_bf16_f32 v9, v10, v11
	global_store_dwordx2 v[0:1], v[8:9], off offset:160
	v_pk_mul_f32 v[8:9], v[16:17], v[36:37] op_sel_hi:[0,1]
	v_pk_mul_f32 v[10:11], v[16:17], v[38:39] op_sel_hi:[0,1]
	v_cvt_pk_bf16_f32 v8, v8, v9
	v_cvt_pk_bf16_f32 v9, v10, v11
	global_store_dwordx2 v[0:1], v[8:9], off offset:192
	v_pk_mul_f32 v[8:9], v[16:17], v[64:65] op_sel_hi:[0,1]
	v_pk_mul_f32 v[10:11], v[16:17], v[66:67] op_sel_hi:[0,1]
	v_cvt_pk_bf16_f32 v8, v8, v9
	v_cvt_pk_bf16_f32 v9, v10, v11
	global_store_dwordx2 v[0:1], v[8:9], off offset:224
	v_pk_mul_f32 v[8:9], v[16:17], v[40:41] op_sel_hi:[0,1]
	v_pk_mul_f32 v[10:11], v[16:17], v[42:43] op_sel_hi:[0,1]
	v_cvt_pk_bf16_f32 v8, v8, v9
	v_cvt_pk_bf16_f32 v9, v10, v11
	global_store_dwordx2 v[0:1], v[8:9], off offset:256
	v_pk_mul_f32 v[8:9], v[16:17], v[44:45] op_sel_hi:[0,1]
	v_pk_mul_f32 v[10:11], v[16:17], v[46:47] op_sel_hi:[0,1]
	v_cvt_pk_bf16_f32 v8, v8, v9
	v_cvt_pk_bf16_f32 v9, v10, v11
	global_store_dwordx2 v[0:1], v[8:9], off offset:288
	v_pk_mul_f32 v[8:9], v[16:17], v[48:49] op_sel_hi:[0,1]
	v_pk_mul_f32 v[10:11], v[16:17], v[50:51] op_sel_hi:[0,1]
	v_cvt_pk_bf16_f32 v8, v8, v9
	v_cvt_pk_bf16_f32 v9, v10, v11
	global_store_dwordx2 v[0:1], v[8:9], off offset:320
	v_pk_mul_f32 v[8:9], v[16:17], v[68:69] op_sel_hi:[0,1]
	v_pk_mul_f32 v[10:11], v[16:17], v[70:71] op_sel_hi:[0,1]
	v_cvt_pk_bf16_f32 v8, v8, v9
	v_cvt_pk_bf16_f32 v9, v10, v11
	global_store_dwordx2 v[0:1], v[8:9], off offset:352
	v_pk_mul_f32 v[8:9], v[16:17], v[52:53] op_sel_hi:[0,1]
	v_pk_mul_f32 v[10:11], v[16:17], v[54:55] op_sel_hi:[0,1]
	v_cvt_pk_bf16_f32 v8, v8, v9
	v_cvt_pk_bf16_f32 v9, v10, v11
	global_store_dwordx2 v[0:1], v[8:9], off offset:384
	v_pk_mul_f32 v[8:9], v[16:17], v[56:57] op_sel_hi:[0,1]
	v_pk_mul_f32 v[10:11], v[16:17], v[58:59] op_sel_hi:[0,1]
	v_cvt_pk_bf16_f32 v8, v8, v9
	v_cvt_pk_bf16_f32 v9, v10, v11
	v_pk_mul_f32 v[12:13], v[16:17], v[12:13] op_sel_hi:[0,1]
	v_pk_mul_f32 v[14:15], v[16:17], v[14:15] op_sel_hi:[0,1]
	global_store_dwordx2 v[0:1], v[8:9], off offset:416
	v_pk_mul_f32 v[8:9], v[16:17], v[60:61] op_sel_hi:[0,1]
	v_pk_mul_f32 v[10:11], v[16:17], v[62:63] op_sel_hi:[0,1]
	v_pk_mul_f32 v[4:5], v[16:17], v[4:5] op_sel_hi:[0,1]
	v_pk_mul_f32 v[6:7], v[16:17], v[6:7] op_sel_hi:[0,1]
	v_cvt_pk_bf16_f32 v12, v12, v13
	v_cvt_pk_bf16_f32 v13, v14, v15
	v_cvt_pk_bf16_f32 v8, v8, v9
	v_cvt_pk_bf16_f32 v9, v10, v11
	v_cvt_pk_bf16_f32 v4, v4, v5
	v_cvt_pk_bf16_f32 v5, v6, v7
	global_store_dwordx2 v[0:1], v[12:13], off
	global_store_dwordx2 v[0:1], v[8:9], off offset:448
	global_store_dwordx2 v[0:1], v[4:5], off offset:480
	s_waitcnt lgkmcnt(0)
	s_barrier
